# cache policy hints: hid stores sc0 sc1 nt, final output stores nt, nt loads for once-read streams (x/p conversion, weight transposes, outproj residual base)
# speedup vs baseline: 1.0629x; 1.0179x over previous
.LBB0_22:
	s_movk_i32 s0, 0x3ff
	v_cmp_lt_i32_e32 vcc, s0, v56
	s_and_saveexec_b64 s[0:1], vcc
	s_xor_b64 s[92:93], exec, s[0:1]
	s_cbranch_execz .LBB0_128
	s_movk_i32 s0, 0x47f
	v_cmp_lt_u32_e32 vcc, s0, v56
	s_and_saveexec_b64 s[0:1], vcc
	s_xor_b64 s[94:95], exec, s[0:1]
	s_cbranch_execz .LBB0_125
	s_movk_i32 s0, 0x67f
	v_cmp_lt_u32_e32 vcc, s0, v56
	s_and_saveexec_b64 s[0:1], vcc
	s_xor_b64 s[96:97], exec, s[0:1]
	s_cbranch_execz .LBB0_122
	s_movk_i32 s0, 0x167f
	v_cmp_lt_u32_e32 vcc, s0, v56
	s_and_saveexec_b64 s[0:1], vcc
	s_xor_b64 s[24:25], exec, s[0:1]
	s_cbranch_execz .LBB0_95
	s_movk_i32 s0, 0x267f
	v_cmp_lt_u32_e32 vcc, s0, v56
	s_and_saveexec_b64 s[0:1], vcc
	s_xor_b64 s[30:31], exec, s[0:1]
	s_cbranch_execz .LBB0_92
	s_movk_i32 s0, 0x2a7f
	v_cmp_lt_u32_e32 vcc, s0, v56
	s_and_saveexec_b64 s[0:1], vcc
	s_xor_b64 s[42:43], exec, s[0:1]
	s_cbranch_execz .LBB0_65
	s_movk_i32 s0, 0x2b7f
	v_cmp_lt_u32_e32 vcc, s0, v56
	s_and_saveexec_b64 s[0:1], vcc
	s_xor_b64 s[76:77], exec, s[0:1]
	s_cbranch_execz .LBB0_62
	v_add_u32_e32 v2, 0xffffd480, v56
	v_lshrrev_b32_e32 v2, 5, v2
	v_lshlrev_b64 v[20:21], 18, v[2:3]
	v_and_b32_e32 v57, 0xe0, v51
	v_lshl_add_u64 v[22:23], s[54:55], 0, v[20:21]
	v_and_b32_e32 v20, 0xc0, v53
	v_lshlrev_b32_e32 v28, 2, v57
	v_mov_b32_e32 v29, v3
	v_or_b32_e32 v31, v20, v0
	v_lshl_add_u64 v[22:23], v[22:23], 0, v[28:29]
	v_mov_b32_e32 v19, v3
	v_lshl_add_u64 v[22:23], v[22:23], 0, v[18:19]
	v_lshlrev_b32_e32 v28, 10, v31
	v_lshl_add_u64 v[22:23], v[22:23], 0, v[28:29]
	s_movk_i32 s0, 0x1000
	v_add_co_u32_e32 v28, vcc, s0, v22
	s_movk_i32 s0, 0x2000
	s_nop 0
	v_addc_co_u32_e32 v29, vcc, 0, v23, vcc
	v_add_co_u32_e32 v58, vcc, s0, v22
	s_movk_i32 s0, 0x3000
	s_nop 0
	v_addc_co_u32_e32 v59, vcc, 0, v23, vcc
	v_add_co_u32_e32 v60, vcc, s0, v22
	s_movk_i32 s0, 0x4000
	s_nop 0
	v_addc_co_u32_e32 v61, vcc, 0, v23, vcc
	v_add_co_u32_e32 v62, vcc, s0, v22
	s_movk_i32 s0, 0x5000
	s_nop 0
	v_addc_co_u32_e32 v63, vcc, 0, v23, vcc
	v_add_co_u32_e32 v64, vcc, s0, v22
	s_movk_i32 s0, 0x6000
	s_nop 0
	v_addc_co_u32_e32 v65, vcc, 0, v23, vcc
	v_add_co_u32_e32 v66, vcc, s0, v22
	s_movk_i32 s0, 0x7000
	s_nop 0
	v_addc_co_u32_e32 v67, vcc, 0, v23, vcc
	v_add_co_u32_e32 v68, vcc, s0, v22
	s_mov_b32 s0, 0x8000
	s_nop 0
	v_addc_co_u32_e32 v69, vcc, 0, v23, vcc
	v_add_co_u32_e32 v70, vcc, s0, v22
	s_mov_b32 s0, 0x9000
	s_nop 0
	v_addc_co_u32_e32 v71, vcc, 0, v23, vcc
	global_load_dword v81, v[58:59], off offset:2048 nt
	global_load_dword v80, v[62:63], off offset:-4096 nt
	global_load_dword v76, v[62:63], off nt
	global_load_dword v78, v[62:63], off offset:2048 nt
	global_load_dword v77, v[66:67], off offset:-4096 nt
	global_load_dword v72, v[66:67], off nt
	global_load_dword v73, v[66:67], off offset:2048 nt
	global_load_dword v74, v[70:71], off offset:-4096 nt
	v_add_co_u32_e32 v62, vcc, s0, v22
	s_mov_b32 s0, 0xa000
	s_nop 0
	v_addc_co_u32_e32 v63, vcc, 0, v23, vcc
	v_add_co_u32_e32 v66, vcc, s0, v22
	s_mov_b32 s0, 0xb000
	s_nop 0
	v_addc_co_u32_e32 v67, vcc, 0, v23, vcc
	v_add_co_u32_e32 v88, vcc, s0, v22
	s_mov_b32 s0, 0xc000
	s_nop 0
	v_addc_co_u32_e32 v89, vcc, 0, v23, vcc
	v_add_co_u32_e32 v90, vcc, s0, v22
	s_mov_b32 s0, 0xd000
	s_nop 0
	v_addc_co_u32_e32 v91, vcc, 0, v23, vcc
	global_load_dword v86, v[22:23], off nt
	global_load_dword v85, v[22:23], off offset:2048 nt
	global_load_dword v84, v[28:29], off offset:2048 nt
	global_load_dword v82, v[60:61], off offset:2048 nt
	global_load_dword v79, v[64:65], off offset:2048 nt
	global_load_dword v75, v[68:69], off offset:2048 nt
	s_nop 0
	global_load_dword v68, v[62:63], off offset:2048 nt
	global_load_dword v64, v[88:89], off offset:2048 nt
	global_load_dword v69, v[70:71], off nt
	s_nop 0
	global_load_dword v71, v[70:71], off offset:2048 nt
	s_nop 0
	global_load_dword v70, v[66:67], off offset:-4096 nt
	global_load_dword v65, v[66:67], off nt
	s_nop 0
	global_load_dword v67, v[66:67], off offset:2048 nt
	s_nop 0
	global_load_dword v66, v[90:91], off offset:-4096 nt
	global_load_dword v60, v[90:91], off nt
	global_load_dword v61, v[90:91], off offset:2048 nt
	v_add_co_u32_e32 v28, vcc, s0, v22
	v_readlane_b32 s0, v242, 9
	s_nop 0
	v_addc_co_u32_e32 v29, vcc, 0, v23, vcc
	v_add_co_u32_e32 v88, vcc, 0xe000, v22
	v_readlane_b32 s1, v242, 10
	s_nop 0
	v_addc_co_u32_e32 v89, vcc, 0, v23, vcc
	v_add_co_u32_e32 v22, vcc, 0xf000, v22
	v_cndmask_b32_e64 v30, 0, 1, s[0:1]
	s_nop 0
	v_addc_co_u32_e32 v23, vcc, 0, v23, vcc
	global_load_dword v87, v[58:59], off offset:-4096 nt
	global_load_dword v83, v[58:59], off nt
	global_load_dword v63, v[28:29], off nt
	global_load_dword v62, v[28:29], off offset:2048 nt
	global_load_dword v21, v[88:89], off nt
	s_nop 0
	global_load_dword v58, v[88:89], off offset:2048 nt
	global_load_dword v59, v[22:23], off nt
	global_load_dword v19, v[22:23], off offset:2048 nt
	v_lshlrev_b32_e32 v22, 8, v2
	v_mov_b32_e32 v23, v3
	v_lshl_add_u64 v[28:29], v[22:23], 2, s[52:53]
	v_cmp_ne_u32_e64 s[6:7], 1, v30
	s_andn2_b64 vcc, exec, s[0:1]
	v_add_lshl_u32 v30, v20, v0, 2
	s_cbranch_vccnz .LBB0_177
	v_lshlrev_b32_e32 v88, 2, v31
	v_mov_b32_e32 v89, v3
	v_lshl_add_u64 v[88:89], v[28:29], 0, v[88:89]
	v_mov_b32_e32 v31, v3
	v_lshl_add_u64 v[90:91], v[28:29], 0, v[30:31]
	global_load_dword v88, v[88:89], off nt
	s_nop 0
	global_load_dword v89, v[90:91], off offset:8 nt
	global_load_dword v92, v[90:91], off offset:16 nt
	global_load_dword v31, v[90:91], off offset:24 nt
	v_add_u32_e32 v90, v27, v33
	s_waitcnt vmcnt(3)
	v_mul_f32_e32 v91, v86, v88
	s_waitcnt vmcnt(2)
	v_mul_f32_e32 v89, v85, v89
	s_waitcnt vmcnt(1)
	v_mul_f32_e32 v88, v87, v92
	ds_write_b32 v32, v91
	ds_write_b32 v90, v89
	s_cbranch_execnz .LBB0_32

.LBB0_32:
	s_waitcnt vmcnt(22)
	v_add_u32_e32 v85, v27, v34
	s_waitcnt vmcnt(0)
	v_mul_f32_e32 v31, v84, v31
	s_and_b64 vcc, exec, s[6:7]
	ds_write2_b32 v85, v88, v31 offset1:66
	s_cbranch_vccnz .LBB0_178
	v_mov_b32_e32 v31, v3
	v_lshl_add_u64 v[84:85], v[28:29], 0, v[30:31]
	global_load_dword v86, v[84:85], off offset:32 nt
	global_load_dword v87, v[84:85], off offset:40 nt
	global_load_dword v88, v[84:85], off offset:48 nt
	global_load_dword v31, v[84:85], off offset:56 nt
	v_add_u32_e32 v85, v27, v35
	s_waitcnt vmcnt(3)
	v_mul_f32_e32 v86, v83, v86
	s_waitcnt vmcnt(2)
	v_mul_f32_e32 v87, v81, v87
	s_waitcnt vmcnt(1)
	v_mul_f32_e32 v84, v80, v88
	ds_write2_b32 v85, v86, v87 offset1:66
	s_cbranch_execnz .LBB0_35

.LBB0_35:
	v_add_u32_e32 v80, v27, v36
	s_waitcnt vmcnt(0)
	v_mul_f32_e32 v31, v82, v31
	s_and_b64 vcc, exec, s[6:7]
	ds_write2_b32 v80, v84, v31 offset1:66
	s_cbranch_vccnz .LBB0_179
	v_mov_b32_e32 v31, v3
	v_lshl_add_u64 v[80:81], v[28:29], 0, v[30:31]
	global_load_dword v82, v[80:81], off offset:64 nt
	global_load_dword v83, v[80:81], off offset:72 nt
	global_load_dword v84, v[80:81], off offset:80 nt
	global_load_dword v31, v[80:81], off offset:88 nt
	v_add_u32_e32 v81, v27, v37
	s_waitcnt vmcnt(3)
	v_mul_f32_e32 v82, v76, v82
	s_waitcnt vmcnt(2)
	v_mul_f32_e32 v83, v78, v83
	s_waitcnt vmcnt(1)
	v_mul_f32_e32 v80, v77, v84
	ds_write2_b32 v81, v82, v83 offset1:66
	s_cbranch_execnz .LBB0_38

.LBB0_38:
	v_add_u32_e32 v76, v27, v38
	s_waitcnt vmcnt(0)
	v_mul_f32_e32 v31, v79, v31
	s_and_b64 vcc, exec, s[6:7]
	ds_write2_b32 v76, v80, v31 offset1:66
	s_cbranch_vccnz .LBB0_180
	v_mov_b32_e32 v31, v3
	v_lshl_add_u64 v[76:77], v[28:29], 0, v[30:31]
	global_load_dword v78, v[76:77], off offset:96 nt
	global_load_dword v79, v[76:77], off offset:104 nt
	global_load_dword v80, v[76:77], off offset:112 nt
	global_load_dword v31, v[76:77], off offset:120 nt
	v_add_u32_e32 v77, v27, v39
	s_waitcnt vmcnt(3)
	v_mul_f32_e32 v78, v72, v78
	s_waitcnt vmcnt(2)
	v_mul_f32_e32 v79, v73, v79
	s_waitcnt vmcnt(1)
	v_mul_f32_e32 v76, v74, v80
	ds_write2_b32 v77, v78, v79 offset1:66
	s_cbranch_execnz .LBB0_41

.LBB0_41:
	v_add_u32_e32 v72, v27, v40
	s_waitcnt vmcnt(0)
	v_mul_f32_e32 v31, v75, v31
	s_and_b64 vcc, exec, s[6:7]
	ds_write2_b32 v72, v76, v31 offset1:66
	s_cbranch_vccnz .LBB0_181
	v_mov_b32_e32 v31, v3
	v_lshl_add_u64 v[72:73], v[28:29], 0, v[30:31]
	global_load_dword v74, v[72:73], off offset:128 nt
	global_load_dword v75, v[72:73], off offset:136 nt
	global_load_dword v76, v[72:73], off offset:144 nt
	global_load_dword v31, v[72:73], off offset:152 nt
	v_add_u32_e32 v73, v27, v41
	s_waitcnt vmcnt(3)
	v_mul_f32_e32 v74, v69, v74
	s_waitcnt vmcnt(2)
	v_mul_f32_e32 v75, v71, v75
	s_waitcnt vmcnt(1)
	v_mul_f32_e32 v72, v70, v76
	ds_write2_b32 v73, v74, v75 offset1:66
	s_cbranch_execnz .LBB0_44

.LBB0_44:
	v_add_u32_e32 v69, v27, v42
	s_waitcnt vmcnt(0)
	v_mul_f32_e32 v31, v68, v31
	s_and_b64 vcc, exec, s[6:7]
	ds_write2_b32 v69, v72, v31 offset1:66
	s_cbranch_vccnz .LBB0_182
	v_mov_b32_e32 v31, v3
	v_lshl_add_u64 v[68:69], v[28:29], 0, v[30:31]
	global_load_dword v70, v[68:69], off offset:160 nt
	global_load_dword v71, v[68:69], off offset:168 nt
	global_load_dword v72, v[68:69], off offset:176 nt
	global_load_dword v31, v[68:69], off offset:184 nt
	v_add_u32_e32 v69, v27, v43
	s_waitcnt vmcnt(3)
	v_mul_f32_e32 v70, v65, v70
	s_waitcnt vmcnt(2)
	v_mul_f32_e32 v71, v67, v71
	s_waitcnt vmcnt(1)
	v_mul_f32_e32 v68, v66, v72
	ds_write2_b32 v69, v70, v71 offset1:66
	s_cbranch_execnz .LBB0_47

.LBB0_47:
	v_add_u32_e32 v65, v27, v44
	s_waitcnt vmcnt(0)
	v_mul_f32_e32 v31, v64, v31
	s_and_b64 vcc, exec, s[6:7]
	ds_write2_b32 v65, v68, v31 offset1:66
	s_cbranch_vccnz .LBB0_183
	v_mov_b32_e32 v31, v3
	v_lshl_add_u64 v[64:65], v[28:29], 0, v[30:31]
	global_load_dword v66, v[64:65], off offset:192 nt
	global_load_dword v67, v[64:65], off offset:200 nt
	global_load_dword v68, v[64:65], off offset:208 nt
	global_load_dword v31, v[64:65], off offset:216 nt
	v_add_u32_e32 v65, v27, v45
	s_waitcnt vmcnt(3)
	v_mul_f32_e32 v66, v60, v66
	s_waitcnt vmcnt(2)
	v_mul_f32_e32 v67, v61, v67
	s_waitcnt vmcnt(1)
	v_mul_f32_e32 v64, v63, v68
	ds_write2_b32 v65, v66, v67 offset1:66
	s_cbranch_execnz .LBB0_50

.LBB0_50:
	v_add_u32_e32 v60, v27, v45
	s_waitcnt vmcnt(0)
	v_mul_f32_e32 v31, v62, v31
	ds_write2_b32 v60, v64, v31 offset0:132 offset1:198
	s_and_b64 vcc, exec, s[6:7]
	v_add_u32_e32 v60, 0x400, v60
	s_cbranch_vccnz .LBB0_184
	v_mov_b32_e32 v31, v3
	v_lshl_add_u64 v[28:29], v[28:29], 0, v[30:31]
	global_load_dword v30, v[28:29], off offset:224 nt
	global_load_dword v31, v[28:29], off offset:232 nt
	global_load_dword v61, v[28:29], off offset:240 nt
	s_nop 0
	global_load_dword v28, v[28:29], off offset:248 nt
	s_waitcnt vmcnt(3)
	v_mul_f32_e32 v30, v21, v30
	s_waitcnt vmcnt(2)
	v_mul_f32_e32 v31, v58, v31
	s_waitcnt vmcnt(1)
	v_mul_f32_e32 v29, v59, v61
	ds_write2_b32 v60, v30, v31 offset0:8 offset1:74
	s_cbranch_execnz .LBB0_53

.LBB0_53:
	s_waitcnt vmcnt(0)
	v_mul_f32_e32 v19, v19, v28
	ds_write2_b32 v60, v29, v19 offset0:140 offset1:206
	v_readlane_b32 s6, v242, 11
	s_waitcnt lgkmcnt(0)
	v_readlane_b32 s7, v242, 12
	v_lshl_add_u64 v[22:23], v[22:23], 2, s[56:57]
	v_or_b32_e32 v28, v57, v46
	v_cndmask_b32_e64 v21, 0, 1, s[6:7]
	v_mov_b32_e32 v19, 1.0
	v_cmp_ne_u32_e64 s[0:1], 1, v21
	s_andn2_b64 vcc, exec, s[6:7]
	v_mov_b32_e32 v29, 1.0
	s_cbranch_vccnz .LBB0_55
	v_lshlrev_b32_e32 v30, 2, v28
	v_mov_b32_e32 v31, v3
	v_lshl_add_u64 v[30:31], v[22:23], 0, v[30:31]
	global_load_dword v29, v[30:31], off nt
.LBB0_55:
	v_readlane_b32 s6, v242, 3
	v_lshlrev_b64 v[30:31], 16, v[2:3]
	v_readlane_b32 s7, v242, 4
	v_lshlrev_b32_e32 v2, 1, v20
	ds_read2_b32 v[58:59], v47 offset1:33
	v_lshl_add_u64 v[30:31], v[30:31], 1, s[6:7]
	v_lshl_add_u64 v[20:21], v[30:31], 0, v[2:3]
	ds_read2_b32 v[30:31], v47 offset0:66 offset1:99
	v_lshlrev_b32_e32 v2, 1, v4
	v_lshl_add_u64 v[20:21], v[20:21], 0, v[2:3]
	s_waitcnt vmcnt(0) lgkmcnt(1)
	v_mul_f32_e32 v2, v29, v58
	v_mul_f32_e32 v58, v29, v59
	ds_read2_b32 v[60:61], v47 offset0:132 offset1:165
	v_cvt_pk_bf16_f32 v58, v2, v58
	s_waitcnt lgkmcnt(1)
	v_mul_f32_e32 v2, v29, v30
	v_mul_f32_e32 v59, v29, v31
	ds_read2_b32 v[30:31], v47 offset0:198 offset1:231
	v_cvt_pk_bf16_f32 v59, v2, v59
	s_waitcnt lgkmcnt(1)
	v_mul_f32_e32 v2, v29, v60
	v_mul_f32_e32 v60, v29, v61
	v_cvt_pk_bf16_f32 v60, v2, v60
	s_waitcnt lgkmcnt(0)
	v_mul_f32_e32 v2, v29, v30
	v_mul_f32_e32 v29, v29, v31
	v_cvt_pk_bf16_f32 v61, v2, v29
	v_lshlrev_b32_e32 v2, 9, v28
	v_lshl_add_u64 v[28:29], v[20:21], 0, v[2:3]
	global_store_dwordx4 v[28:29], v[58:61], off
	s_and_b64 vcc, exec, s[0:1]
	v_add_lshl_u32 v28, v57, v46, 2
	s_cbranch_vccnz .LBB0_57
	v_mov_b32_e32 v29, v3
	v_lshl_add_u64 v[30:31], v[22:23], 0, v[28:29]
	global_load_dword v19, v[30:31], off offset:32 nt
.LBB0_57:
	ds_read2_b32 v[30:31], v47 offset0:8 offset1:41
	ds_read2_b32 v[60:61], v47 offset0:74 offset1:107
	ds_read2_b32 v[62:63], v47 offset0:140 offset1:173
	v_or_b32_e32 v2, v57, v48
	v_lshlrev_b32_e32 v2, 9, v2
	s_and_b64 vcc, exec, s[0:1]
	s_waitcnt vmcnt(0) lgkmcnt(2)
	v_mul_f32_e32 v29, v19, v30
	v_mul_f32_e32 v30, v19, v31
	v_cvt_pk_bf16_f32 v58, v29, v30
	ds_read2_b32 v[30:31], v47 offset0:206 offset1:239
	s_waitcnt lgkmcnt(2)
	v_mul_f32_e32 v29, v19, v60
	v_mul_f32_e32 v59, v19, v61
	v_cvt_pk_bf16_f32 v59, v29, v59
	s_waitcnt lgkmcnt(1)
	v_mul_f32_e32 v29, v19, v62
	v_mul_f32_e32 v60, v19, v63
	v_cvt_pk_bf16_f32 v60, v29, v60
	s_waitcnt lgkmcnt(0)
	v_mul_f32_e32 v29, v19, v30
	v_mul_f32_e32 v19, v19, v31
	v_cvt_pk_bf16_f32 v61, v29, v19
	v_lshl_add_u64 v[30:31], v[20:21], 0, v[2:3]
	v_mov_b32_e32 v19, 1.0
	v_mov_b32_e32 v2, 1.0
	global_store_dwordx4 v[30:31], v[58:61], off
	s_cbranch_vccnz .LBB0_59
	v_mov_b32_e32 v29, v3
	v_lshl_add_u64 v[30:31], v[22:23], 0, v[28:29]
	global_load_dword v2, v[30:31], off offset:64 nt
.LBB0_59:
	ds_read2_b32 v[30:31], v47 offset0:16 offset1:49
	ds_read2_b32 v[60:61], v47 offset0:82 offset1:115
	ds_read2_b32 v[62:63], v47 offset0:148 offset1:181
	v_or_b32_e32 v29, v57, v49
	s_and_b64 vcc, exec, s[0:1]
	s_waitcnt vmcnt(0) lgkmcnt(1)
	v_mul_f32_e32 v59, v2, v60
	v_mul_f32_e32 v30, v2, v30
	v_mul_f32_e32 v31, v2, v31
	v_cvt_pk_bf16_f32 v58, v30, v31
	ds_read2_b32 v[30:31], v47 offset0:214 offset1:247
	v_mul_f32_e32 v60, v2, v61
	v_cvt_pk_bf16_f32 v59, v59, v60
	s_waitcnt lgkmcnt(1)
	v_mul_f32_e32 v60, v2, v62
	v_mul_f32_e32 v61, v2, v63
	s_waitcnt lgkmcnt(0)
	v_mul_f32_e32 v30, v2, v30
	v_mul_f32_e32 v2, v2, v31
	v_cvt_pk_bf16_f32 v60, v60, v61
	v_cvt_pk_bf16_f32 v61, v30, v2
	v_lshlrev_b32_e32 v2, 9, v29
	v_lshl_add_u64 v[30:31], v[20:21], 0, v[2:3]
	global_store_dwordx4 v[30:31], v[58:61], off
	s_cbranch_vccnz .LBB0_61
	v_mov_b32_e32 v29, v3
	v_lshl_add_u64 v[22:23], v[22:23], 0, v[28:29]
	global_load_dword v19, v[22:23], off offset:96 nt

.LBB0_62:
	s_andn2_saveexec_b64 s[0:1], s[76:77]
	s_cbranch_execz .LBB0_64
	v_add_u32_e32 v2, 0xffffd580, v56
	v_lshrrev_b32_e32 v2, 7, v2
	v_lshlrev_b64 v[20:21], 20, v[2:3]
	v_and_b32_e32 v74, 0x3e0, v51
	v_lshl_add_u64 v[20:21], s[68:69], 0, v[20:21]
	v_lshlrev_b64 v[22:23], 19, v[2:3]
	v_and_b32_e32 v57, 0xc0, v54
	v_lshlrev_b32_e32 v2, 2, v74
	v_or_b32_e32 v28, v57, v0
	v_lshl_add_u64 v[20:21], v[20:21], 0, v[2:3]
	v_mov_b32_e32 v19, v3
	v_lshl_add_u64 v[20:21], v[20:21], 0, v[18:19]
	v_lshlrev_b32_e32 v2, 12, v28
	v_lshl_add_u64 v[20:21], v[20:21], 0, v[2:3]
	s_movk_i32 s6, 0x2000
	v_add_co_u32_e32 v28, vcc, s6, v20
	s_movk_i32 s6, 0x4000
	s_nop 0
	v_addc_co_u32_e32 v29, vcc, 0, v21, vcc
	v_add_co_u32_e32 v30, vcc, s6, v20
	s_movk_i32 s6, 0x6000
	s_nop 0
	v_addc_co_u32_e32 v31, vcc, 0, v21, vcc
	v_add_co_u32_e32 v58, vcc, s6, v20
	s_mov_b32 s6, 0x8000
	s_nop 0
	v_addc_co_u32_e32 v59, vcc, 0, v21, vcc
	v_add_co_u32_e32 v60, vcc, s6, v20
	s_mov_b32 s6, 0xa000
	s_nop 0
	v_addc_co_u32_e32 v61, vcc, 0, v21, vcc
	v_add_co_u32_e32 v62, vcc, s6, v20
	s_mov_b32 s6, 0xc000
	s_nop 0
	v_addc_co_u32_e32 v63, vcc, 0, v21, vcc
	v_add_co_u32_e32 v64, vcc, s6, v20
	s_mov_b32 s6, 0xe000
	s_nop 0
	v_addc_co_u32_e32 v65, vcc, 0, v21, vcc
	v_add_co_u32_e32 v66, vcc, s6, v20
	s_mov_b32 s6, 0x10000
	s_nop 0
	v_addc_co_u32_e32 v67, vcc, 0, v21, vcc
	global_load_dword v2, v[20:21], off nt
	global_load_dword v19, v[28:29], off nt
	global_load_dword v70, v[30:31], off nt
	global_load_dword v71, v[58:59], off nt
	global_load_dword v72, v[60:61], off nt
	global_load_dword v73, v[62:63], off nt
	global_load_dword v75, v[64:65], off nt
	global_load_dword v76, v[66:67], off nt
	v_add_co_u32_e32 v28, vcc, s6, v20
	s_mov_b32 s6, 0x12000
	s_nop 0
	v_addc_co_u32_e32 v29, vcc, 0, v21, vcc
	v_add_co_u32_e32 v30, vcc, s6, v20
	s_mov_b32 s6, 0x14000
	s_nop 0
	v_addc_co_u32_e32 v31, vcc, 0, v21, vcc
	v_add_co_u32_e32 v58, vcc, s6, v20
	s_mov_b32 s6, 0x16000
	s_nop 0
	v_addc_co_u32_e32 v59, vcc, 0, v21, vcc
	v_add_co_u32_e32 v60, vcc, s6, v20
	s_mov_b32 s6, 0x18000
	s_nop 0
	v_addc_co_u32_e32 v61, vcc, 0, v21, vcc
	v_add_co_u32_e32 v62, vcc, s6, v20
	s_mov_b32 s6, 0x1a000
	s_nop 0
	v_addc_co_u32_e32 v63, vcc, 0, v21, vcc
	v_add_co_u32_e32 v64, vcc, s6, v20
	s_mov_b32 s6, 0x1c000
	s_nop 0
	v_addc_co_u32_e32 v65, vcc, 0, v21, vcc
	v_add_co_u32_e32 v66, vcc, s6, v20
	s_mov_b32 s6, 0x1e000
	s_nop 0
	v_addc_co_u32_e32 v67, vcc, 0, v21, vcc
	v_add_co_u32_e32 v68, vcc, s6, v20
	s_mov_b32 s6, 0x20000
	s_nop 0
	v_addc_co_u32_e32 v69, vcc, 0, v21, vcc
	global_load_dword v77, v[28:29], off nt
	global_load_dword v78, v[30:31], off nt
	global_load_dword v79, v[58:59], off nt
	global_load_dword v80, v[60:61], off nt
	global_load_dword v81, v[62:63], off nt
	global_load_dword v82, v[64:65], off nt
	global_load_dword v83, v[66:67], off nt
	global_load_dword v84, v[68:69], off nt
	v_add_co_u32_e32 v28, vcc, s6, v20
	s_mov_b32 s6, 0x22000
	s_nop 0
	v_addc_co_u32_e32 v29, vcc, 0, v21, vcc
	v_add_co_u32_e32 v30, vcc, s6, v20
	s_mov_b32 s6, 0x24000
	s_nop 0
	v_addc_co_u32_e32 v31, vcc, 0, v21, vcc
	v_add_co_u32_e32 v58, vcc, s6, v20
	s_mov_b32 s6, 0x26000
	s_nop 0
	v_addc_co_u32_e32 v59, vcc, 0, v21, vcc
	v_add_co_u32_e32 v60, vcc, s6, v20
	s_mov_b32 s6, 0x28000
	s_nop 0
	v_addc_co_u32_e32 v61, vcc, 0, v21, vcc
	v_add_co_u32_e32 v62, vcc, s6, v20
	s_mov_b32 s6, 0x2a000
	s_nop 0
	v_addc_co_u32_e32 v63, vcc, 0, v21, vcc
	v_add_co_u32_e32 v64, vcc, s6, v20
	s_mov_b32 s6, 0x2c000
	s_nop 0
	v_addc_co_u32_e32 v65, vcc, 0, v21, vcc
	v_add_co_u32_e32 v66, vcc, s6, v20
	s_mov_b32 s6, 0x2e000
	s_nop 0
	v_addc_co_u32_e32 v67, vcc, 0, v21, vcc
	v_add_co_u32_e32 v68, vcc, s6, v20
	s_mov_b32 s6, 0x30000
	s_nop 0
	v_addc_co_u32_e32 v69, vcc, 0, v21, vcc
	global_load_dword v85, v[28:29], off nt
	global_load_dword v86, v[30:31], off nt
	global_load_dword v87, v[58:59], off nt
	global_load_dword v88, v[60:61], off nt
	global_load_dword v89, v[62:63], off nt
	global_load_dword v90, v[64:65], off nt
	global_load_dword v91, v[66:67], off nt
	s_nop 0
	global_load_dword v68, v[68:69], off nt
	v_add_co_u32_e32 v28, vcc, s6, v20
	s_mov_b32 s6, 0x32000
	s_nop 0
	v_addc_co_u32_e32 v29, vcc, 0, v21, vcc
	v_add_co_u32_e32 v30, vcc, s6, v20
	s_mov_b32 s6, 0x34000
	s_nop 0
	v_addc_co_u32_e32 v31, vcc, 0, v21, vcc
	v_add_co_u32_e32 v58, vcc, s6, v20
	s_mov_b32 s6, 0x36000
	s_nop 0
	v_addc_co_u32_e32 v59, vcc, 0, v21, vcc
	v_add_co_u32_e32 v60, vcc, s6, v20
	s_mov_b32 s6, 0x38000
	s_nop 0
	v_addc_co_u32_e32 v61, vcc, 0, v21, vcc
	v_add_co_u32_e32 v62, vcc, s6, v20
	s_mov_b32 s6, 0x3a000
	s_nop 0
	v_addc_co_u32_e32 v63, vcc, 0, v21, vcc
	v_add_co_u32_e32 v64, vcc, s6, v20
	s_mov_b32 s6, 0x3c000
	s_nop 0
	v_addc_co_u32_e32 v65, vcc, 0, v21, vcc
	v_add_co_u32_e32 v66, vcc, s6, v20
	s_mov_b32 s6, 0x3e000
	s_nop 0
	v_addc_co_u32_e32 v67, vcc, 0, v21, vcc
	v_add_co_u32_e32 v20, vcc, s6, v20
	v_readlane_b32 s6, v242, 5
	s_nop 0
	v_addc_co_u32_e32 v21, vcc, 0, v21, vcc
	global_load_dword v28, v[28:29], off nt
	s_nop 0
	global_load_dword v29, v[30:31], off nt
	s_nop 0
	global_load_dword v30, v[58:59], off nt
	global_load_dword v31, v[60:61], off nt
	s_nop 0
	global_load_dword v58, v[62:63], off nt
	global_load_dword v59, v[64:65], off nt
	global_load_dword v60, v[66:67], off nt
	global_load_dword v61, v[20:21], off nt
	s_waitcnt vmcnt(30)
	ds_write2_b32 v32, v2, v19 offset1:66
	s_waitcnt vmcnt(28)
	ds_write2_b32 v32, v70, v71 offset0:132 offset1:198
	v_add_u32_e32 v2, 0x400, v32
	s_waitcnt vmcnt(26)
	ds_write2_b32 v2, v72, v73 offset0:8 offset1:74
	s_waitcnt vmcnt(24)
	ds_write2_b32 v2, v75, v76 offset0:140 offset1:206
	v_add_u32_e32 v2, 0x800, v32
	s_waitcnt vmcnt(22)
	ds_write2_b32 v2, v77, v78 offset0:16 offset1:82
	s_waitcnt vmcnt(20)
	ds_write2_b32 v2, v79, v80 offset0:148 offset1:214
	v_add_u32_e32 v2, 0xc00, v32
	s_waitcnt vmcnt(18)
	ds_write2_b32 v2, v81, v82 offset0:24 offset1:90
	s_waitcnt vmcnt(16)
	ds_write2_b32 v2, v83, v84 offset0:156 offset1:222
	v_add_u32_e32 v2, 0x1000, v32
	s_waitcnt vmcnt(14)
	ds_write2_b32 v2, v85, v86 offset0:32 offset1:98
	s_waitcnt vmcnt(12)
	ds_write2_b32 v2, v87, v88 offset0:164 offset1:230
	v_add_u32_e32 v2, 0x1400, v32
	s_waitcnt vmcnt(10)
	ds_write2_b32 v2, v89, v90 offset0:40 offset1:106
	s_waitcnt vmcnt(8)
	ds_write2_b32 v2, v91, v68 offset0:172 offset1:238
	v_add_u32_e32 v2, 0x1800, v32
	s_waitcnt vmcnt(6)
	ds_write2_b32 v2, v28, v29 offset0:48 offset1:114
	s_waitcnt vmcnt(4)
	ds_write2_b32 v2, v30, v31 offset0:180 offset1:246
	v_add_u32_e32 v2, 0x1c00, v32
	v_readlane_b32 s7, v242, 6
	s_waitcnt vmcnt(2)
	ds_write2_b32 v2, v58, v59 offset0:56 offset1:122
	s_waitcnt vmcnt(0)
	ds_write2_b32 v2, v60, v61 offset0:188 offset1:254
	v_lshl_add_u64 v[20:21], s[6:7], 0, v[22:23]
	s_waitcnt lgkmcnt(0)
	v_lshlrev_b32_e32 v2, 1, v57
	v_lshl_add_u64 v[20:21], v[20:21], 0, v[2:3]
	v_lshlrev_b32_e32 v2, 1, v4
	ds_read2_b32 v[30:31], v47 offset0:33 offset1:41
	ds_read2_b32 v[58:59], v47 offset1:8
	ds_read2_b32 v[60:61], v47 offset0:66 offset1:74
	ds_read2_b32 v[62:63], v47 offset0:99 offset1:107
	ds_read2_b32 v[64:65], v47 offset0:132 offset1:140
	ds_read2_b32 v[66:67], v47 offset0:165 offset1:173
	ds_read2_b32 v[68:69], v47 offset0:198 offset1:206
	ds_read2_b32 v[70:71], v47 offset0:231 offset1:239
	v_lshl_add_u64 v[28:29], v[20:21], 0, v[2:3]
	v_or_b32_e32 v2, v74, v46
	v_lshlrev_b32_e32 v2, 9, v2
	v_lshl_add_u64 v[72:73], v[28:29], 0, v[2:3]
	v_or_b32_e32 v2, v74, v48
	s_waitcnt lgkmcnt(6)
	v_cvt_pk_bf16_f32 v20, v58, v30
	v_lshlrev_b32_e32 v2, 9, v2
	s_waitcnt lgkmcnt(4)
	v_cvt_pk_bf16_f32 v21, v60, v62
	s_waitcnt lgkmcnt(2)
	v_cvt_pk_bf16_f32 v22, v64, v66
	s_waitcnt lgkmcnt(0)
	v_cvt_pk_bf16_f32 v23, v68, v70
	global_store_dwordx4 v[72:73], v[20:23], off
	s_nop 1
	v_cvt_pk_bf16_f32 v20, v59, v31
	v_lshl_add_u64 v[30:31], v[28:29], 0, v[2:3]
	v_cvt_pk_bf16_f32 v21, v61, v63
	v_cvt_pk_bf16_f32 v22, v65, v67
	v_cvt_pk_bf16_f32 v23, v69, v71
	global_store_dwordx4 v[30:31], v[20:23], off
	ds_read2_b32 v[30:31], v47 offset0:16 offset1:24
	ds_read2_b32 v[58:59], v47 offset0:49 offset1:57
	ds_read2_b32 v[60:61], v47 offset0:82 offset1:90
	ds_read2_b32 v[62:63], v47 offset0:115 offset1:123
	ds_read2_b32 v[64:65], v47 offset0:148 offset1:156
	ds_read2_b32 v[66:67], v47 offset0:181 offset1:189
	ds_read2_b32 v[68:69], v47 offset0:214 offset1:222
	ds_read2_b32 v[70:71], v47 offset0:247 offset1:255
	v_or_b32_e32 v2, v74, v49
	v_lshlrev_b32_e32 v2, 9, v2
	v_lshl_add_u64 v[72:73], v[28:29], 0, v[2:3]
	v_or_b32_e32 v2, v74, v50
	v_lshlrev_b32_e32 v2, 9, v2
	s_waitcnt lgkmcnt(6)
	v_cvt_pk_bf16_f32 v20, v30, v58
	s_waitcnt lgkmcnt(4)
	v_cvt_pk_bf16_f32 v21, v60, v62
	s_waitcnt lgkmcnt(2)
	v_cvt_pk_bf16_f32 v22, v64, v66
	s_waitcnt lgkmcnt(0)
	v_cvt_pk_bf16_f32 v23, v68, v70
	v_lshl_add_u64 v[28:29], v[28:29], 0, v[2:3]
	global_store_dwordx4 v[72:73], v[20:23], off
	s_nop 1
	v_cvt_pk_bf16_f32 v20, v31, v59
	v_cvt_pk_bf16_f32 v21, v61, v63
	v_cvt_pk_bf16_f32 v22, v65, v67
	v_cvt_pk_bf16_f32 v23, v69, v71
	global_store_dwordx4 v[28:29], v[20:23], off
	s_waitcnt lgkmcnt(0)

.LBB0_65:
	s_andn2_saveexec_b64 s[0:1], s[42:43]
	s_cbranch_execz .LBB0_91
	v_add_u32_e32 v2, 0xffffd980, v56
	v_lshrrev_b32_e32 v2, 9, v2
	v_lshlrev_b64 v[20:21], 22, v[2:3]
	v_lshl_add_u64 v[22:23], s[66:67], 0, v[20:21]
	v_add_u32_e32 v19, 0xffffb300, v54
	v_and_b32_e32 v21, 0x3e0, v51
	v_and_b32_e32 v20, 0x3c0, v19
	v_lshlrev_b32_e32 v30, 2, v21
	v_mov_b32_e32 v31, v3
	v_or_b32_e32 v29, v20, v0
	v_lshl_add_u64 v[22:23], v[22:23], 0, v[30:31]
	v_mov_b32_e32 v19, v3
	v_lshl_add_u64 v[22:23], v[22:23], 0, v[18:19]
	v_lshlrev_b32_e32 v30, 12, v29
	v_lshl_add_u64 v[22:23], v[22:23], 0, v[30:31]
	s_movk_i32 s6, 0x2000
	v_add_co_u32_e32 v30, vcc, s6, v22
	s_movk_i32 s6, 0x4000
	s_nop 0
	v_addc_co_u32_e32 v31, vcc, 0, v23, vcc
	v_add_co_u32_e32 v58, vcc, s6, v22
	s_movk_i32 s6, 0x6000
	s_nop 0
	v_addc_co_u32_e32 v59, vcc, 0, v23, vcc
	v_add_co_u32_e32 v60, vcc, s6, v22
	s_mov_b32 s6, 0x8000
	s_nop 0
	v_addc_co_u32_e32 v61, vcc, 0, v23, vcc
	v_add_co_u32_e32 v62, vcc, s6, v22
	s_mov_b32 s6, 0xa000
	s_nop 0
	v_addc_co_u32_e32 v63, vcc, 0, v23, vcc
	v_add_co_u32_e32 v64, vcc, s6, v22
	s_mov_b32 s6, 0xc000
	s_nop 0
	v_addc_co_u32_e32 v65, vcc, 0, v23, vcc
	v_add_co_u32_e32 v66, vcc, s6, v22
	s_mov_b32 s6, 0xe000
	s_nop 0
	v_addc_co_u32_e32 v67, vcc, 0, v23, vcc
	v_add_co_u32_e32 v68, vcc, s6, v22
	s_mov_b32 s6, 0x10000
	s_nop 0
	v_addc_co_u32_e32 v69, vcc, 0, v23, vcc
	global_load_dword v85, v[22:23], off nt
	global_load_dword v84, v[30:31], off nt
	global_load_dword v83, v[58:59], off nt
	global_load_dword v82, v[60:61], off nt
	global_load_dword v79, v[62:63], off nt
	global_load_dword v81, v[64:65], off nt
	global_load_dword v80, v[66:67], off nt
	global_load_dword v75, v[68:69], off nt
	v_add_co_u32_e32 v30, vcc, s6, v22
	s_mov_b32 s6, 0x12000
	s_nop 0
	v_addc_co_u32_e32 v31, vcc, 0, v23, vcc
	v_add_co_u32_e32 v58, vcc, s6, v22
	s_mov_b32 s6, 0x14000
	s_nop 0
	v_addc_co_u32_e32 v59, vcc, 0, v23, vcc
	v_add_co_u32_e32 v60, vcc, s6, v22
	s_mov_b32 s6, 0x16000
	s_nop 0
	v_addc_co_u32_e32 v61, vcc, 0, v23, vcc
	v_add_co_u32_e32 v62, vcc, s6, v22
	s_mov_b32 s6, 0x18000
	s_nop 0
	v_addc_co_u32_e32 v63, vcc, 0, v23, vcc
	v_add_co_u32_e32 v64, vcc, s6, v22
	s_mov_b32 s6, 0x1a000
	s_nop 0
	v_addc_co_u32_e32 v65, vcc, 0, v23, vcc
	v_add_co_u32_e32 v66, vcc, s6, v22
	s_mov_b32 s6, 0x1c000
	s_nop 0
	v_addc_co_u32_e32 v67, vcc, 0, v23, vcc
	v_add_co_u32_e32 v68, vcc, s6, v22
	s_mov_b32 s6, 0x1e000
	s_nop 0
	v_addc_co_u32_e32 v69, vcc, 0, v23, vcc
	v_add_co_u32_e32 v86, vcc, s6, v22
	s_mov_b32 s6, 0x20000
	s_nop 0
	v_addc_co_u32_e32 v87, vcc, 0, v23, vcc
	global_load_dword v76, v[30:31], off nt
	global_load_dword v78, v[58:59], off nt
	global_load_dword v77, v[60:61], off nt
	global_load_dword v74, v[62:63], off nt
	global_load_dword v71, v[64:65], off nt
	global_load_dword v73, v[66:67], off nt
	global_load_dword v72, v[68:69], off nt
	s_nop 0
	global_load_dword v67, v[86:87], off nt
	v_add_co_u32_e32 v30, vcc, s6, v22
	s_mov_b32 s6, 0x22000
	s_nop 0
	v_addc_co_u32_e32 v31, vcc, 0, v23, vcc
	v_add_co_u32_e32 v58, vcc, s6, v22
	s_mov_b32 s6, 0x24000
	s_nop 0
	v_addc_co_u32_e32 v59, vcc, 0, v23, vcc
	v_add_co_u32_e32 v60, vcc, s6, v22
	s_mov_b32 s6, 0x26000
	s_nop 0
	v_addc_co_u32_e32 v61, vcc, 0, v23, vcc
	v_add_co_u32_e32 v62, vcc, s6, v22
	s_mov_b32 s6, 0x28000
	s_nop 0
	v_addc_co_u32_e32 v63, vcc, 0, v23, vcc
	v_add_co_u32_e32 v64, vcc, s6, v22
	s_mov_b32 s6, 0x2a000
	s_nop 0
	v_addc_co_u32_e32 v65, vcc, 0, v23, vcc
	v_add_co_u32_e32 v86, vcc, s6, v22
	s_mov_b32 s6, 0x2c000
	s_nop 0
	v_addc_co_u32_e32 v87, vcc, 0, v23, vcc
	v_add_co_u32_e32 v88, vcc, s6, v22
	s_mov_b32 s6, 0x2e000
	s_nop 0
	v_addc_co_u32_e32 v89, vcc, 0, v23, vcc
	v_add_co_u32_e32 v90, vcc, s6, v22
	s_mov_b32 s6, 0x30000
	s_nop 0
	v_addc_co_u32_e32 v91, vcc, 0, v23, vcc
	global_load_dword v68, v[30:31], off nt
	global_load_dword v70, v[58:59], off nt
	global_load_dword v69, v[60:61], off nt
	global_load_dword v66, v[62:63], off nt
	s_nop 0
	global_load_dword v59, v[64:65], off nt
	global_load_dword v61, v[86:87], off nt
	global_load_dword v60, v[88:89], off nt
	global_load_dword v58, v[90:91], off nt
	v_add_co_u32_e32 v30, vcc, s6, v22
	s_mov_b32 s6, 0x32000
	s_nop 0
	v_addc_co_u32_e32 v31, vcc, 0, v23, vcc
	v_add_co_u32_e32 v64, vcc, s6, v22
	s_mov_b32 s6, 0x34000
	s_nop 0
	v_addc_co_u32_e32 v65, vcc, 0, v23, vcc
	v_add_co_u32_e32 v86, vcc, s6, v22
	s_mov_b32 s6, 0x36000
	s_nop 0
	v_addc_co_u32_e32 v87, vcc, 0, v23, vcc
	v_add_co_u32_e32 v88, vcc, s6, v22
	s_mov_b32 s6, 0x38000
	s_nop 0
	v_addc_co_u32_e32 v89, vcc, 0, v23, vcc
	v_add_co_u32_e32 v90, vcc, s6, v22
	v_readlane_b32 s42, v242, 13
	s_nop 0
	v_addc_co_u32_e32 v91, vcc, 0, v23, vcc
	v_add_co_u32_e32 v92, vcc, 0x3a000, v22
	v_readlane_b32 s43, v242, 14
	s_nop 0
	v_addc_co_u32_e32 v93, vcc, 0, v23, vcc
	v_add_co_u32_e32 v94, vcc, 0x3c000, v22
	v_cndmask_b32_e64 v28, 0, 1, s[42:43]
	s_nop 0
	v_addc_co_u32_e32 v95, vcc, 0, v23, vcc
	v_add_co_u32_e32 v22, vcc, 0x3e000, v22
	v_cmp_ne_u32_e64 s[6:7], 1, v28
	s_nop 0
	v_addc_co_u32_e32 v23, vcc, 0, v23, vcc
	global_load_dword v63, v[30:31], off nt
	s_nop 0
	global_load_dword v65, v[64:65], off nt
	s_nop 0
	global_load_dword v64, v[86:87], off nt
	global_load_dword v62, v[88:89], off nt
	global_load_dword v30, v[90:91], off nt
	global_load_dword v57, v[92:93], off nt
	global_load_dword v31, v[94:95], off nt
	global_load_dword v19, v[22:23], off nt
	v_lshlrev_b32_e32 v22, 10, v2
	v_mov_b32_e32 v23, v3
	v_lshl_add_u64 v[22:23], v[22:23], 2, s[64:65]
	s_andn2_b64 vcc, exec, s[42:43]
	v_add_lshl_u32 v28, v20, v0, 2
	s_cbranch_vccnz .LBB0_169
	v_lshlrev_b32_e32 v86, 2, v29
	v_mov_b32_e32 v87, v3
	v_lshl_add_u64 v[86:87], v[22:23], 0, v[86:87]
	v_mov_b32_e32 v29, v3
	v_lshl_add_u64 v[88:89], v[22:23], 0, v[28:29]
	global_load_dword v86, v[86:87], off nt
	s_nop 0
	global_load_dword v87, v[88:89], off offset:8 nt
	global_load_dword v90, v[88:89], off offset:16 nt
	global_load_dword v29, v[88:89], off offset:24 nt
	v_add_u32_e32 v88, v27, v33
	s_waitcnt vmcnt(3)
	v_mul_f32_e32 v89, v85, v86
	s_waitcnt vmcnt(2)
	v_mul_f32_e32 v87, v84, v87
	s_waitcnt vmcnt(1)
	v_mul_f32_e32 v86, v83, v90
	ds_write_b32 v32, v89
	ds_write_b32 v88, v87
	s_cbranch_execnz .LBB0_69

.LBB0_69:
	s_waitcnt vmcnt(29)
	v_add_u32_e32 v83, v27, v34
	s_waitcnt vmcnt(0)
	v_mul_f32_e32 v29, v82, v29
	s_and_b64 vcc, exec, s[6:7]
	ds_write2_b32 v83, v86, v29 offset1:66
	s_cbranch_vccnz .LBB0_170
	v_mov_b32_e32 v29, v3
	v_lshl_add_u64 v[82:83], v[22:23], 0, v[28:29]
	global_load_dword v84, v[82:83], off offset:32 nt
	global_load_dword v85, v[82:83], off offset:40 nt
	global_load_dword v86, v[82:83], off offset:48 nt
	global_load_dword v29, v[82:83], off offset:56 nt
	v_add_u32_e32 v83, v27, v35
	s_waitcnt vmcnt(3)
	v_mul_f32_e32 v84, v79, v84
	s_waitcnt vmcnt(2)
	v_mul_f32_e32 v85, v81, v85
	s_waitcnt vmcnt(1)
	v_mul_f32_e32 v82, v80, v86
	ds_write2_b32 v83, v84, v85 offset1:66
	s_cbranch_execnz .LBB0_72

.LBB0_72:
	v_add_u32_e32 v79, v27, v36
	s_waitcnt vmcnt(0)
	v_mul_f32_e32 v29, v75, v29
	s_and_b64 vcc, exec, s[6:7]
	ds_write2_b32 v79, v82, v29 offset1:66
	s_cbranch_vccnz .LBB0_171
	v_mov_b32_e32 v29, v3
	v_lshl_add_u64 v[80:81], v[22:23], 0, v[28:29]
	global_load_dword v75, v[80:81], off offset:64 nt
	global_load_dword v79, v[80:81], off offset:72 nt
	global_load_dword v82, v[80:81], off offset:80 nt
	global_load_dword v29, v[80:81], off offset:88 nt
	v_add_u32_e32 v80, v27, v37
	s_waitcnt vmcnt(3)
	v_mul_f32_e32 v81, v76, v75
	s_waitcnt vmcnt(2)
	v_mul_f32_e32 v79, v78, v79
	s_waitcnt vmcnt(1)
	v_mul_f32_e32 v75, v77, v82
	ds_write2_b32 v80, v81, v79 offset1:66
	s_cbranch_execnz .LBB0_75

.LBB0_75:
	v_add_u32_e32 v76, v27, v38
	s_waitcnt vmcnt(0)
	v_mul_f32_e32 v29, v74, v29
	s_and_b64 vcc, exec, s[6:7]
	ds_write2_b32 v76, v75, v29 offset1:66
	s_cbranch_vccnz .LBB0_172
	v_mov_b32_e32 v29, v3
	v_lshl_add_u64 v[74:75], v[22:23], 0, v[28:29]
	global_load_dword v76, v[74:75], off offset:96 nt
	global_load_dword v77, v[74:75], off offset:104 nt
	global_load_dword v78, v[74:75], off offset:112 nt
	global_load_dword v29, v[74:75], off offset:120 nt
	v_add_u32_e32 v75, v27, v39
	s_waitcnt vmcnt(3)
	v_mul_f32_e32 v76, v71, v76
	s_waitcnt vmcnt(2)
	v_mul_f32_e32 v77, v73, v77
	s_waitcnt vmcnt(1)
	v_mul_f32_e32 v74, v72, v78
	ds_write2_b32 v75, v76, v77 offset1:66
	s_cbranch_execnz .LBB0_78

.LBB0_78:
	v_add_u32_e32 v71, v27, v40
	s_waitcnt vmcnt(0)
	v_mul_f32_e32 v29, v67, v29
	s_and_b64 vcc, exec, s[6:7]
	ds_write2_b32 v71, v74, v29 offset1:66
	s_cbranch_vccnz .LBB0_173
	v_mov_b32_e32 v29, v3
	v_lshl_add_u64 v[72:73], v[22:23], 0, v[28:29]
	global_load_dword v67, v[72:73], off offset:128 nt
	global_load_dword v71, v[72:73], off offset:136 nt
	global_load_dword v74, v[72:73], off offset:144 nt
	global_load_dword v29, v[72:73], off offset:152 nt
	v_add_u32_e32 v72, v27, v41
	s_waitcnt vmcnt(3)
	v_mul_f32_e32 v73, v68, v67
	s_waitcnt vmcnt(2)
	v_mul_f32_e32 v71, v70, v71
	s_waitcnt vmcnt(1)
	v_mul_f32_e32 v67, v69, v74
	ds_write2_b32 v72, v73, v71 offset1:66
	s_cbranch_execnz .LBB0_81

.LBB0_81:
	v_add_u32_e32 v68, v27, v42
	s_waitcnt vmcnt(0)
	v_mul_f32_e32 v29, v66, v29
	s_and_b64 vcc, exec, s[6:7]
	ds_write2_b32 v68, v67, v29 offset1:66
	s_cbranch_vccnz .LBB0_174
	v_mov_b32_e32 v29, v3
	v_lshl_add_u64 v[66:67], v[22:23], 0, v[28:29]
	global_load_dword v68, v[66:67], off offset:160 nt
	global_load_dword v69, v[66:67], off offset:168 nt
	global_load_dword v70, v[66:67], off offset:176 nt
	global_load_dword v29, v[66:67], off offset:184 nt
	v_add_u32_e32 v67, v27, v43
	s_waitcnt vmcnt(3)
	v_mul_f32_e32 v68, v59, v68
	s_waitcnt vmcnt(2)
	v_mul_f32_e32 v69, v61, v69
	s_waitcnt vmcnt(1)
	v_mul_f32_e32 v66, v60, v70
	ds_write2_b32 v67, v68, v69 offset1:66
	s_cbranch_execnz .LBB0_84

.LBB0_84:
	v_add_u32_e32 v59, v27, v44
	s_waitcnt vmcnt(0)
	v_mul_f32_e32 v29, v58, v29
	s_and_b64 vcc, exec, s[6:7]
	ds_write2_b32 v59, v66, v29 offset1:66
	s_cbranch_vccnz .LBB0_175
	v_mov_b32_e32 v29, v3
	v_lshl_add_u64 v[58:59], v[22:23], 0, v[28:29]
	global_load_dword v60, v[58:59], off offset:192 nt
	global_load_dword v61, v[58:59], off offset:200 nt
	global_load_dword v66, v[58:59], off offset:208 nt
	global_load_dword v29, v[58:59], off offset:216 nt
	v_add_u32_e32 v59, v27, v45
	s_waitcnt vmcnt(3)
	v_mul_f32_e32 v60, v63, v60
	s_waitcnt vmcnt(2)
	v_mul_f32_e32 v61, v65, v61
	s_waitcnt vmcnt(1)
	v_mul_f32_e32 v58, v64, v66
	ds_write2_b32 v59, v60, v61 offset1:66
	s_cbranch_execnz .LBB0_87

.LBB0_87:
	v_add_u32_e32 v59, v27, v45
	s_waitcnt vmcnt(0)
	v_mul_f32_e32 v29, v62, v29
	ds_write2_b32 v59, v58, v29 offset0:132 offset1:198
	s_and_b64 vcc, exec, s[6:7]
	v_add_u32_e32 v58, 0x400, v59
	s_cbranch_vccnz .LBB0_176
	v_mov_b32_e32 v29, v3
	v_lshl_add_u64 v[22:23], v[22:23], 0, v[28:29]
	global_load_dword v28, v[22:23], off offset:224 nt
	global_load_dword v29, v[22:23], off offset:232 nt
	global_load_dword v59, v[22:23], off offset:240 nt
	s_nop 0
	global_load_dword v22, v[22:23], off offset:248 nt
	s_waitcnt vmcnt(3)
	v_mul_f32_e32 v28, v30, v28
	s_waitcnt vmcnt(2)
	v_mul_f32_e32 v29, v57, v29
	s_waitcnt vmcnt(1)
	v_mul_f32_e32 v23, v31, v59
	ds_write2_b32 v58, v28, v29 offset0:8 offset1:74
	s_cbranch_execnz .LBB0_90

.LBB0_92:
	s_andn2_saveexec_b64 s[0:1], s[30:31]
	s_cbranch_execz .LBB0_94
	v_add_u32_e32 v2, 0xffffe980, v56
	v_lshrrev_b32_e32 v2, 11, v2
	v_lshlrev_b64 v[20:21], 24, v[2:3]
	v_lshlrev_b64 v[22:23], 23, v[2:3]
	v_add_u32_e32 v2, 0xffffd300, v54
	v_and_b32_e32 v74, 0x3e0, v51
	v_lshl_add_u64 v[20:21], s[62:63], 0, v[20:21]
	v_and_b32_e32 v57, 0xfc0, v2
	v_lshlrev_b32_e32 v2, 2, v74
	v_or_b32_e32 v28, v57, v0
	v_lshl_add_u64 v[20:21], v[20:21], 0, v[2:3]
	v_mov_b32_e32 v19, v3
	v_lshl_add_u64 v[20:21], v[20:21], 0, v[18:19]
	v_lshlrev_b32_e32 v2, 12, v28
	v_lshl_add_u64 v[20:21], v[20:21], 0, v[2:3]
	s_movk_i32 s6, 0x2000
	v_add_co_u32_e32 v28, vcc, s6, v20
	s_movk_i32 s6, 0x4000
	s_nop 0
	v_addc_co_u32_e32 v29, vcc, 0, v21, vcc
	v_add_co_u32_e32 v30, vcc, s6, v20
	s_movk_i32 s6, 0x6000
	s_nop 0
	v_addc_co_u32_e32 v31, vcc, 0, v21, vcc
	v_add_co_u32_e32 v58, vcc, s6, v20
	s_mov_b32 s6, 0x8000
	s_nop 0
	v_addc_co_u32_e32 v59, vcc, 0, v21, vcc
	v_add_co_u32_e32 v60, vcc, s6, v20
	s_mov_b32 s6, 0xa000
	s_nop 0
	v_addc_co_u32_e32 v61, vcc, 0, v21, vcc
	v_add_co_u32_e32 v62, vcc, s6, v20
	s_mov_b32 s6, 0xc000
	s_nop 0
	v_addc_co_u32_e32 v63, vcc, 0, v21, vcc
	v_add_co_u32_e32 v64, vcc, s6, v20
	s_mov_b32 s6, 0xe000
	s_nop 0
	v_addc_co_u32_e32 v65, vcc, 0, v21, vcc
	v_add_co_u32_e32 v66, vcc, s6, v20
	s_mov_b32 s6, 0x10000
	s_nop 0
	v_addc_co_u32_e32 v67, vcc, 0, v21, vcc
	global_load_dword v2, v[20:21], off nt
	global_load_dword v19, v[28:29], off nt
	global_load_dword v70, v[30:31], off nt
	global_load_dword v71, v[58:59], off nt
	global_load_dword v72, v[60:61], off nt
	global_load_dword v73, v[62:63], off nt
	global_load_dword v75, v[64:65], off nt
	global_load_dword v76, v[66:67], off nt
	v_add_co_u32_e32 v28, vcc, s6, v20
	s_mov_b32 s6, 0x12000
	s_nop 0
	v_addc_co_u32_e32 v29, vcc, 0, v21, vcc
	v_add_co_u32_e32 v30, vcc, s6, v20
	s_mov_b32 s6, 0x14000
	s_nop 0
	v_addc_co_u32_e32 v31, vcc, 0, v21, vcc
	v_add_co_u32_e32 v58, vcc, s6, v20
	s_mov_b32 s6, 0x16000
	s_nop 0
	v_addc_co_u32_e32 v59, vcc, 0, v21, vcc
	v_add_co_u32_e32 v60, vcc, s6, v20
	s_mov_b32 s6, 0x18000
	s_nop 0
	v_addc_co_u32_e32 v61, vcc, 0, v21, vcc
	v_add_co_u32_e32 v62, vcc, s6, v20
	s_mov_b32 s6, 0x1a000
	s_nop 0
	v_addc_co_u32_e32 v63, vcc, 0, v21, vcc
	v_add_co_u32_e32 v64, vcc, s6, v20
	s_mov_b32 s6, 0x1c000
	s_nop 0
	v_addc_co_u32_e32 v65, vcc, 0, v21, vcc
	v_add_co_u32_e32 v66, vcc, s6, v20
	s_mov_b32 s6, 0x1e000
	s_nop 0
	v_addc_co_u32_e32 v67, vcc, 0, v21, vcc
	v_add_co_u32_e32 v68, vcc, s6, v20
	s_mov_b32 s6, 0x20000
	s_nop 0
	v_addc_co_u32_e32 v69, vcc, 0, v21, vcc
	global_load_dword v77, v[28:29], off nt
	global_load_dword v78, v[30:31], off nt
	global_load_dword v79, v[58:59], off nt
	global_load_dword v80, v[60:61], off nt
	global_load_dword v81, v[62:63], off nt
	global_load_dword v82, v[64:65], off nt
	global_load_dword v83, v[66:67], off nt
	global_load_dword v84, v[68:69], off nt
	v_add_co_u32_e32 v28, vcc, s6, v20
	s_mov_b32 s6, 0x22000
	s_nop 0
	v_addc_co_u32_e32 v29, vcc, 0, v21, vcc
	v_add_co_u32_e32 v30, vcc, s6, v20
	s_mov_b32 s6, 0x24000
	s_nop 0
	v_addc_co_u32_e32 v31, vcc, 0, v21, vcc
	v_add_co_u32_e32 v58, vcc, s6, v20
	s_mov_b32 s6, 0x26000
	s_nop 0
	v_addc_co_u32_e32 v59, vcc, 0, v21, vcc
	v_add_co_u32_e32 v60, vcc, s6, v20
	s_mov_b32 s6, 0x28000
	s_nop 0
	v_addc_co_u32_e32 v61, vcc, 0, v21, vcc
	v_add_co_u32_e32 v62, vcc, s6, v20
	s_mov_b32 s6, 0x2a000
	s_nop 0
	v_addc_co_u32_e32 v63, vcc, 0, v21, vcc
	v_add_co_u32_e32 v64, vcc, s6, v20
	s_mov_b32 s6, 0x2c000
	s_nop 0
	v_addc_co_u32_e32 v65, vcc, 0, v21, vcc
	v_add_co_u32_e32 v66, vcc, s6, v20
	s_mov_b32 s6, 0x2e000
	s_nop 0
	v_addc_co_u32_e32 v67, vcc, 0, v21, vcc
	v_add_co_u32_e32 v68, vcc, s6, v20
	s_mov_b32 s6, 0x30000
	s_nop 0
	v_addc_co_u32_e32 v69, vcc, 0, v21, vcc
	global_load_dword v85, v[28:29], off nt
	global_load_dword v86, v[30:31], off nt
	global_load_dword v87, v[58:59], off nt
	global_load_dword v88, v[60:61], off nt
	global_load_dword v89, v[62:63], off nt
	global_load_dword v90, v[64:65], off nt
	global_load_dword v91, v[66:67], off nt
	s_nop 0
	global_load_dword v68, v[68:69], off nt
	v_add_co_u32_e32 v28, vcc, s6, v20
	s_mov_b32 s6, 0x32000
	s_nop 0
	v_addc_co_u32_e32 v29, vcc, 0, v21, vcc
	v_add_co_u32_e32 v30, vcc, s6, v20
	s_mov_b32 s6, 0x34000
	s_nop 0
	v_addc_co_u32_e32 v31, vcc, 0, v21, vcc
	v_add_co_u32_e32 v58, vcc, s6, v20
	s_mov_b32 s6, 0x36000
	s_nop 0
	v_addc_co_u32_e32 v59, vcc, 0, v21, vcc
	v_add_co_u32_e32 v60, vcc, s6, v20
	s_mov_b32 s6, 0x38000
	s_nop 0
	v_addc_co_u32_e32 v61, vcc, 0, v21, vcc
	v_add_co_u32_e32 v62, vcc, s6, v20
	s_mov_b32 s6, 0x3a000
	s_nop 0
	v_addc_co_u32_e32 v63, vcc, 0, v21, vcc
	v_add_co_u32_e32 v64, vcc, s6, v20
	s_mov_b32 s6, 0x3c000
	s_nop 0
	v_addc_co_u32_e32 v65, vcc, 0, v21, vcc
	v_add_co_u32_e32 v66, vcc, s6, v20
	s_mov_b32 s6, 0x3e000
	s_nop 0
	v_addc_co_u32_e32 v67, vcc, 0, v21, vcc
	v_add_co_u32_e32 v20, vcc, s6, v20
	s_nop 1
	v_addc_co_u32_e32 v21, vcc, 0, v21, vcc
	global_load_dword v28, v[28:29], off nt
	s_nop 0
	global_load_dword v29, v[30:31], off nt
	s_nop 0
	global_load_dword v30, v[58:59], off nt
	global_load_dword v31, v[60:61], off nt
	s_nop 0
	global_load_dword v58, v[62:63], off nt
	global_load_dword v59, v[64:65], off nt
	global_load_dword v60, v[66:67], off nt
	global_load_dword v61, v[20:21], off nt
	s_waitcnt vmcnt(30)
	ds_write2_b32 v32, v2, v19 offset1:66
	s_waitcnt vmcnt(28)
	ds_write2_b32 v32, v70, v71 offset0:132 offset1:198
	v_add_u32_e32 v2, 0x400, v32
	s_waitcnt vmcnt(26)
	ds_write2_b32 v2, v72, v73 offset0:8 offset1:74
	s_waitcnt vmcnt(24)
	ds_write2_b32 v2, v75, v76 offset0:140 offset1:206
	v_add_u32_e32 v2, 0x800, v32
	s_waitcnt vmcnt(22)
	ds_write2_b32 v2, v77, v78 offset0:16 offset1:82
	s_waitcnt vmcnt(20)
	ds_write2_b32 v2, v79, v80 offset0:148 offset1:214
	v_add_u32_e32 v2, 0xc00, v32
	s_waitcnt vmcnt(18)
	ds_write2_b32 v2, v81, v82 offset0:24 offset1:90
	s_waitcnt vmcnt(16)
	ds_write2_b32 v2, v83, v84 offset0:156 offset1:222
	v_add_u32_e32 v2, 0x1000, v32
	s_waitcnt vmcnt(14)
	ds_write2_b32 v2, v85, v86 offset0:32 offset1:98
	s_waitcnt vmcnt(12)
	ds_write2_b32 v2, v87, v88 offset0:164 offset1:230
	v_add_u32_e32 v2, 0x1400, v32
	s_waitcnt vmcnt(10)
	ds_write2_b32 v2, v89, v90 offset0:40 offset1:106
	s_waitcnt vmcnt(8)
	ds_write2_b32 v2, v91, v68 offset0:172 offset1:238
	v_add_u32_e32 v2, 0x1800, v32
	s_waitcnt vmcnt(6)
	ds_write2_b32 v2, v28, v29 offset0:48 offset1:114
	s_waitcnt vmcnt(4)
	ds_write2_b32 v2, v30, v31 offset0:180 offset1:246
	v_add_u32_e32 v2, 0x1c00, v32
	s_waitcnt vmcnt(2)
	ds_write2_b32 v2, v58, v59 offset0:56 offset1:122
	s_waitcnt vmcnt(0)
	ds_write2_b32 v2, v60, v61 offset0:188 offset1:254
	v_lshl_add_u64 v[20:21], s[82:83], 0, v[22:23]
	s_waitcnt lgkmcnt(0)
	v_lshlrev_b32_e32 v2, 1, v57
	v_lshl_add_u64 v[20:21], v[20:21], 0, v[2:3]
	v_lshlrev_b32_e32 v2, 1, v4
	ds_read2_b32 v[30:31], v47 offset0:33 offset1:41
	ds_read2_b32 v[58:59], v47 offset1:8
	ds_read2_b32 v[60:61], v47 offset0:66 offset1:74
	ds_read2_b32 v[62:63], v47 offset0:99 offset1:107
	ds_read2_b32 v[64:65], v47 offset0:132 offset1:140
	ds_read2_b32 v[66:67], v47 offset0:165 offset1:173
	ds_read2_b32 v[68:69], v47 offset0:198 offset1:206
	ds_read2_b32 v[70:71], v47 offset0:231 offset1:239
	v_lshl_add_u64 v[28:29], v[20:21], 0, v[2:3]
	v_or_b32_e32 v2, v74, v46
	v_lshlrev_b32_e32 v2, 13, v2
	v_lshl_add_u64 v[72:73], v[28:29], 0, v[2:3]
	v_or_b32_e32 v2, v74, v48
	s_waitcnt lgkmcnt(6)
	v_cvt_pk_bf16_f32 v20, v58, v30
	v_lshlrev_b32_e32 v2, 13, v2
	s_waitcnt lgkmcnt(4)
	v_cvt_pk_bf16_f32 v21, v60, v62
	s_waitcnt lgkmcnt(2)
	v_cvt_pk_bf16_f32 v22, v64, v66
	s_waitcnt lgkmcnt(0)
	v_cvt_pk_bf16_f32 v23, v68, v70
	global_store_dwordx4 v[72:73], v[20:23], off
	s_nop 1
	v_cvt_pk_bf16_f32 v20, v59, v31
	v_lshl_add_u64 v[30:31], v[28:29], 0, v[2:3]
	v_cvt_pk_bf16_f32 v21, v61, v63
	v_cvt_pk_bf16_f32 v22, v65, v67
	v_cvt_pk_bf16_f32 v23, v69, v71
	global_store_dwordx4 v[30:31], v[20:23], off
	ds_read2_b32 v[30:31], v47 offset0:16 offset1:24
	ds_read2_b32 v[58:59], v47 offset0:49 offset1:57
	ds_read2_b32 v[60:61], v47 offset0:82 offset1:90
	ds_read2_b32 v[62:63], v47 offset0:115 offset1:123
	ds_read2_b32 v[64:65], v47 offset0:148 offset1:156
	ds_read2_b32 v[66:67], v47 offset0:181 offset1:189
	ds_read2_b32 v[68:69], v47 offset0:214 offset1:222
	ds_read2_b32 v[70:71], v47 offset0:247 offset1:255
	v_or_b32_e32 v2, v74, v49
	v_lshlrev_b32_e32 v2, 13, v2
	v_lshl_add_u64 v[72:73], v[28:29], 0, v[2:3]
	v_or_b32_e32 v2, v74, v50
	v_lshlrev_b32_e32 v2, 13, v2
	s_waitcnt lgkmcnt(6)
	v_cvt_pk_bf16_f32 v20, v30, v58
	s_waitcnt lgkmcnt(4)
	v_cvt_pk_bf16_f32 v21, v60, v62
	s_waitcnt lgkmcnt(2)
	v_cvt_pk_bf16_f32 v22, v64, v66
	s_waitcnt lgkmcnt(0)
	v_cvt_pk_bf16_f32 v23, v68, v70
	v_lshl_add_u64 v[28:29], v[28:29], 0, v[2:3]
	global_store_dwordx4 v[72:73], v[20:23], off
	s_nop 1
	v_cvt_pk_bf16_f32 v20, v31, v59
	v_cvt_pk_bf16_f32 v21, v61, v63
	v_cvt_pk_bf16_f32 v22, v65, v67
	v_cvt_pk_bf16_f32 v23, v69, v71
	global_store_dwordx4 v[28:29], v[20:23], off
	s_waitcnt lgkmcnt(0)

.LBB0_95:
	s_andn2_saveexec_b64 s[0:1], s[24:25]
	s_cbranch_execz .LBB0_121
	v_add_u32_e32 v19, 0xfffff980, v56
	v_lshrrev_b32_e32 v2, 11, v19
	v_lshlrev_b64 v[20:21], 24, v[2:3]
	v_lshl_add_u64 v[22:23], s[60:61], 0, v[20:21]
	v_lshrrev_b32_e32 v19, 1, v19
	v_and_b32_e32 v21, 0xfe0, v51
	v_and_b32_e32 v20, 0x3c0, v19
	v_lshlrev_b32_e32 v30, 2, v21
	v_mov_b32_e32 v31, v3
	v_or_b32_e32 v29, v20, v0
	v_lshl_add_u64 v[22:23], v[22:23], 0, v[30:31]
	v_mov_b32_e32 v19, v3
	v_lshl_add_u64 v[22:23], v[22:23], 0, v[18:19]
	v_lshlrev_b32_e32 v30, 14, v29
	v_lshl_add_u64 v[22:23], v[22:23], 0, v[30:31]
	s_mov_b32 s6, 0x8000
	v_add_co_u32_e32 v30, vcc, s6, v22
	s_mov_b32 s6, 0x10000
	s_nop 0
	v_addc_co_u32_e32 v31, vcc, 0, v23, vcc
	v_add_co_u32_e32 v58, vcc, s6, v22
	s_mov_b32 s6, 0x18000
	s_nop 0
	v_addc_co_u32_e32 v59, vcc, 0, v23, vcc
	v_add_co_u32_e32 v60, vcc, s6, v22
	s_mov_b32 s6, 0x20000
	s_nop 0
	v_addc_co_u32_e32 v61, vcc, 0, v23, vcc
	v_add_co_u32_e32 v62, vcc, s6, v22
	s_mov_b32 s6, 0x28000
	s_nop 0
	v_addc_co_u32_e32 v63, vcc, 0, v23, vcc
	v_add_co_u32_e32 v64, vcc, s6, v22
	s_mov_b32 s6, 0x30000
	s_nop 0
	v_addc_co_u32_e32 v65, vcc, 0, v23, vcc
	v_add_co_u32_e32 v66, vcc, s6, v22
	s_mov_b32 s6, 0x38000
	s_nop 0
	v_addc_co_u32_e32 v67, vcc, 0, v23, vcc
	v_add_co_u32_e32 v68, vcc, s6, v22
	s_mov_b32 s6, 0x40000
	s_nop 0
	v_addc_co_u32_e32 v69, vcc, 0, v23, vcc
	global_load_dword v85, v[22:23], off nt
	global_load_dword v84, v[30:31], off nt
	global_load_dword v83, v[58:59], off nt
	global_load_dword v82, v[60:61], off nt
	global_load_dword v79, v[62:63], off nt
	global_load_dword v81, v[64:65], off nt
	global_load_dword v80, v[66:67], off nt
	global_load_dword v75, v[68:69], off nt
	v_add_co_u32_e32 v30, vcc, s6, v22
	s_mov_b32 s6, 0x48000
	s_nop 0
	v_addc_co_u32_e32 v31, vcc, 0, v23, vcc
	v_add_co_u32_e32 v58, vcc, s6, v22
	s_mov_b32 s6, 0x50000
	s_nop 0
	v_addc_co_u32_e32 v59, vcc, 0, v23, vcc
	v_add_co_u32_e32 v60, vcc, s6, v22
	s_mov_b32 s6, 0x58000
	s_nop 0
	v_addc_co_u32_e32 v61, vcc, 0, v23, vcc
	v_add_co_u32_e32 v62, vcc, s6, v22
	s_mov_b32 s6, 0x60000
	s_nop 0
	v_addc_co_u32_e32 v63, vcc, 0, v23, vcc
	v_add_co_u32_e32 v64, vcc, s6, v22
	s_mov_b32 s6, 0x68000
	s_nop 0
	v_addc_co_u32_e32 v65, vcc, 0, v23, vcc
	v_add_co_u32_e32 v66, vcc, s6, v22
	s_mov_b32 s6, 0x70000
	s_nop 0
	v_addc_co_u32_e32 v67, vcc, 0, v23, vcc
	v_add_co_u32_e32 v68, vcc, s6, v22
	s_mov_b32 s6, 0x78000
	s_nop 0
	v_addc_co_u32_e32 v69, vcc, 0, v23, vcc
	v_add_co_u32_e32 v86, vcc, s6, v22
	s_mov_b32 s6, 0x80000
	s_nop 0
	v_addc_co_u32_e32 v87, vcc, 0, v23, vcc
	global_load_dword v76, v[30:31], off nt
	global_load_dword v78, v[58:59], off nt
	global_load_dword v77, v[60:61], off nt
	global_load_dword v74, v[62:63], off nt
	global_load_dword v71, v[64:65], off nt
	global_load_dword v73, v[66:67], off nt
	global_load_dword v72, v[68:69], off nt
	s_nop 0
	global_load_dword v67, v[86:87], off nt
	v_add_co_u32_e32 v30, vcc, s6, v22
	s_mov_b32 s6, 0x88000
	s_nop 0
	v_addc_co_u32_e32 v31, vcc, 0, v23, vcc
	v_add_co_u32_e32 v58, vcc, s6, v22
	s_mov_b32 s6, 0x90000
	s_nop 0
	v_addc_co_u32_e32 v59, vcc, 0, v23, vcc
	v_add_co_u32_e32 v60, vcc, s6, v22
	s_mov_b32 s6, 0x98000
	s_nop 0
	v_addc_co_u32_e32 v61, vcc, 0, v23, vcc
	v_add_co_u32_e32 v62, vcc, s6, v22
	s_mov_b32 s6, 0xa0000
	s_nop 0
	v_addc_co_u32_e32 v63, vcc, 0, v23, vcc
	v_add_co_u32_e32 v64, vcc, s6, v22
	s_mov_b32 s6, 0xa8000
	s_nop 0
	v_addc_co_u32_e32 v65, vcc, 0, v23, vcc
	v_add_co_u32_e32 v86, vcc, s6, v22
	s_mov_b32 s6, 0xb0000
	s_nop 0
	v_addc_co_u32_e32 v87, vcc, 0, v23, vcc
	v_add_co_u32_e32 v88, vcc, s6, v22
	s_mov_b32 s6, 0xb8000
	s_nop 0
	v_addc_co_u32_e32 v89, vcc, 0, v23, vcc
	v_add_co_u32_e32 v90, vcc, s6, v22
	s_mov_b32 s6, 0xc0000
	s_nop 0
	v_addc_co_u32_e32 v91, vcc, 0, v23, vcc
	global_load_dword v68, v[30:31], off nt
	global_load_dword v70, v[58:59], off nt
	global_load_dword v69, v[60:61], off nt
	global_load_dword v66, v[62:63], off nt
	s_nop 0
	global_load_dword v59, v[64:65], off nt
	global_load_dword v61, v[86:87], off nt
	global_load_dword v60, v[88:89], off nt
	global_load_dword v58, v[90:91], off nt
	v_add_co_u32_e32 v30, vcc, s6, v22
	s_mov_b32 s6, 0xc8000
	s_nop 0
	v_addc_co_u32_e32 v31, vcc, 0, v23, vcc
	v_add_co_u32_e32 v64, vcc, s6, v22
	s_mov_b32 s6, 0xd0000
	s_nop 0
	v_addc_co_u32_e32 v65, vcc, 0, v23, vcc
	v_add_co_u32_e32 v86, vcc, s6, v22
	s_mov_b32 s6, 0xd8000
	s_nop 0
	v_addc_co_u32_e32 v87, vcc, 0, v23, vcc
	v_add_co_u32_e32 v88, vcc, s6, v22
	s_mov_b32 s6, 0xe0000
	s_nop 0
	v_addc_co_u32_e32 v89, vcc, 0, v23, vcc
	v_add_co_u32_e32 v90, vcc, s6, v22
	v_cndmask_b32_e64 v28, 0, 1, s[86:87]
	s_nop 0
	v_addc_co_u32_e32 v91, vcc, 0, v23, vcc
	v_add_co_u32_e32 v92, vcc, 0xe8000, v22
	v_cmp_ne_u32_e64 s[6:7], 1, v28
	s_nop 0
	v_addc_co_u32_e32 v93, vcc, 0, v23, vcc
	v_add_co_u32_e32 v94, vcc, 0xf0000, v22
	v_add_lshl_u32 v28, v20, v0, 2
	s_nop 0
	v_addc_co_u32_e32 v95, vcc, 0, v23, vcc
	v_add_co_u32_e32 v22, vcc, 0xf8000, v22
	s_nop 1
	v_addc_co_u32_e32 v23, vcc, 0, v23, vcc
	global_load_dword v63, v[30:31], off nt
	s_nop 0
	global_load_dword v65, v[64:65], off nt
	s_nop 0
	global_load_dword v64, v[86:87], off nt
	global_load_dword v62, v[88:89], off nt
	global_load_dword v30, v[90:91], off nt
	global_load_dword v57, v[92:93], off nt
	global_load_dword v31, v[94:95], off nt
	global_load_dword v19, v[22:23], off nt
	v_lshlrev_b32_e32 v22, 10, v2
	v_mov_b32_e32 v23, v3
	v_lshl_add_u64 v[22:23], v[22:23], 2, s[58:59]
	s_andn2_b64 vcc, exec, s[86:87]
	s_cbranch_vccnz .LBB0_161
	v_lshlrev_b32_e32 v86, 2, v29
	v_mov_b32_e32 v87, v3
	v_lshl_add_u64 v[86:87], v[22:23], 0, v[86:87]
	v_mov_b32_e32 v29, v3
	v_lshl_add_u64 v[88:89], v[22:23], 0, v[28:29]
	global_load_dword v86, v[86:87], off nt
	s_nop 0
	global_load_dword v87, v[88:89], off offset:8 nt
	global_load_dword v90, v[88:89], off offset:16 nt
	global_load_dword v29, v[88:89], off offset:24 nt
	v_add_u32_e32 v88, v27, v33
	s_waitcnt vmcnt(3)
	v_mul_f32_e32 v89, v85, v86
	s_waitcnt vmcnt(2)
	v_mul_f32_e32 v87, v84, v87
	s_waitcnt vmcnt(1)
	v_mul_f32_e32 v86, v83, v90
	ds_write_b32 v32, v89
	ds_write_b32 v88, v87
	s_cbranch_execnz .LBB0_99

.LBB0_122:
	s_andn2_saveexec_b64 s[0:1], s[96:97]
	s_cbranch_execz .LBB0_124
	v_add_u32_e32 v2, 0x1f700, v54
	v_and_b32_e32 v19, 0x1ffc0, v2
	v_and_b32_e32 v57, 0x3e0, v51
	v_or_b32_e32 v22, v19, v0
	v_lshlrev_b32_e32 v2, 2, v57
	v_lshl_add_u64 v[20:21], v[12:13], 0, v[2:3]
	v_lshlrev_b32_e32 v2, 12, v22
	v_lshl_add_u64 v[20:21], v[20:21], 0, v[2:3]
	v_add_co_u32_e32 v22, vcc, 0x2000, v20
	s_nop 1
	v_addc_co_u32_e32 v23, vcc, 0, v21, vcc
	v_add_co_u32_e32 v28, vcc, 0x4000, v20
	s_nop 1
	v_addc_co_u32_e32 v29, vcc, 0, v21, vcc
	v_add_co_u32_e32 v30, vcc, 0x6000, v20
	s_nop 1
	v_addc_co_u32_e32 v31, vcc, 0, v21, vcc
	v_add_co_u32_e32 v58, vcc, 0x8000, v20
	s_nop 1
	v_addc_co_u32_e32 v59, vcc, 0, v21, vcc
	v_add_co_u32_e32 v60, vcc, 0xa000, v20
	s_nop 1
	v_addc_co_u32_e32 v61, vcc, 0, v21, vcc
	v_add_co_u32_e32 v62, vcc, 0xc000, v20
	s_nop 1
	v_addc_co_u32_e32 v63, vcc, 0, v21, vcc
	v_add_co_u32_e32 v64, vcc, 0xe000, v20
	s_nop 1
	v_addc_co_u32_e32 v65, vcc, 0, v21, vcc
	global_load_dword v2, v[20:21], off nt
	global_load_dword v68, v[22:23], off nt
	global_load_dword v69, v[28:29], off nt
	global_load_dword v70, v[30:31], off nt
	global_load_dword v71, v[58:59], off nt
	global_load_dword v72, v[60:61], off nt
	global_load_dword v73, v[62:63], off nt
	global_load_dword v74, v[64:65], off nt
	v_add_co_u32_e32 v22, vcc, 0x10000, v20
	s_nop 1
	v_addc_co_u32_e32 v23, vcc, 0, v21, vcc
	v_add_co_u32_e32 v28, vcc, 0x12000, v20
	s_nop 1
	v_addc_co_u32_e32 v29, vcc, 0, v21, vcc
	v_add_co_u32_e32 v30, vcc, 0x14000, v20
	s_nop 1
	v_addc_co_u32_e32 v31, vcc, 0, v21, vcc
	v_add_co_u32_e32 v58, vcc, 0x16000, v20
	s_nop 1
	v_addc_co_u32_e32 v59, vcc, 0, v21, vcc
	v_add_co_u32_e32 v60, vcc, 0x18000, v20
	s_nop 1
	v_addc_co_u32_e32 v61, vcc, 0, v21, vcc
	v_add_co_u32_e32 v62, vcc, 0x1a000, v20
	s_nop 1
	v_addc_co_u32_e32 v63, vcc, 0, v21, vcc
	v_add_co_u32_e32 v64, vcc, 0x1c000, v20
	s_nop 1
	v_addc_co_u32_e32 v65, vcc, 0, v21, vcc
	v_add_co_u32_e32 v66, vcc, 0x1e000, v20
	s_nop 1
	v_addc_co_u32_e32 v67, vcc, 0, v21, vcc
	global_load_dword v75, v[22:23], off nt
	global_load_dword v76, v[28:29], off nt
	global_load_dword v77, v[30:31], off nt
	global_load_dword v78, v[58:59], off nt
	global_load_dword v79, v[60:61], off nt
	global_load_dword v80, v[62:63], off nt
	global_load_dword v81, v[64:65], off nt
	global_load_dword v82, v[66:67], off nt
	v_add_co_u32_e32 v22, vcc, 0x20000, v20
	s_nop 1
	v_addc_co_u32_e32 v23, vcc, 0, v21, vcc
	v_add_co_u32_e32 v28, vcc, 0x22000, v20
	s_nop 1
	v_addc_co_u32_e32 v29, vcc, 0, v21, vcc
	v_add_co_u32_e32 v30, vcc, 0x24000, v20
	s_nop 1
	v_addc_co_u32_e32 v31, vcc, 0, v21, vcc
	v_add_co_u32_e32 v58, vcc, 0x26000, v20
	s_nop 1
	v_addc_co_u32_e32 v59, vcc, 0, v21, vcc
	v_add_co_u32_e32 v60, vcc, 0x28000, v20
	s_nop 1
	v_addc_co_u32_e32 v61, vcc, 0, v21, vcc
	v_add_co_u32_e32 v62, vcc, 0x2a000, v20
	s_nop 1
	v_addc_co_u32_e32 v63, vcc, 0, v21, vcc
	v_add_co_u32_e32 v64, vcc, 0x2c000, v20
	s_nop 1
	v_addc_co_u32_e32 v65, vcc, 0, v21, vcc
	v_add_co_u32_e32 v66, vcc, 0x2e000, v20
	s_nop 1
	v_addc_co_u32_e32 v67, vcc, 0, v21, vcc
	global_load_dword v83, v[22:23], off nt
	global_load_dword v84, v[28:29], off nt
	global_load_dword v85, v[30:31], off nt
	global_load_dword v86, v[58:59], off nt
	global_load_dword v87, v[60:61], off nt
	global_load_dword v88, v[62:63], off nt
	global_load_dword v89, v[64:65], off nt
	s_nop 0
	global_load_dword v66, v[66:67], off nt
	v_add_co_u32_e32 v22, vcc, 0x30000, v20
	s_nop 1
	v_addc_co_u32_e32 v23, vcc, 0, v21, vcc
	v_add_co_u32_e32 v28, vcc, 0x32000, v20
	s_nop 1
	v_addc_co_u32_e32 v29, vcc, 0, v21, vcc
	v_add_co_u32_e32 v30, vcc, 0x34000, v20
	s_nop 1
	v_addc_co_u32_e32 v31, vcc, 0, v21, vcc
	v_add_co_u32_e32 v58, vcc, 0x36000, v20
	s_nop 1
	v_addc_co_u32_e32 v59, vcc, 0, v21, vcc
	v_add_co_u32_e32 v60, vcc, 0x38000, v20
	s_nop 1
	v_addc_co_u32_e32 v61, vcc, 0, v21, vcc
	v_add_co_u32_e32 v62, vcc, 0x3a000, v20
	s_nop 1
	v_addc_co_u32_e32 v63, vcc, 0, v21, vcc
	v_add_co_u32_e32 v64, vcc, 0x3c000, v20
	s_nop 1
	v_addc_co_u32_e32 v65, vcc, 0, v21, vcc
	v_add_co_u32_e32 v20, vcc, 0x3e000, v20
	s_nop 1
	v_addc_co_u32_e32 v21, vcc, 0, v21, vcc
	global_load_dword v22, v[22:23], off nt
	s_nop 0
	global_load_dword v23, v[28:29], off nt
	s_nop 0
	global_load_dword v28, v[30:31], off nt
	global_load_dword v29, v[58:59], off nt
	s_nop 0
	global_load_dword v30, v[60:61], off nt
	global_load_dword v31, v[62:63], off nt
	global_load_dword v58, v[64:65], off nt
	s_nop 0
	global_load_dword v20, v[20:21], off nt
	s_waitcnt vmcnt(30)
	ds_write2_b32 v32, v2, v68 offset1:66
	s_waitcnt vmcnt(28)
	ds_write2_b32 v32, v69, v70 offset0:132 offset1:198
	v_add_u32_e32 v2, 0x400, v32
	s_waitcnt vmcnt(26)
	ds_write2_b32 v2, v71, v72 offset0:8 offset1:74
	s_waitcnt vmcnt(24)
	ds_write2_b32 v2, v73, v74 offset0:140 offset1:206
	v_add_u32_e32 v2, 0x800, v32
	s_waitcnt vmcnt(22)
	ds_write2_b32 v2, v75, v76 offset0:16 offset1:82
	s_waitcnt vmcnt(20)
	ds_write2_b32 v2, v77, v78 offset0:148 offset1:214
	v_add_u32_e32 v2, 0xc00, v32
	s_waitcnt vmcnt(18)
	ds_write2_b32 v2, v79, v80 offset0:24 offset1:90
	s_waitcnt vmcnt(16)
	ds_write2_b32 v2, v81, v82 offset0:156 offset1:222
	v_add_u32_e32 v2, 0x1000, v32
	s_waitcnt vmcnt(14)
	ds_write2_b32 v2, v83, v84 offset0:32 offset1:98
	s_waitcnt vmcnt(12)
	ds_write2_b32 v2, v85, v86 offset0:164 offset1:230
	v_add_u32_e32 v2, 0x1400, v32
	s_waitcnt vmcnt(10)
	ds_write2_b32 v2, v87, v88 offset0:40 offset1:106
	s_waitcnt vmcnt(8)
	ds_write2_b32 v2, v89, v66 offset0:172 offset1:238
	v_add_u32_e32 v2, 0x1800, v32
	s_waitcnt vmcnt(6)
	ds_write2_b32 v2, v22, v23 offset0:48 offset1:114
	s_waitcnt vmcnt(4)
	ds_write2_b32 v2, v28, v29 offset0:180 offset1:246
	v_add_u32_e32 v2, 0x1c00, v32
	s_waitcnt vmcnt(2)
	ds_write2_b32 v2, v30, v31 offset0:56 offset1:122
	s_waitcnt vmcnt(0)
	ds_write2_b32 v2, v58, v20 offset0:188 offset1:254
	s_waitcnt lgkmcnt(0)
	v_lshlrev_b32_e32 v2, 1, v19
	ds_read2_b32 v[30:31], v47 offset0:33 offset1:41
	ds_read2_b32 v[58:59], v47 offset1:8
	ds_read2_b32 v[60:61], v47 offset0:66 offset1:74
	ds_read2_b32 v[62:63], v47 offset0:99 offset1:107
	ds_read2_b32 v[64:65], v47 offset0:132 offset1:140
	ds_read2_b32 v[66:67], v47 offset0:165 offset1:173
	ds_read2_b32 v[68:69], v47 offset0:198 offset1:206
	ds_read2_b32 v[70:71], v47 offset0:231 offset1:239
	v_lshl_add_u64 v[28:29], v[8:9], 0, v[2:3]
	v_or_b32_e32 v2, v57, v46
	v_lshlrev_b32_e32 v2, 11, v2
	v_lshl_add_u64 v[72:73], v[28:29], 0, v[2:3]
	v_or_b32_e32 v2, v57, v48
	s_waitcnt lgkmcnt(6)
	v_cvt_pk_bf16_f32 v20, v58, v30
	v_lshlrev_b32_e32 v2, 11, v2
	s_waitcnt lgkmcnt(4)
	v_cvt_pk_bf16_f32 v21, v60, v62
	s_waitcnt lgkmcnt(2)
	v_cvt_pk_bf16_f32 v22, v64, v66
	s_waitcnt lgkmcnt(0)
	v_cvt_pk_bf16_f32 v23, v68, v70
	global_store_dwordx4 v[72:73], v[20:23], off
	s_nop 1
	v_cvt_pk_bf16_f32 v20, v59, v31
	v_lshl_add_u64 v[30:31], v[28:29], 0, v[2:3]
	v_cvt_pk_bf16_f32 v21, v61, v63
	v_cvt_pk_bf16_f32 v22, v65, v67
	v_cvt_pk_bf16_f32 v23, v69, v71
	global_store_dwordx4 v[30:31], v[20:23], off
	ds_read2_b32 v[30:31], v47 offset0:16 offset1:24
	ds_read2_b32 v[58:59], v47 offset0:49 offset1:57
	ds_read2_b32 v[60:61], v47 offset0:82 offset1:90
	ds_read2_b32 v[62:63], v47 offset0:115 offset1:123
	ds_read2_b32 v[64:65], v47 offset0:148 offset1:156
	ds_read2_b32 v[66:67], v47 offset0:181 offset1:189
	ds_read2_b32 v[68:69], v47 offset0:214 offset1:222
	ds_read2_b32 v[70:71], v47 offset0:247 offset1:255
	v_or_b32_e32 v2, v57, v49
	v_lshlrev_b32_e32 v2, 11, v2
	v_lshl_add_u64 v[72:73], v[28:29], 0, v[2:3]
	v_or_b32_e32 v2, v57, v50
	v_lshlrev_b32_e32 v2, 11, v2
	s_waitcnt lgkmcnt(6)
	v_cvt_pk_bf16_f32 v20, v30, v58
	s_waitcnt lgkmcnt(4)
	v_cvt_pk_bf16_f32 v21, v60, v62
	s_waitcnt lgkmcnt(2)
	v_cvt_pk_bf16_f32 v22, v64, v66
	s_waitcnt lgkmcnt(0)
	v_cvt_pk_bf16_f32 v23, v68, v70
	v_lshl_add_u64 v[28:29], v[28:29], 0, v[2:3]
	global_store_dwordx4 v[72:73], v[20:23], off
	s_nop 1
	v_cvt_pk_bf16_f32 v20, v31, v59
	v_cvt_pk_bf16_f32 v21, v61, v63
	v_cvt_pk_bf16_f32 v22, v65, v67
	v_cvt_pk_bf16_f32 v23, v69, v71
	global_store_dwordx4 v[28:29], v[20:23], off
	s_waitcnt lgkmcnt(0)

.LBB0_125:
	s_andn2_saveexec_b64 s[0:1], s[94:95]
	s_cbranch_execz .LBB0_127
	v_and_b32_e32 v19, 0x3c0, v55
	v_and_b32_e32 v57, 0x1e0, v51
	v_or_b32_e32 v22, v19, v0
	v_lshlrev_b32_e32 v2, 2, v57
	v_lshl_add_u64 v[20:21], v[14:15], 0, v[2:3]
	v_lshlrev_b32_e32 v2, 11, v22
	v_lshl_add_u64 v[20:21], v[20:21], 0, v[2:3]
	v_add_co_u32_e32 v22, vcc, 0x1000, v20
	s_nop 1
	v_addc_co_u32_e32 v23, vcc, 0, v21, vcc
	v_add_co_u32_e32 v28, vcc, 0x2000, v20
	s_nop 1
	v_addc_co_u32_e32 v29, vcc, 0, v21, vcc
	v_add_co_u32_e32 v30, vcc, 0x3000, v20
	s_nop 1
	v_addc_co_u32_e32 v31, vcc, 0, v21, vcc
	v_add_co_u32_e32 v58, vcc, 0x4000, v20
	s_nop 1
	v_addc_co_u32_e32 v59, vcc, 0, v21, vcc
	v_add_co_u32_e32 v60, vcc, 0x5000, v20
	s_nop 1
	v_addc_co_u32_e32 v61, vcc, 0, v21, vcc
	v_add_co_u32_e32 v62, vcc, 0x6000, v20
	s_nop 1
	v_addc_co_u32_e32 v63, vcc, 0, v21, vcc
	v_add_co_u32_e32 v64, vcc, 0x7000, v20
	s_nop 1
	v_addc_co_u32_e32 v65, vcc, 0, v21, vcc
	global_load_dword v2, v[20:21], off nt
	global_load_dword v68, v[22:23], off nt
	global_load_dword v69, v[28:29], off nt
	global_load_dword v70, v[30:31], off nt
	global_load_dword v71, v[58:59], off nt
	global_load_dword v72, v[60:61], off nt
	global_load_dword v73, v[62:63], off nt
	global_load_dword v74, v[64:65], off nt
	v_add_co_u32_e32 v22, vcc, 0x8000, v20
	s_nop 1
	v_addc_co_u32_e32 v23, vcc, 0, v21, vcc
	v_add_co_u32_e32 v28, vcc, 0x9000, v20
	s_nop 1
	v_addc_co_u32_e32 v29, vcc, 0, v21, vcc
	v_add_co_u32_e32 v30, vcc, 0xa000, v20
	s_nop 1
	v_addc_co_u32_e32 v31, vcc, 0, v21, vcc
	v_add_co_u32_e32 v58, vcc, 0xb000, v20
	s_nop 1
	v_addc_co_u32_e32 v59, vcc, 0, v21, vcc
	v_add_co_u32_e32 v60, vcc, 0xc000, v20
	s_nop 1
	v_addc_co_u32_e32 v61, vcc, 0, v21, vcc
	v_add_co_u32_e32 v62, vcc, 0xd000, v20
	s_nop 1
	v_addc_co_u32_e32 v63, vcc, 0, v21, vcc
	v_add_co_u32_e32 v64, vcc, 0xe000, v20
	s_nop 1
	v_addc_co_u32_e32 v65, vcc, 0, v21, vcc
	v_add_co_u32_e32 v66, vcc, 0xf000, v20
	s_nop 1
	v_addc_co_u32_e32 v67, vcc, 0, v21, vcc
	global_load_dword v75, v[22:23], off nt
	global_load_dword v76, v[28:29], off nt
	global_load_dword v77, v[30:31], off nt
	global_load_dword v78, v[58:59], off nt
	global_load_dword v79, v[60:61], off nt
	global_load_dword v80, v[62:63], off nt
	global_load_dword v81, v[64:65], off nt
	global_load_dword v82, v[66:67], off nt
	v_add_co_u32_e32 v22, vcc, 0x10000, v20
	s_nop 1
	v_addc_co_u32_e32 v23, vcc, 0, v21, vcc
	v_add_co_u32_e32 v28, vcc, 0x11000, v20
	s_nop 1
	v_addc_co_u32_e32 v29, vcc, 0, v21, vcc
	v_add_co_u32_e32 v30, vcc, 0x12000, v20
	s_nop 1
	v_addc_co_u32_e32 v31, vcc, 0, v21, vcc
	v_add_co_u32_e32 v58, vcc, 0x13000, v20
	s_nop 1
	v_addc_co_u32_e32 v59, vcc, 0, v21, vcc
	v_add_co_u32_e32 v60, vcc, 0x14000, v20
	s_nop 1
	v_addc_co_u32_e32 v61, vcc, 0, v21, vcc
	v_add_co_u32_e32 v62, vcc, 0x15000, v20
	s_nop 1
	v_addc_co_u32_e32 v63, vcc, 0, v21, vcc
	v_add_co_u32_e32 v64, vcc, 0x16000, v20
	s_nop 1
	v_addc_co_u32_e32 v65, vcc, 0, v21, vcc
	v_add_co_u32_e32 v66, vcc, 0x17000, v20
	s_nop 1
	v_addc_co_u32_e32 v67, vcc, 0, v21, vcc
	global_load_dword v83, v[22:23], off nt
	global_load_dword v84, v[28:29], off nt
	global_load_dword v85, v[30:31], off nt
	global_load_dword v86, v[58:59], off nt
	global_load_dword v87, v[60:61], off nt
	global_load_dword v88, v[62:63], off nt
	global_load_dword v89, v[64:65], off nt
	s_nop 0
	global_load_dword v66, v[66:67], off nt
	v_add_co_u32_e32 v22, vcc, 0x18000, v20
	s_nop 1
	v_addc_co_u32_e32 v23, vcc, 0, v21, vcc
	v_add_co_u32_e32 v28, vcc, 0x19000, v20
	s_nop 1
	v_addc_co_u32_e32 v29, vcc, 0, v21, vcc
	v_add_co_u32_e32 v30, vcc, 0x1a000, v20
	s_nop 1
	v_addc_co_u32_e32 v31, vcc, 0, v21, vcc
	v_add_co_u32_e32 v58, vcc, 0x1b000, v20
	s_nop 1
	v_addc_co_u32_e32 v59, vcc, 0, v21, vcc
	v_add_co_u32_e32 v60, vcc, 0x1c000, v20
	s_nop 1
	v_addc_co_u32_e32 v61, vcc, 0, v21, vcc
	v_add_co_u32_e32 v62, vcc, 0x1d000, v20
	s_nop 1
	v_addc_co_u32_e32 v63, vcc, 0, v21, vcc
	v_add_co_u32_e32 v64, vcc, 0x1e000, v20
	s_nop 1
	v_addc_co_u32_e32 v65, vcc, 0, v21, vcc
	v_add_co_u32_e32 v20, vcc, 0x1f000, v20
	s_nop 1
	v_addc_co_u32_e32 v21, vcc, 0, v21, vcc
	global_load_dword v22, v[22:23], off nt
	s_nop 0
	global_load_dword v23, v[28:29], off nt
	s_nop 0
	global_load_dword v28, v[30:31], off nt
	global_load_dword v29, v[58:59], off nt
	s_nop 0
	global_load_dword v30, v[60:61], off nt
	global_load_dword v31, v[62:63], off nt
	global_load_dword v58, v[64:65], off nt
	s_nop 0
	global_load_dword v20, v[20:21], off nt
	s_waitcnt vmcnt(30)
	ds_write2_b32 v32, v2, v68 offset1:66
	s_waitcnt vmcnt(28)
	ds_write2_b32 v32, v69, v70 offset0:132 offset1:198
	v_add_u32_e32 v2, 0x400, v32
	s_waitcnt vmcnt(26)
	ds_write2_b32 v2, v71, v72 offset0:8 offset1:74
	s_waitcnt vmcnt(24)
	ds_write2_b32 v2, v73, v74 offset0:140 offset1:206
	v_add_u32_e32 v2, 0x800, v32
	s_waitcnt vmcnt(22)
	ds_write2_b32 v2, v75, v76 offset0:16 offset1:82
	s_waitcnt vmcnt(20)
	ds_write2_b32 v2, v77, v78 offset0:148 offset1:214
	v_add_u32_e32 v2, 0xc00, v32
	s_waitcnt vmcnt(18)
	ds_write2_b32 v2, v79, v80 offset0:24 offset1:90
	s_waitcnt vmcnt(16)
	ds_write2_b32 v2, v81, v82 offset0:156 offset1:222
	v_add_u32_e32 v2, 0x1000, v32
	s_waitcnt vmcnt(14)
	ds_write2_b32 v2, v83, v84 offset0:32 offset1:98
	s_waitcnt vmcnt(12)
	ds_write2_b32 v2, v85, v86 offset0:164 offset1:230
	v_add_u32_e32 v2, 0x1400, v32
	s_waitcnt vmcnt(10)
	ds_write2_b32 v2, v87, v88 offset0:40 offset1:106
	s_waitcnt vmcnt(8)
	ds_write2_b32 v2, v89, v66 offset0:172 offset1:238
	v_add_u32_e32 v2, 0x1800, v32
	s_waitcnt vmcnt(6)
	ds_write2_b32 v2, v22, v23 offset0:48 offset1:114
	s_waitcnt vmcnt(4)
	ds_write2_b32 v2, v28, v29 offset0:180 offset1:246
	v_add_u32_e32 v2, 0x1c00, v32
	s_waitcnt vmcnt(2)
	ds_write2_b32 v2, v30, v31 offset0:56 offset1:122
	s_waitcnt vmcnt(0)
	ds_write2_b32 v2, v58, v20 offset0:188 offset1:254
	s_waitcnt lgkmcnt(0)
	v_lshlrev_b32_e32 v2, 1, v19
	ds_read2_b32 v[30:31], v47 offset0:33 offset1:41
	ds_read2_b32 v[58:59], v47 offset1:8
	ds_read2_b32 v[60:61], v47 offset0:66 offset1:74
	ds_read2_b32 v[62:63], v47 offset0:99 offset1:107
	ds_read2_b32 v[64:65], v47 offset0:132 offset1:140
	ds_read2_b32 v[66:67], v47 offset0:165 offset1:173
	ds_read2_b32 v[68:69], v47 offset0:198 offset1:206
	ds_read2_b32 v[70:71], v47 offset0:231 offset1:239
	v_lshl_add_u64 v[28:29], v[10:11], 0, v[2:3]
	v_or_b32_e32 v2, v57, v46
	v_lshlrev_b32_e32 v2, 10, v2
	v_lshl_add_u64 v[72:73], v[28:29], 0, v[2:3]
	v_or_b32_e32 v2, v57, v48
	s_waitcnt lgkmcnt(6)
	v_cvt_pk_bf16_f32 v20, v58, v30
	v_lshlrev_b32_e32 v2, 10, v2
	s_waitcnt lgkmcnt(4)
	v_cvt_pk_bf16_f32 v21, v60, v62
	s_waitcnt lgkmcnt(2)
	v_cvt_pk_bf16_f32 v22, v64, v66
	s_waitcnt lgkmcnt(0)
	v_cvt_pk_bf16_f32 v23, v68, v70
	global_store_dwordx4 v[72:73], v[20:23], off
	s_nop 1
	v_cvt_pk_bf16_f32 v20, v59, v31
	v_lshl_add_u64 v[30:31], v[28:29], 0, v[2:3]
	v_cvt_pk_bf16_f32 v21, v61, v63
	v_cvt_pk_bf16_f32 v22, v65, v67
	v_cvt_pk_bf16_f32 v23, v69, v71
	global_store_dwordx4 v[30:31], v[20:23], off
	ds_read2_b32 v[30:31], v47 offset0:16 offset1:24
	ds_read2_b32 v[58:59], v47 offset0:49 offset1:57
	ds_read2_b32 v[60:61], v47 offset0:82 offset1:90
	ds_read2_b32 v[62:63], v47 offset0:115 offset1:123
	ds_read2_b32 v[64:65], v47 offset0:148 offset1:156
	ds_read2_b32 v[66:67], v47 offset0:181 offset1:189
	ds_read2_b32 v[68:69], v47 offset0:214 offset1:222
	ds_read2_b32 v[70:71], v47 offset0:247 offset1:255
	v_or_b32_e32 v2, v57, v49
	v_lshlrev_b32_e32 v2, 10, v2
	v_lshl_add_u64 v[72:73], v[28:29], 0, v[2:3]
	v_or_b32_e32 v2, v57, v50
	v_lshlrev_b32_e32 v2, 10, v2
	s_waitcnt lgkmcnt(6)
	v_cvt_pk_bf16_f32 v20, v30, v58
	s_waitcnt lgkmcnt(4)
	v_cvt_pk_bf16_f32 v21, v60, v62
	s_waitcnt lgkmcnt(2)
	v_cvt_pk_bf16_f32 v22, v64, v66
	s_waitcnt lgkmcnt(0)
	v_cvt_pk_bf16_f32 v23, v68, v70
	v_lshl_add_u64 v[28:29], v[28:29], 0, v[2:3]
	global_store_dwordx4 v[72:73], v[20:23], off
	s_nop 1
	v_cvt_pk_bf16_f32 v20, v31, v59
	v_cvt_pk_bf16_f32 v21, v61, v63
	v_cvt_pk_bf16_f32 v22, v65, v67
	v_cvt_pk_bf16_f32 v23, v69, v71
	global_store_dwordx4 v[28:29], v[20:23], off
	s_waitcnt lgkmcnt(0)

.LBB0_128:
	s_andn2_saveexec_b64 s[0:1], s[92:93]
	s_cbranch_execz .LBB0_21
	v_ashrrev_i32_e32 v2, 31, v56
	v_lshrrev_b32_e32 v2, 26, v2
	v_add_u32_e32 v2, v56, v2
	v_ashrrev_i32_e32 v19, 6, v2
	v_and_b32_e32 v20, 0xffffffc0, v2
	v_lshlrev_b32_e32 v2, 11, v19
	v_or_b32_e32 v28, v20, v0
	v_sub_u32_e32 v22, v51, v2
	v_or_b32_e32 v64, 6, v28
	v_or_b32_e32 v66, 8, v28
	v_or_b32_e32 v68, 10, v28
	v_or_b32_e32 v70, 12, v28
	v_or_b32_e32 v72, 14, v28
	v_ashrrev_i32_e32 v23, 31, v22
	v_ashrrev_i32_e32 v29, 31, v28
	v_or_b32_e32 v60, 2, v28
	v_or_b32_e32 v62, 4, v28
	v_ashrrev_i32_e32 v65, 31, v64
	v_ashrrev_i32_e32 v67, 31, v66
	v_ashrrev_i32_e32 v69, 31, v68
	v_ashrrev_i32_e32 v71, 31, v70
	v_ashrrev_i32_e32 v73, 31, v72
	v_lshl_add_u64 v[30:31], v[22:23], 2, v[16:17]
	v_lshlrev_b64 v[58:59], 13, v[28:29]
	v_ashrrev_i32_e32 v61, 31, v60
	v_ashrrev_i32_e32 v63, 31, v62
	v_lshlrev_b64 v[64:65], 13, v[64:65]
	v_lshlrev_b64 v[66:67], 13, v[66:67]
	v_lshlrev_b64 v[68:69], 13, v[68:69]
	v_lshlrev_b64 v[70:71], 13, v[70:71]
	v_lshlrev_b64 v[72:73], 13, v[72:73]
	v_lshl_add_u64 v[58:59], v[30:31], 0, v[58:59]
	v_lshlrev_b64 v[60:61], 13, v[60:61]
	v_lshlrev_b64 v[62:63], 13, v[62:63]
	v_lshl_add_u64 v[64:65], v[30:31], 0, v[64:65]
	v_lshl_add_u64 v[66:67], v[30:31], 0, v[66:67]
	v_lshl_add_u64 v[68:69], v[30:31], 0, v[68:69]
	v_lshl_add_u64 v[70:71], v[30:31], 0, v[70:71]
	v_lshl_add_u64 v[72:73], v[30:31], 0, v[72:73]
	v_lshl_add_u64 v[60:61], v[30:31], 0, v[60:61]
	v_lshl_add_u64 v[62:63], v[30:31], 0, v[62:63]
	global_load_dword v83, v[58:59], off nt
	global_load_dword v84, v[60:61], off nt
	global_load_dword v82, v[62:63], off nt
	global_load_dword v81, v[64:65], off nt
	global_load_dword v74, v[66:67], off nt
	global_load_dword v76, v[68:69], off nt
	global_load_dword v75, v[70:71], off nt
	s_nop 0
	global_load_dword v73, v[72:73], off nt
	v_or_b32_e32 v58, 16, v28
	v_or_b32_e32 v64, 22, v28
	v_or_b32_e32 v66, 24, v28
	v_or_b32_e32 v68, 26, v28
	v_or_b32_e32 v70, 28, v28
	v_ashrrev_i32_e32 v59, 31, v58
	v_or_b32_e32 v60, 18, v28
	v_or_b32_e32 v62, 20, v28
	v_ashrrev_i32_e32 v65, 31, v64
	v_ashrrev_i32_e32 v67, 31, v66
	v_ashrrev_i32_e32 v69, 31, v68
	v_ashrrev_i32_e32 v71, 31, v70
	v_or_b32_e32 v78, 30, v28
	v_lshlrev_b64 v[58:59], 13, v[58:59]
	v_ashrrev_i32_e32 v61, 31, v60
	v_ashrrev_i32_e32 v63, 31, v62
	v_lshlrev_b64 v[64:65], 13, v[64:65]
	v_lshlrev_b64 v[66:67], 13, v[66:67]
	v_lshlrev_b64 v[68:69], 13, v[68:69]
	v_lshlrev_b64 v[70:71], 13, v[70:71]
	v_ashrrev_i32_e32 v79, 31, v78
	v_lshl_add_u64 v[58:59], v[30:31], 0, v[58:59]
	v_lshlrev_b64 v[60:61], 13, v[60:61]
	v_lshlrev_b64 v[62:63], 13, v[62:63]
	v_lshl_add_u64 v[64:65], v[30:31], 0, v[64:65]
	v_lshl_add_u64 v[66:67], v[30:31], 0, v[66:67]
	v_lshl_add_u64 v[68:69], v[30:31], 0, v[68:69]
	v_lshl_add_u64 v[70:71], v[30:31], 0, v[70:71]
	v_lshlrev_b64 v[78:79], 13, v[78:79]
	v_lshl_add_u64 v[60:61], v[30:31], 0, v[60:61]
	v_lshl_add_u64 v[62:63], v[30:31], 0, v[62:63]
	v_lshl_add_u64 v[86:87], v[30:31], 0, v[78:79]
	global_load_dword v78, v[58:59], off nt
	global_load_dword v80, v[60:61], off nt
	global_load_dword v79, v[62:63], off nt
	global_load_dword v77, v[64:65], off nt
	s_nop 0
	global_load_dword v66, v[66:67], off nt
	s_nop 0
	global_load_dword v68, v[68:69], off nt
	s_nop 0
	global_load_dword v67, v[70:71], off nt
	global_load_dword v65, v[86:87], off nt
	v_or_b32_e32 v70, 38, v28
	v_ashrrev_i32_e32 v71, 31, v70
	v_lshlrev_b64 v[70:71], 13, v[70:71]
	v_lshl_add_u64 v[86:87], v[30:31], 0, v[70:71]
	v_or_b32_e32 v70, 40, v28
	v_ashrrev_i32_e32 v71, 31, v70
	v_lshlrev_b64 v[70:71], 13, v[70:71]
	v_lshl_add_u64 v[88:89], v[30:31], 0, v[70:71]
	v_or_b32_e32 v70, 42, v28
	v_ashrrev_i32_e32 v71, 31, v70
	v_lshlrev_b64 v[70:71], 13, v[70:71]
	v_lshl_add_u64 v[90:91], v[30:31], 0, v[70:71]
	v_or_b32_e32 v70, 44, v28
	v_ashrrev_i32_e32 v71, 31, v70
	v_or_b32_e32 v58, 32, v28
	v_or_b32_e32 v60, 34, v28
	v_or_b32_e32 v62, 36, v28
	v_lshlrev_b64 v[70:71], 13, v[70:71]
	v_ashrrev_i32_e32 v59, 31, v58
	v_ashrrev_i32_e32 v61, 31, v60
	v_ashrrev_i32_e32 v63, 31, v62
	v_lshl_add_u64 v[92:93], v[30:31], 0, v[70:71]
	v_or_b32_e32 v70, 46, v28
	v_lshlrev_b64 v[58:59], 13, v[58:59]
	v_lshlrev_b64 v[60:61], 13, v[60:61]
	v_lshlrev_b64 v[62:63], 13, v[62:63]
	v_ashrrev_i32_e32 v71, 31, v70
	v_lshl_add_u64 v[58:59], v[30:31], 0, v[58:59]
	v_lshl_add_u64 v[60:61], v[30:31], 0, v[60:61]
	v_lshl_add_u64 v[62:63], v[30:31], 0, v[62:63]
	v_lshlrev_b64 v[70:71], 13, v[70:71]
	v_lshl_add_u64 v[94:95], v[30:31], 0, v[70:71]
	global_load_dword v70, v[58:59], off nt
	global_load_dword v72, v[60:61], off nt
	global_load_dword v71, v[62:63], off nt
	global_load_dword v69, v[86:87], off nt
	s_nop 0
	global_load_dword v58, v[88:89], off nt
	global_load_dword v60, v[90:91], off nt
	global_load_dword v59, v[92:93], off nt
	global_load_dword v57, v[94:95], off nt
	v_or_b32_e32 v62, 48, v28
	v_ashrrev_i32_e32 v63, 31, v62
	v_or_b32_e32 v86, 50, v28
	v_or_b32_e32 v88, 52, v28
	v_or_b32_e32 v90, 54, v28
	v_or_b32_e32 v92, 56, v28
	v_or_b32_e32 v94, 58, v28
	v_or_b32_e32 v96, 60, v28
	v_or_b32_e32 v98, 62, v28
	v_lshlrev_b64 v[62:63], 13, v[62:63]
	v_ashrrev_i32_e32 v87, 31, v86
	v_ashrrev_i32_e32 v89, 31, v88
	v_ashrrev_i32_e32 v91, 31, v90
	v_ashrrev_i32_e32 v93, 31, v92
	v_ashrrev_i32_e32 v95, 31, v94
	v_ashrrev_i32_e32 v97, 31, v96
	v_ashrrev_i32_e32 v99, 31, v98
	v_lshl_add_u64 v[62:63], v[30:31], 0, v[62:63]
	v_lshlrev_b64 v[86:87], 13, v[86:87]
	v_lshlrev_b64 v[88:89], 13, v[88:89]
	v_lshlrev_b64 v[90:91], 13, v[90:91]
	v_lshlrev_b64 v[92:93], 13, v[92:93]
	v_lshlrev_b64 v[94:95], 13, v[94:95]
	v_lshlrev_b64 v[96:97], 13, v[96:97]
	v_lshlrev_b64 v[98:99], 13, v[98:99]
	v_lshl_add_u64 v[86:87], v[30:31], 0, v[86:87]
	v_lshl_add_u64 v[88:89], v[30:31], 0, v[88:89]
	v_lshl_add_u64 v[90:91], v[30:31], 0, v[90:91]
	v_lshl_add_u64 v[92:93], v[30:31], 0, v[92:93]
	v_lshl_add_u64 v[94:95], v[30:31], 0, v[94:95]
	v_lshl_add_u64 v[96:97], v[30:31], 0, v[96:97]
	v_lshl_add_u64 v[98:99], v[30:31], 0, v[98:99]
	global_load_dword v62, v[62:63], off nt
	s_nop 0
	global_load_dword v64, v[86:87], off nt
	global_load_dword v63, v[88:89], off nt
	global_load_dword v61, v[90:91], off nt
	global_load_dword v30, v[92:93], off nt
	global_load_dword v31, v[94:95], off nt
	global_load_dword v23, v[96:97], off nt
	global_load_dword v19, v[98:99], off nt
	v_cndmask_b32_e64 v21, 0, 1, s[88:89]
	v_cmp_ne_u32_e64 s[6:7], 1, v21
	s_andn2_b64 vcc, exec, s[88:89]
	v_ashrrev_i32_e32 v21, 31, v20
	v_add_u32_e32 v85, v27, v33
	s_cbranch_vccnz .LBB0_152
	v_lshl_add_u64 v[28:29], v[28:29], 2, s[40:41]
	global_load_dword v86, v[28:29], off nt
	v_lshl_add_u64 v[28:29], v[20:21], 0, v[0:1]
	v_lshl_add_u64 v[28:29], v[28:29], 2, s[40:41]
	global_load_dword v87, v[28:29], off offset:8 nt
	global_load_dword v88, v[28:29], off offset:16 nt
	s_nop 0
	global_load_dword v28, v[28:29], off offset:24 nt
	s_waitcnt vmcnt(3)
	v_mul_f32_e32 v29, v83, v86
	ds_write_b32 v32, v29
	s_waitcnt vmcnt(2)
	v_mul_f32_e32 v86, v84, v87
	s_waitcnt vmcnt(1)
	v_mul_f32_e32 v29, v82, v88
	ds_write_b32 v85, v86
	s_cbranch_execnz .LBB0_132

.LBB0_132:
	s_waitcnt vmcnt(29)
	v_add_u32_e32 v82, v27, v34
	s_waitcnt vmcnt(0)
	v_mul_f32_e32 v28, v81, v28
	ds_write2_b32 v82, v29, v28 offset1:66
	s_and_b64 vcc, exec, s[6:7]
	v_add_u32_e32 v28, v27, v35
	s_cbranch_vccnz .LBB0_153
	v_lshl_add_u64 v[82:83], v[20:21], 0, v[0:1]
	v_lshl_add_u64 v[82:83], v[82:83], 2, s[40:41]
	global_load_dword v81, v[82:83], off offset:32 nt
	global_load_dword v84, v[82:83], off offset:40 nt
	global_load_dword v85, v[82:83], off offset:48 nt
	global_load_dword v29, v[82:83], off offset:56 nt
	s_waitcnt vmcnt(3)
	v_mul_f32_e32 v82, v74, v81
	s_waitcnt vmcnt(2)
	v_mul_f32_e32 v83, v76, v84
	s_waitcnt vmcnt(1)
	v_mul_f32_e32 v81, v75, v85
	ds_write2_b32 v28, v82, v83 offset1:66
	s_cbranch_execnz .LBB0_135

.LBB0_135:
	v_add_u32_e32 v28, v27, v36
	s_waitcnt vmcnt(0)
	v_mul_f32_e32 v29, v73, v29
	ds_write2_b32 v28, v81, v29 offset1:66
	s_and_b64 vcc, exec, s[6:7]
	v_add_u32_e32 v28, v27, v37
	s_cbranch_vccnz .LBB0_154
	v_lshl_add_u64 v[74:75], v[20:21], 0, v[0:1]
	v_lshl_add_u64 v[74:75], v[74:75], 2, s[40:41]
	global_load_dword v73, v[74:75], off offset:64 nt
	global_load_dword v76, v[74:75], off offset:72 nt
	global_load_dword v81, v[74:75], off offset:80 nt
	global_load_dword v29, v[74:75], off offset:88 nt
	s_waitcnt vmcnt(3)
	v_mul_f32_e32 v74, v78, v73
	s_waitcnt vmcnt(2)
	v_mul_f32_e32 v75, v80, v76
	s_waitcnt vmcnt(1)
	v_mul_f32_e32 v73, v79, v81
	ds_write2_b32 v28, v74, v75 offset1:66
	s_cbranch_execnz .LBB0_138

.LBB0_138:
	v_add_u32_e32 v28, v27, v38
	s_waitcnt vmcnt(0)
	v_mul_f32_e32 v29, v77, v29
	ds_write2_b32 v28, v73, v29 offset1:66
	s_and_b64 vcc, exec, s[6:7]
	v_add_u32_e32 v28, v27, v39
	s_cbranch_vccnz .LBB0_155
	v_lshl_add_u64 v[74:75], v[20:21], 0, v[0:1]
	v_lshl_add_u64 v[74:75], v[74:75], 2, s[40:41]
	global_load_dword v73, v[74:75], off offset:96 nt
	global_load_dword v76, v[74:75], off offset:104 nt
	global_load_dword v77, v[74:75], off offset:112 nt
	global_load_dword v29, v[74:75], off offset:120 nt
	s_waitcnt vmcnt(3)
	v_mul_f32_e32 v74, v66, v73
	s_waitcnt vmcnt(2)
	v_mul_f32_e32 v75, v68, v76
	s_waitcnt vmcnt(1)
	v_mul_f32_e32 v73, v67, v77
	ds_write2_b32 v28, v74, v75 offset1:66
	s_cbranch_execnz .LBB0_141

.LBB0_141:
	v_add_u32_e32 v28, v27, v40
	s_waitcnt vmcnt(0)
	v_mul_f32_e32 v29, v65, v29
	ds_write2_b32 v28, v73, v29 offset1:66
	s_and_b64 vcc, exec, s[6:7]
	v_add_u32_e32 v28, v27, v41
	s_cbranch_vccnz .LBB0_156
	v_lshl_add_u64 v[66:67], v[20:21], 0, v[0:1]
	v_lshl_add_u64 v[66:67], v[66:67], 2, s[40:41]
	global_load_dword v65, v[66:67], off offset:128 nt
	global_load_dword v68, v[66:67], off offset:136 nt
	global_load_dword v73, v[66:67], off offset:144 nt
	global_load_dword v29, v[66:67], off offset:152 nt
	s_waitcnt vmcnt(3)
	v_mul_f32_e32 v66, v70, v65
	s_waitcnt vmcnt(2)
	v_mul_f32_e32 v67, v72, v68
	s_waitcnt vmcnt(1)
	v_mul_f32_e32 v65, v71, v73
	ds_write2_b32 v28, v66, v67 offset1:66
	s_cbranch_execnz .LBB0_144

.LBB0_144:
	v_add_u32_e32 v28, v27, v42
	s_waitcnt vmcnt(0)
	v_mul_f32_e32 v29, v69, v29
	ds_write2_b32 v28, v65, v29 offset1:66
	s_and_b64 vcc, exec, s[6:7]
	v_add_u32_e32 v28, v27, v43
	s_cbranch_vccnz .LBB0_157
	v_lshl_add_u64 v[66:67], v[20:21], 0, v[0:1]
	v_lshl_add_u64 v[66:67], v[66:67], 2, s[40:41]
	global_load_dword v65, v[66:67], off offset:160 nt
	global_load_dword v68, v[66:67], off offset:168 nt
	global_load_dword v69, v[66:67], off offset:176 nt
	global_load_dword v29, v[66:67], off offset:184 nt
	s_waitcnt vmcnt(3)
	v_mul_f32_e32 v66, v58, v65
	s_waitcnt vmcnt(2)
	v_mul_f32_e32 v67, v60, v68
	s_waitcnt vmcnt(1)
	v_mul_f32_e32 v65, v59, v69
	ds_write2_b32 v28, v66, v67 offset1:66
	s_cbranch_execnz .LBB0_147

.LBB0_147:
	v_add_u32_e32 v28, v27, v44
	s_waitcnt vmcnt(0)
	v_mul_f32_e32 v29, v57, v29
	ds_write2_b32 v28, v65, v29 offset1:66
	s_and_b64 vcc, exec, s[6:7]
	v_add_u32_e32 v28, v27, v45
	s_cbranch_vccnz .LBB0_158
	v_lshl_add_u64 v[58:59], v[20:21], 0, v[0:1]
	v_lshl_add_u64 v[58:59], v[58:59], 2, s[40:41]
	global_load_dword v57, v[58:59], off offset:192 nt
	global_load_dword v60, v[58:59], off offset:200 nt
	global_load_dword v65, v[58:59], off offset:208 nt
	global_load_dword v29, v[58:59], off offset:216 nt
	s_waitcnt vmcnt(3)
	v_mul_f32_e32 v58, v62, v57
	s_waitcnt vmcnt(2)
	v_mul_f32_e32 v59, v64, v60
	s_waitcnt vmcnt(1)
	v_mul_f32_e32 v57, v63, v65
	ds_write2_b32 v28, v58, v59 offset1:66
	s_cbranch_execnz .LBB0_150

.LBB0_150:
	s_waitcnt vmcnt(0)
	v_mul_f32_e32 v29, v61, v29
	ds_write2_b32 v28, v57, v29 offset0:132 offset1:198
	s_and_b64 vcc, exec, s[6:7]
	v_add_u32_e32 v28, 0x400, v28
	s_cbranch_vccnz .LBB0_159
	v_lshl_add_u64 v[58:59], v[20:21], 0, v[0:1]
	v_lshl_add_u64 v[58:59], v[58:59], 2, s[40:41]
	global_load_dword v57, v[58:59], off offset:224 nt
	global_load_dword v60, v[58:59], off offset:232 nt
	global_load_dword v61, v[58:59], off offset:240 nt
	global_load_dword v29, v[58:59], off offset:248 nt
	s_waitcnt vmcnt(3)
	v_mul_f32_e32 v58, v30, v57
	s_waitcnt vmcnt(2)
	v_mul_f32_e32 v59, v31, v60
	s_waitcnt vmcnt(1)
	v_mul_f32_e32 v57, v23, v61
	ds_write2_b32 v28, v58, v59 offset0:8 offset1:74
	s_cbranch_execnz .LBB0_20
	s_branch .LBB0_160

.LBB0_189:
	global_load_dwordx4 v[8:11], v[30:31], off offset:-4096 nt
	s_waitcnt lgkmcnt(0)
	global_load_dwordx4 v[4:7], v[30:31], off nt
	global_load_dwordx4 v[20:23], v[30:31], off offset:-3072 nt
	global_load_dwordx4 v[0:3], v[30:31], off offset:1024 nt
	global_load_dwordx4 v[42:45], v[30:31], off offset:2048 nt
	global_load_dwordx4 v[46:49], v[30:31], off offset:3072 nt
	global_load_dwordx4 v[16:19], v[30:31], off offset:-2048 nt
	global_load_dwordx4 v[12:15], v[30:31], off offset:-1024 nt
	v_cmp_lt_i32_e64 s[0:1], v35, v34
	s_waitcnt vmcnt(7)
	v_cvt_pk_bf16_f32 v64, v8, v9
	v_mov_b32_e32 v50, v9
	s_waitcnt vmcnt(6)
	v_mov_b32_e32 v51, v5
	v_mov_b32_e32 v54, v11
	v_mov_b32_e32 v55, v7
	s_waitcnt vmcnt(5)
	v_mov_b32_e32 v58, v21
	s_waitcnt vmcnt(4)
	v_mov_b32_e32 v59, v1
	v_mov_b32_e32 v62, v23
	v_mov_b32_e32 v63, v3
	v_mov_b32_e32 v52, v10
	v_mov_b32_e32 v53, v6
	v_mov_b32_e32 v56, v20
	v_mov_b32_e32 v57, v0
	v_mov_b32_e32 v60, v22
	v_mov_b32_e32 v61, v2
	s_waitcnt vmcnt(3)
	v_cvt_pk_bf16_f32 v66, v42, v43
	v_cvt_pk_bf16_f32 v67, v44, v45
	v_mov_b32_e32 v9, v4
	v_mov_b32_e32 v71, v42
	s_waitcnt vmcnt(1)
	v_mov_b32_e32 v42, v17
	v_mov_b32_e32 v73, v44
	v_mov_b32_e32 v44, v19
	v_pk_mul_f32 v[50:51], v[50:51], v[50:51]
	v_pk_mul_f32 v[54:55], v[54:55], v[54:55]
	v_pk_mul_f32 v[58:59], v[58:59], v[58:59]
	v_pk_mul_f32 v[62:63], v[62:63], v[62:63]
	v_cvt_pk_bf16_f32 v68, v46, v47
	v_cvt_pk_bf16_f32 v69, v48, v49
	v_mov_b32_e32 v70, v16
	v_mov_b32_e32 v72, v18
	v_mov_b32_e32 v75, v46
	s_waitcnt vmcnt(0)
	v_mov_b32_e32 v46, v13
	v_mov_b32_e32 v77, v48
	v_mov_b32_e32 v48, v15
	v_pk_mul_f32 v[42:43], v[42:43], v[42:43]
	v_pk_mul_f32 v[44:45], v[44:45], v[44:45]
	v_pk_fma_f32 v[52:53], v[52:53], v[52:53], v[54:55]
	v_pk_fma_f32 v[54:55], v[56:57], v[56:57], v[58:59]
	v_pk_fma_f32 v[56:57], v[60:61], v[60:61], v[62:63]
	v_pk_fma_f32 v[8:9], v[8:9], v[8:9], v[50:51]
	v_mov_b32_e32 v74, v12
	v_mov_b32_e32 v76, v14
	v_pk_mul_f32 v[46:47], v[46:47], v[46:47]
	v_pk_mul_f32 v[48:49], v[48:49], v[48:49]
	v_pk_fma_f32 v[42:43], v[70:71], v[70:71], v[42:43]
	v_pk_fma_f32 v[44:45], v[72:73], v[72:73], v[44:45]
	v_pk_add_f32 v[50:51], v[54:55], v[56:57]
	v_pk_add_f32 v[8:9], v[8:9], v[52:53]
	v_pk_fma_f32 v[46:47], v[74:75], v[74:75], v[46:47]
	v_pk_fma_f32 v[48:49], v[76:77], v[76:77], v[48:49]
	v_pk_add_f32 v[42:43], v[42:43], v[44:45]
	v_pk_add_f32 v[8:9], v[8:9], v[50:51]
	v_cndmask_b32_e64 v41, v27, v35, s[0:1]
	v_pk_add_f32 v[44:45], v[46:47], v[48:49]
	v_pk_add_f32 v[8:9], v[8:9], v[42:43]
	v_lshlrev_b32_e32 v41, 2, v41
	v_pk_add_f32 v[8:9], v[8:9], v[44:45]
	ds_bpermute_b32 v42, v41, v8
	ds_bpermute_b32 v43, v41, v9
	v_cmp_lt_i32_e64 s[0:1], v36, v34
	v_cvt_pk_bf16_f32 v12, v12, v13
	v_cvt_pk_bf16_f32 v13, v14, v15
	v_cvt_pk_bf16_f32 v4, v4, v5
	s_waitcnt lgkmcnt(0)
	v_pk_add_f32 v[8:9], v[8:9], v[42:43]
	v_cvt_pk_bf16_f32 v5, v6, v7
	v_cndmask_b32_e64 v65, v27, v36, s[0:1]
	v_lshlrev_b32_e32 v41, 2, v65
	ds_bpermute_b32 v42, v41, v8
	ds_bpermute_b32 v43, v41, v9
	v_cmp_lt_i32_e64 s[0:1], v37, v34
	v_cvt_pk_bf16_f32 v65, v10, v11
	v_cvt_pk_bf16_f32 v10, v20, v21
	v_cvt_pk_bf16_f32 v6, v0, v1
	s_waitcnt lgkmcnt(0)
	v_pk_add_f32 v[8:9], v[8:9], v[42:43]
	v_cvt_pk_bf16_f32 v11, v22, v23
	v_cndmask_b32_e64 v78, v27, v37, s[0:1]
	v_lshlrev_b32_e32 v44, 2, v78
	ds_bpermute_b32 v20, v44, v8
	ds_bpermute_b32 v21, v44, v9
	v_cmp_lt_i32_e64 s[0:1], v38, v34
	v_cvt_pk_bf16_f32 v16, v16, v17
	v_cvt_pk_bf16_f32 v17, v18, v19
	global_store_dwordx2 v[32:33], v[64:65], off
	s_waitcnt lgkmcnt(0)
	v_pk_add_f32 v[8:9], v[8:9], v[20:21]
	v_cndmask_b32_e64 v79, v27, v38, s[0:1]
	v_lshlrev_b32_e32 v45, 2, v79
	ds_bpermute_b32 v14, v45, v8
	ds_bpermute_b32 v15, v45, v9
	v_cmp_lt_i32_e64 s[0:1], v39, v34
	global_store_dwordx2 v[32:33], v[10:11], off offset:512
	global_store_dwordx2 v[32:33], v[16:17], off offset:1024
	global_store_dwordx2 v[32:33], v[12:13], off offset:1536
	global_store_dwordx2 v[32:33], v[4:5], off offset:2048
	v_cndmask_b32_e64 v80, v27, v39, s[0:1]
	v_lshlrev_b32_e32 v46, 2, v80
	s_waitcnt lgkmcnt(0)
	v_pk_add_f32 v[0:1], v[8:9], v[14:15]
	ds_bpermute_b32 v8, v46, v0
	ds_bpermute_b32 v9, v46, v1
	v_cmp_lt_i32_e64 s[0:1], v40, v34
	v_cvt_pk_bf16_f32 v7, v2, v3
	global_store_dwordx2 v[32:33], v[6:7], off offset:2560
	global_store_dwordx2 v[32:33], v[66:67], off offset:3072
	global_store_dwordx2 v[32:33], v[68:69], off offset:3584
	v_cndmask_b32_e64 v81, v27, v40, s[0:1]
	v_lshlrev_b32_e32 v41, 2, v81
	s_waitcnt lgkmcnt(0)
	v_pk_add_f32 v[0:1], v[0:1], v[8:9]
	ds_bpermute_b32 v4, v41, v0
	ds_bpermute_b32 v5, v41, v1
	s_and_saveexec_b64 s[0:1], vcc
	s_cbranch_execz .LBB0_188
	s_waitcnt lgkmcnt(0)
	v_pk_add_f32 v[0:1], v[0:1], v[4:5]
	global_store_dwordx2 v[28:29], v[0:1], off
	s_branch .LBB0_188

.LBB0_194:
	v_lshl_add_u64 v[0:1], s[38:39], 0, v[22:23]
	global_load_dwordx4 v[8:11], v[0:1], off nt
	v_lshl_add_u64 v[38:39], v[12:13], 0, s[24:25]
	v_cmp_gt_u64_e32 vcc, s[8:9], v[38:39]
	v_mov_b32_e32 v0, 0
	v_mov_b32_e32 v4, 0
	v_mov_b32_e32 v5, 0
	v_mov_b32_e32 v6, 0
	v_mov_b32_e32 v7, 0
	s_and_saveexec_b64 s[0:1], vcc
	s_cbranch_execz .LBB0_196
	v_lshl_add_u64 v[2:3], s[38:39], 0, v[20:21]
	global_load_dwordx4 v[4:7], v[2:3], off nt
.LBB0_196:
	s_or_b64 exec, exec, s[0:1]
	v_lshl_add_u64 v[2:3], s[42:43], 0, v[12:13]
	v_cmp_gt_u64_e64 s[0:1], s[8:9], v[2:3]
	v_mov_b32_e32 v1, 0
	v_mov_b32_e32 v2, 0
	v_mov_b32_e32 v3, 0
	s_and_saveexec_b64 s[6:7], s[0:1]
	s_cbranch_execz .LBB0_198
	v_lshl_add_u64 v[0:1], s[38:39], 0, v[32:33]
	global_load_dwordx4 v[0:3], v[0:1], off nt
.LBB0_198:
	s_or_b64 exec, exec, s[6:7]
	v_lshl_add_u64 v[12:13], s[52:53], 0, v[12:13]
	v_cmp_gt_u64_e64 s[6:7], s[8:9], v[12:13]
	v_mov_b32_e32 v12, 0
	v_mov_b32_e32 v13, 0
	v_mov_b32_e32 v14, 0
	v_mov_b32_e32 v15, 0
	s_and_saveexec_b64 s[58:59], s[6:7]
	s_cbranch_execz .LBB0_200
	v_lshl_add_u64 v[12:13], s[38:39], 0, v[36:37]
	global_load_dwordx4 v[12:15], v[12:13], off nt

.LBB0_746:
	v_lshl_or_b32 v166, s36, 8, v186
	v_lshl_add_u32 v170, s30, 8, v184
	v_ashrrev_i32_e32 v167, 31, v166
	v_lshlrev_b64 v[202:203], 1, v[166:167]
	v_ashrrev_i32_e32 v171, 31, v170
	v_lshl_add_u64 v[168:169], s[8:9], 0, v[202:203]
	v_lshlrev_b64 v[204:205], 11, v[170:171]
	v_lshl_add_u64 v[128:129], v[168:169], 0, v[204:205]
	global_load_dwordx4 v[194:197], v[128:129], off nt
	global_load_dwordx4 v[198:201], v[128:129], off offset:256 nt
	v_or_b32_e32 v180, 16, v170
	v_or_b32_e32 v176, 32, v170
	v_or_b32_e32 v172, 48, v170
	v_ashrrev_i32_e32 v181, 31, v180
	v_ashrrev_i32_e32 v177, 31, v176
	v_ashrrev_i32_e32 v173, 31, v172
	v_lshlrev_b64 v[182:183], 11, v[180:181]
	v_lshlrev_b64 v[178:179], 11, v[176:177]
	v_lshlrev_b64 v[174:175], 11, v[172:173]
	v_lshl_add_u64 v[128:129], v[168:169], 0, v[182:183]
	v_lshl_add_u64 v[130:131], v[168:169], 0, v[178:179]
	v_lshl_add_u64 v[206:207], v[168:169], 0, v[174:175]
	global_load_dwordx4 v[148:151], v[128:129], off nt
	global_load_dwordx4 v[144:147], v[128:129], off offset:256 nt
	global_load_dwordx4 v[140:143], v[130:131], off nt
	global_load_dwordx4 v[136:139], v[130:131], off offset:256 nt
	global_load_dwordx4 v[132:135], v[206:207], off nt
	s_nop 0
	global_load_dwordx4 v[128:131], v[206:207], off offset:256 nt
	v_and_b32_e32 v193, 64, v190
	v_xor_b32_e32 v191, 16, v190
	v_add_u32_e32 v193, 64, v193
	v_xor_b32_e32 v206, 32, v190
	v_cmp_lt_i32_e32 vcc, v191, v193
	v_lshl_add_u64 v[204:205], s[12:13], 0, v[204:205]
	v_lshl_add_u64 v[202:203], v[204:205], 0, v[202:203]
	v_cndmask_b32_e32 v191, v190, v191, vcc
	v_cmp_lt_i32_e32 vcc, v206, v193
	v_lshlrev_b32_e32 v191, 2, v191
	s_waitcnt vmcnt(0)
	v_lshlrev_b32_e32 v204, 16, v194
	v_cndmask_b32_e32 v193, v190, v206, vcc
	v_and_b32_e32 v205, 0xffff0000, v194
	v_lshlrev_b32_e32 v194, 16, v195
	v_and_b32_e32 v195, 0xffff0000, v195
	v_lshlrev_b32_e32 v206, 16, v196
	v_and_b32_e32 v207, 0xffff0000, v196
	v_lshlrev_b32_e32 v196, 16, v197
	v_and_b32_e32 v197, 0xffff0000, v197
	v_lshlrev_b32_e32 v208, 16, v198
	v_and_b32_e32 v209, 0xffff0000, v198
	v_lshlrev_b32_e32 v198, 16, v199
	v_and_b32_e32 v199, 0xffff0000, v199
	v_lshlrev_b32_e32 v210, 16, v200
	v_and_b32_e32 v211, 0xffff0000, v200
	v_lshlrev_b32_e32 v200, 16, v201
	v_and_b32_e32 v201, 0xffff0000, v201
	v_pk_add_f32 v[126:127], v[126:127], v[194:195]
	v_pk_add_f32 v[124:125], v[124:125], v[204:205]
	v_pk_add_f32 v[122:123], v[122:123], v[196:197]
	v_pk_add_f32 v[120:121], v[120:121], v[206:207]
	v_pk_add_f32 v[118:119], v[118:119], v[198:199]
	v_pk_add_f32 v[116:117], v[116:117], v[208:209]
	v_pk_add_f32 v[194:195], v[114:115], v[200:201]
	v_pk_add_f32 v[196:197], v[112:113], v[210:211]
	v_cvt_pk_bf16_f32 v112, v124, v125
	v_cvt_pk_bf16_f32 v113, v126, v127
	v_mul_f32_e32 v114, v125, v125
	v_mul_f32_e32 v115, v127, v127
	v_mul_f32_e32 v125, v121, v121
	v_mul_f32_e32 v127, v123, v123
	v_mul_f32_e32 v198, v117, v117
	v_mul_f32_e32 v199, v119, v119
	v_mul_f32_e32 v200, v197, v197
	v_mul_f32_e32 v201, v195, v195
	v_fmac_f32_e32 v114, v124, v124
	v_fmac_f32_e32 v115, v126, v126
	v_fmac_f32_e32 v125, v120, v120
	v_fmac_f32_e32 v127, v122, v122
	v_fmac_f32_e32 v198, v116, v116
	v_fmac_f32_e32 v199, v118, v118
	v_fmac_f32_e32 v200, v196, v196
	v_fmac_f32_e32 v201, v194, v194
	v_add_f32_e32 v114, v114, v115
	v_add_f32_e32 v115, v125, v127
	v_add_f32_e32 v124, v198, v199
	v_add_f32_e32 v125, v200, v201
	v_add_f32_e32 v114, v114, v115
	v_add_f32_e32 v115, v124, v125
	v_add_f32_e32 v124, v114, v115
	ds_bpermute_b32 v125, v191, v124
	v_cvt_pk_bf16_f32 v114, v120, v121
	v_cvt_pk_bf16_f32 v115, v122, v123
	global_store_dwordx4 v[202:203], v[112:115], off
	v_cvt_pk_bf16_f32 v116, v116, v117
	v_cvt_pk_bf16_f32 v117, v118, v119
	v_cvt_pk_bf16_f32 v118, v196, v197
	v_cvt_pk_bf16_f32 v119, v194, v195
	global_store_dwordx4 v[202:203], v[116:119], off offset:256
	s_waitcnt lgkmcnt(0)
	v_add_f32_e32 v113, v124, v125
	v_lshlrev_b32_e32 v112, 2, v193
	ds_bpermute_b32 v114, v112, v113
	s_and_saveexec_b64 s[30:31], s[4:5]
	s_cbranch_execz .LBB0_748
	v_lshl_add_u64 v[116:117], v[170:171], 2, s[14:15]
	s_waitcnt lgkmcnt(0)
	v_add_f32_e32 v113, v113, v114
	global_atomic_add_f32 v[116:117], v113, off

.LBB0_754:
	s_or_b64 exec, exec, s[30:31]
	v_add_u32_e32 v100, 0x80, v170
	v_ashrrev_i32_e32 v101, 31, v100
	v_lshlrev_b64 v[110:111], 11, v[100:101]
	s_waitcnt lgkmcnt(0)
	v_lshl_add_u64 v[64:65], v[168:169], 0, v[110:111]
	global_load_dwordx4 v[102:105], v[64:65], off nt
	global_load_dwordx4 v[106:109], v[64:65], off offset:256 nt
	v_add_u32_e32 v96, 0x90, v170
	v_add_u32_e32 v92, 0xa0, v170
	v_add_u32_e32 v88, 0xb0, v170
	v_ashrrev_i32_e32 v97, 31, v96
	v_ashrrev_i32_e32 v93, 31, v92
	v_ashrrev_i32_e32 v89, 31, v88
	v_lshlrev_b64 v[98:99], 11, v[96:97]
	v_lshlrev_b64 v[94:95], 11, v[92:93]
	v_lshlrev_b64 v[90:91], 11, v[88:89]
	v_lshl_add_u64 v[64:65], v[168:169], 0, v[98:99]
	v_lshl_add_u64 v[66:67], v[168:169], 0, v[94:95]
	v_lshl_add_u64 v[114:115], v[168:169], 0, v[90:91]
	global_load_dwordx4 v[84:87], v[64:65], off nt
	global_load_dwordx4 v[80:83], v[64:65], off offset:256 nt
	global_load_dwordx4 v[76:79], v[66:67], off nt
	global_load_dwordx4 v[72:75], v[66:67], off offset:256 nt
	global_load_dwordx4 v[68:71], v[114:115], off nt
	s_nop 0
	global_load_dwordx4 v[64:67], v[114:115], off offset:256 nt
	s_waitcnt vmcnt(7)
	v_lshlrev_b32_e32 v114, 16, v102
	v_and_b32_e32 v115, 0xffff0000, v102
	v_lshlrev_b32_e32 v102, 16, v103
	v_and_b32_e32 v103, 0xffff0000, v103
	v_lshlrev_b32_e32 v116, 16, v104
	v_and_b32_e32 v117, 0xffff0000, v104
	v_lshlrev_b32_e32 v104, 16, v105
	v_and_b32_e32 v105, 0xffff0000, v105
	s_waitcnt vmcnt(6)
	v_lshlrev_b32_e32 v118, 16, v106
	v_and_b32_e32 v119, 0xffff0000, v106
	v_lshlrev_b32_e32 v106, 16, v107
	v_and_b32_e32 v107, 0xffff0000, v107
	v_lshlrev_b32_e32 v120, 16, v108
	v_and_b32_e32 v121, 0xffff0000, v108
	v_lshlrev_b32_e32 v108, 16, v109
	v_and_b32_e32 v109, 0xffff0000, v109
	v_pk_add_f32 v[62:63], v[62:63], v[102:103]
	v_pk_add_f32 v[60:61], v[60:61], v[114:115]
	v_pk_add_f32 v[58:59], v[58:59], v[104:105]
	v_pk_add_f32 v[56:57], v[56:57], v[116:117]
	v_pk_add_f32 v[54:55], v[54:55], v[106:107]
	v_pk_add_f32 v[52:53], v[52:53], v[118:119]
	v_pk_add_f32 v[102:103], v[50:51], v[108:109]
	v_pk_add_f32 v[104:105], v[48:49], v[120:121]
	v_cvt_pk_bf16_f32 v48, v60, v61
	v_cvt_pk_bf16_f32 v49, v62, v63
	v_cvt_pk_bf16_f32 v50, v56, v57
	v_cvt_pk_bf16_f32 v51, v58, v59
	v_mul_f32_e32 v61, v61, v61
	v_mul_f32_e32 v63, v63, v63
	v_mul_f32_e32 v57, v57, v57
	v_mul_f32_e32 v59, v59, v59
	v_mul_f32_e32 v106, v53, v53
	v_mul_f32_e32 v107, v55, v55
	v_mul_f32_e32 v108, v105, v105
	v_mul_f32_e32 v109, v103, v103
	v_fmac_f32_e32 v61, v60, v60
	v_fmac_f32_e32 v63, v62, v62
	v_fmac_f32_e32 v57, v56, v56
	v_fmac_f32_e32 v59, v58, v58
	v_fmac_f32_e32 v106, v52, v52
	v_fmac_f32_e32 v107, v54, v54
	v_fmac_f32_e32 v108, v104, v104
	v_fmac_f32_e32 v109, v102, v102
	v_add_f32_e32 v56, v61, v63
	v_add_f32_e32 v57, v57, v59
	v_add_f32_e32 v58, v106, v107
	v_add_f32_e32 v59, v108, v109
	v_add_f32_e32 v56, v56, v57
	v_add_f32_e32 v57, v58, v59
	v_add_f32_e32 v58, v56, v57
	ds_bpermute_b32 v59, v191, v58
	v_lshl_add_u64 v[56:57], s[12:13], 0, v[110:111]
	v_lshl_add_u64 v[56:57], v[166:167], 1, v[56:57]
	global_store_dwordx4 v[56:57], v[48:51], off
	s_waitcnt lgkmcnt(0)
	s_nop 0
	v_add_f32_e32 v48, v58, v59
	ds_bpermute_b32 v49, v112, v48
	v_cvt_pk_bf16_f32 v50, v52, v53
	v_cvt_pk_bf16_f32 v51, v54, v55
	v_cvt_pk_bf16_f32 v52, v104, v105
	v_cvt_pk_bf16_f32 v53, v102, v103
	global_store_dwordx4 v[56:57], v[50:53], off offset:256
	s_and_saveexec_b64 s[30:31], s[4:5]
	s_cbranch_execz .LBB0_756
	v_lshl_add_u64 v[50:51], v[100:101], 2, s[14:15]
	s_waitcnt lgkmcnt(0)
	v_add_f32_e32 v48, v48, v49
	global_atomic_add_f32 v[50:51], v48, off

.LBB0_852:
	s_waitcnt vmcnt(0)
	v_fmamk_f32 v128, v231, 0x3a800000, v222
	v_mul_f32_e32 v129, 0x4b800000, v128
	v_cmp_gt_f32_e32 vcc, s67, v128
	v_lshlrev_b64 v[132:133], 13, v[208:209]
	s_nop 0
	v_cndmask_b32_e32 v128, v128, v129, vcc
	v_rsq_f32_e32 v130, v128
	v_lshl_or_b32 v128, s78, 8, v221
	v_ashrrev_i32_e32 v129, 31, v128
	v_mul_f32_e32 v131, 0x45800000, v130
	v_cndmask_b32_e32 v130, v130, v131, vcc
	v_pk_mul_f32 v[126:127], v[130:131], v[126:127] op_sel_hi:[0,1]
	v_pk_mul_f32 v[124:125], v[130:131], v[124:125] op_sel_hi:[0,1]
	v_pk_mul_f32 v[122:123], v[130:131], v[122:123] op_sel_hi:[0,1]
	v_pk_mul_f32 v[120:121], v[130:131], v[120:121] op_sel_hi:[0,1]
	v_max_f32_e32 v124, 0, v124
	v_max_f32_e32 v120, 0, v120
	v_max_f32_e32 v125, 0, v125
	v_max_f32_e32 v121, 0, v121
	v_max_f32_e32 v126, 0, v126
	v_max_f32_e32 v122, 0, v122
	v_max_f32_e32 v127, 0, v127
	v_max_f32_e32 v123, 0, v123
	v_mul_f32_e32 v124, v124, v124
	v_mul_f32_e32 v120, v120, v120
	v_mul_f32_e32 v125, v125, v125
	v_mul_f32_e32 v121, v121, v121
	v_mul_f32_e32 v126, v126, v126
	v_mul_f32_e32 v122, v122, v122
	v_mul_f32_e32 v127, v127, v127
	v_mul_f32_e32 v123, v123, v123
	v_cvt_pk_bf16_f32 v124, v124, v125
	v_cvt_pk_bf16_f32 v125, v126, v127
	v_cvt_pk_bf16_f32 v126, v120, v121
	v_cvt_pk_bf16_f32 v127, v122, v123
	v_lshl_add_u64 v[120:121], s[8:9], 0, v[132:133]
	v_lshlrev_b64 v[122:123], 1, v[128:129]
	v_pk_mul_f32 v[112:113], v[130:131], v[112:113] op_sel_hi:[0,1]
	v_lshl_add_u64 v[120:121], v[120:121], 0, v[122:123]
	v_pk_mul_f32 v[116:117], v[130:131], v[116:117] op_sel_hi:[0,1]
	v_pk_mul_f32 v[114:115], v[130:131], v[114:115] op_sel_hi:[0,1]
	v_max_f32_e32 v112, 0, v112
	global_store_dwordx4 v[120:121], v[124:127], off sc0 sc1 nt
	v_pk_mul_f32 v[118:119], v[130:131], v[118:119] op_sel_hi:[0,1]
	v_max_f32_e32 v116, 0, v116
	v_mul_f32_e32 v124, v112, v112
	v_max_f32_e32 v112, 0, v117
	v_max_f32_e32 v113, 0, v113
	v_max_f32_e32 v114, 0, v114
	v_mul_f32_e32 v116, v116, v116
	v_mul_f32_e32 v112, v112, v112
	v_mul_f32_e32 v117, v113, v113
	v_max_f32_e32 v113, 0, v118
	v_mul_f32_e32 v118, v114, v114
	v_max_f32_e32 v114, 0, v119
	v_mul_f32_e32 v113, v113, v113
	v_mul_f32_e32 v114, v114, v114
	v_cvt_pk_bf16_f32 v112, v116, v112
	v_fmamk_f32 v116, v230, 0x3a800000, v222
	v_cvt_pk_bf16_f32 v113, v113, v114
	v_cvt_pk_bf16_f32 v114, v124, v117
	v_mul_f32_e32 v117, 0x4b800000, v116
	v_cmp_gt_f32_e32 vcc, s67, v116
	v_max_f32_e32 v115, 0, v115
	v_mul_f32_e32 v115, v115, v115
	v_cndmask_b32_e32 v116, v116, v117, vcc
	v_rsq_f32_e32 v116, v116
	v_cvt_pk_bf16_f32 v115, v118, v115
	global_store_dwordx4 v[120:121], v[112:115], off offset:256 sc0 sc1 nt
	s_nop 1
	v_mul_f32_e32 v113, 0x45800000, v116
	v_cndmask_b32_e32 v114, v116, v113, vcc
	v_pk_mul_f32 v[106:107], v[114:115], v[106:107] op_sel_hi:[0,1]
	v_pk_mul_f32 v[104:105], v[114:115], v[104:105] op_sel_hi:[0,1]
	v_or_b32_e32 v112, 16, v208
	v_pk_mul_f32 v[110:111], v[114:115], v[110:111] op_sel_hi:[0,1]
	v_pk_mul_f32 v[108:109], v[114:115], v[108:109] op_sel_hi:[0,1]
	v_max_f32_e32 v104, 0, v104
	v_max_f32_e32 v105, 0, v105
	v_max_f32_e32 v106, 0, v106
	v_ashrrev_i32_e32 v113, 31, v112
	v_max_f32_e32 v108, 0, v108
	v_mul_f32_e32 v115, v104, v104
	v_max_f32_e32 v104, 0, v109
	v_mul_f32_e32 v109, v105, v105
	v_max_f32_e32 v105, 0, v110
	v_mul_f32_e32 v110, v106, v106
	v_max_f32_e32 v106, 0, v111
	v_lshlrev_b64 v[112:113], 13, v[112:113]
	v_mul_f32_e32 v108, v108, v108
	v_mul_f32_e32 v104, v104, v104
	v_mul_f32_e32 v105, v105, v105
	v_mul_f32_e32 v106, v106, v106
	v_max_f32_e32 v107, 0, v107
	v_cvt_pk_bf16_f32 v104, v108, v104
	v_cvt_pk_bf16_f32 v105, v105, v106
	v_cvt_pk_bf16_f32 v106, v115, v109
	v_lshl_add_u64 v[108:109], s[8:9], 0, v[112:113]
	v_pk_mul_f32 v[96:97], v[114:115], v[96:97] op_sel_hi:[0,1]
	v_mul_f32_e32 v107, v107, v107
	v_lshl_add_u64 v[108:109], v[108:109], 0, v[122:123]
	v_pk_mul_f32 v[100:101], v[114:115], v[100:101] op_sel_hi:[0,1]
	v_pk_mul_f32 v[98:99], v[114:115], v[98:99] op_sel_hi:[0,1]
	v_max_f32_e32 v96, 0, v96
	v_cvt_pk_bf16_f32 v107, v110, v107
	global_store_dwordx4 v[108:109], v[104:107], off sc0 sc1 nt
	v_pk_mul_f32 v[102:103], v[114:115], v[102:103] op_sel_hi:[0,1]
	v_max_f32_e32 v100, 0, v100
	v_mul_f32_e32 v104, v96, v96
	v_max_f32_e32 v96, 0, v101
	v_max_f32_e32 v97, 0, v97
	v_max_f32_e32 v98, 0, v98
	v_mul_f32_e32 v100, v100, v100
	v_mul_f32_e32 v96, v96, v96
	v_mul_f32_e32 v101, v97, v97
	v_max_f32_e32 v97, 0, v102
	v_mul_f32_e32 v102, v98, v98
	v_max_f32_e32 v98, 0, v103
	v_mul_f32_e32 v97, v97, v97
	v_mul_f32_e32 v98, v98, v98
	v_cvt_pk_bf16_f32 v96, v100, v96
	v_fmamk_f32 v100, v229, 0x3a800000, v222
	v_cvt_pk_bf16_f32 v97, v97, v98
	v_cvt_pk_bf16_f32 v98, v104, v101
	v_mul_f32_e32 v101, 0x4b800000, v100
	v_cmp_gt_f32_e32 vcc, s67, v100
	v_max_f32_e32 v99, 0, v99
	v_mul_f32_e32 v99, v99, v99
	v_cndmask_b32_e32 v100, v100, v101, vcc
	v_rsq_f32_e32 v100, v100
	v_cvt_pk_bf16_f32 v99, v102, v99
	global_store_dwordx4 v[108:109], v[96:99], off offset:256 sc0 sc1 nt
	s_nop 1
	v_mul_f32_e32 v97, 0x45800000, v100
	v_cndmask_b32_e32 v98, v100, v97, vcc
	v_pk_mul_f32 v[90:91], v[98:99], v[90:91] op_sel_hi:[0,1]
	v_pk_mul_f32 v[88:89], v[98:99], v[88:89] op_sel_hi:[0,1]
	v_or_b32_e32 v96, 32, v208
	v_pk_mul_f32 v[94:95], v[98:99], v[94:95] op_sel_hi:[0,1]
	v_pk_mul_f32 v[92:93], v[98:99], v[92:93] op_sel_hi:[0,1]
	v_max_f32_e32 v88, 0, v88
	v_max_f32_e32 v89, 0, v89
	v_max_f32_e32 v90, 0, v90
	v_ashrrev_i32_e32 v97, 31, v96
	v_max_f32_e32 v92, 0, v92
	v_mul_f32_e32 v99, v88, v88
	v_max_f32_e32 v88, 0, v93
	v_mul_f32_e32 v93, v89, v89
	v_max_f32_e32 v89, 0, v94
	v_mul_f32_e32 v94, v90, v90
	v_max_f32_e32 v90, 0, v95
	v_lshlrev_b64 v[96:97], 13, v[96:97]
	v_mul_f32_e32 v92, v92, v92
	v_mul_f32_e32 v88, v88, v88
	v_mul_f32_e32 v89, v89, v89
	v_mul_f32_e32 v90, v90, v90
	v_max_f32_e32 v91, 0, v91
	v_cvt_pk_bf16_f32 v88, v92, v88
	v_cvt_pk_bf16_f32 v89, v89, v90
	v_cvt_pk_bf16_f32 v90, v99, v93
	v_lshl_add_u64 v[92:93], s[8:9], 0, v[96:97]
	v_pk_mul_f32 v[80:81], v[98:99], v[80:81] op_sel_hi:[0,1]
	v_mul_f32_e32 v91, v91, v91
	v_lshl_add_u64 v[92:93], v[92:93], 0, v[122:123]
	v_pk_mul_f32 v[84:85], v[98:99], v[84:85] op_sel_hi:[0,1]
	v_pk_mul_f32 v[82:83], v[98:99], v[82:83] op_sel_hi:[0,1]
	v_max_f32_e32 v80, 0, v80
	v_cvt_pk_bf16_f32 v91, v94, v91
	global_store_dwordx4 v[92:93], v[88:91], off sc0 sc1 nt
	v_pk_mul_f32 v[86:87], v[98:99], v[86:87] op_sel_hi:[0,1]
	v_max_f32_e32 v84, 0, v84
	v_mul_f32_e32 v88, v80, v80
	v_max_f32_e32 v80, 0, v85
	v_max_f32_e32 v81, 0, v81
	v_max_f32_e32 v82, 0, v82
	v_mul_f32_e32 v84, v84, v84
	v_mul_f32_e32 v80, v80, v80
	v_mul_f32_e32 v85, v81, v81
	v_max_f32_e32 v81, 0, v86
	v_mul_f32_e32 v86, v82, v82
	v_max_f32_e32 v82, 0, v87
	v_mul_f32_e32 v81, v81, v81
	v_mul_f32_e32 v82, v82, v82
	v_cvt_pk_bf16_f32 v80, v84, v80
	v_fmamk_f32 v84, v228, 0x3a800000, v222
	v_cvt_pk_bf16_f32 v81, v81, v82
	v_cvt_pk_bf16_f32 v82, v88, v85
	v_mul_f32_e32 v85, 0x4b800000, v84
	v_cmp_gt_f32_e32 vcc, s67, v84
	v_max_f32_e32 v83, 0, v83
	v_mul_f32_e32 v83, v83, v83
	v_cndmask_b32_e32 v84, v84, v85, vcc
	v_rsq_f32_e32 v84, v84
	v_cvt_pk_bf16_f32 v83, v86, v83
	global_store_dwordx4 v[92:93], v[80:83], off offset:256 sc0 sc1 nt
	s_nop 1
	v_mul_f32_e32 v81, 0x45800000, v84
	v_cndmask_b32_e32 v82, v84, v81, vcc
	v_pk_mul_f32 v[74:75], v[82:83], v[74:75] op_sel_hi:[0,1]
	v_pk_mul_f32 v[72:73], v[82:83], v[72:73] op_sel_hi:[0,1]
	v_or_b32_e32 v80, 48, v208
	v_pk_mul_f32 v[78:79], v[82:83], v[78:79] op_sel_hi:[0,1]
	v_pk_mul_f32 v[76:77], v[82:83], v[76:77] op_sel_hi:[0,1]
	v_max_f32_e32 v72, 0, v72
	v_max_f32_e32 v73, 0, v73
	v_max_f32_e32 v74, 0, v74
	v_ashrrev_i32_e32 v81, 31, v80
	v_max_f32_e32 v76, 0, v76
	v_mul_f32_e32 v83, v72, v72
	v_max_f32_e32 v72, 0, v77
	v_mul_f32_e32 v77, v73, v73
	v_max_f32_e32 v73, 0, v78
	v_mul_f32_e32 v78, v74, v74
	v_max_f32_e32 v74, 0, v79
	v_lshlrev_b64 v[80:81], 13, v[80:81]
	v_mul_f32_e32 v76, v76, v76
	v_mul_f32_e32 v72, v72, v72
	v_mul_f32_e32 v73, v73, v73
	v_mul_f32_e32 v74, v74, v74
	v_max_f32_e32 v75, 0, v75
	v_cvt_pk_bf16_f32 v72, v76, v72
	v_cvt_pk_bf16_f32 v73, v73, v74
	v_cvt_pk_bf16_f32 v74, v83, v77
	v_lshl_add_u64 v[76:77], s[8:9], 0, v[80:81]
	v_pk_mul_f32 v[66:67], v[82:83], v[66:67] op_sel_hi:[0,1]
	v_pk_mul_f32 v[64:65], v[82:83], v[64:65] op_sel_hi:[0,1]
	v_mul_f32_e32 v75, v75, v75
	v_lshl_add_u64 v[76:77], v[76:77], 0, v[122:123]
	v_pk_mul_f32 v[70:71], v[82:83], v[70:71] op_sel_hi:[0,1]
	v_pk_mul_f32 v[68:69], v[82:83], v[68:69] op_sel_hi:[0,1]
	v_max_f32_e32 v64, 0, v64
	v_max_f32_e32 v65, 0, v65
	v_max_f32_e32 v66, 0, v66
	v_cvt_pk_bf16_f32 v75, v78, v75
	global_store_dwordx4 v[76:77], v[72:75], off sc0 sc1 nt
	v_max_f32_e32 v68, 0, v68
	v_mul_f32_e32 v68, v68, v68
	v_mul_f32_e32 v72, v64, v64
	v_max_f32_e32 v64, 0, v69
	v_mul_f32_e32 v69, v65, v65
	v_max_f32_e32 v65, 0, v70
	v_mul_f32_e32 v70, v66, v66
	v_max_f32_e32 v66, 0, v71
	v_mul_f32_e32 v65, v65, v65
	v_mul_f32_e32 v66, v66, v66
	v_mul_f32_e32 v64, v64, v64
	v_cvt_pk_bf16_f32 v65, v65, v66
	v_fmamk_f32 v66, v227, 0x3a800000, v222
	v_cvt_pk_bf16_f32 v64, v68, v64
	v_mul_f32_e32 v68, 0x4b800000, v66
	v_cmp_gt_f32_e32 vcc, s67, v66
	v_max_f32_e32 v67, 0, v67
	v_mul_f32_e32 v67, v67, v67
	v_cndmask_b32_e32 v66, v66, v68, vcc
	v_rsq_f32_e32 v68, v66
	v_cvt_pk_bf16_f32 v66, v72, v69
	v_cvt_pk_bf16_f32 v67, v70, v67
	global_store_dwordx4 v[76:77], v[64:67], off offset:256 sc0 sc1 nt
	s_nop 1
	v_mul_f32_e32 v64, 0x45800000, v68
	v_cndmask_b32_e32 v64, v68, v64, vcc
	v_pk_mul_f32 v[58:59], v[64:65], v[58:59] op_sel_hi:[0,1]
	v_pk_mul_f32 v[56:57], v[64:65], v[56:57] op_sel_hi:[0,1]
	v_pk_mul_f32 v[62:63], v[64:65], v[62:63] op_sel_hi:[0,1]
	v_pk_mul_f32 v[60:61], v[64:65], v[60:61] op_sel_hi:[0,1]
	v_max_f32_e32 v56, 0, v56
	v_max_f32_e32 v57, 0, v57
	v_max_f32_e32 v58, 0, v58
	v_max_f32_e32 v59, 0, v59
	v_mul_f32_e32 v65, v56, v56
	v_max_f32_e32 v56, 0, v61
	v_mul_f32_e32 v61, v57, v57
	v_max_f32_e32 v57, 0, v62
	v_mul_f32_e32 v62, v58, v58
	v_mul_f32_e32 v59, v59, v59
	v_max_f32_e32 v60, 0, v60
	v_mul_f32_e32 v56, v56, v56
	v_max_f32_e32 v58, 0, v63
	v_cvt_pk_bf16_f32 v59, v62, v59
	v_add_co_u32_e32 v62, vcc, s68, v120
	v_pk_mul_f32 v[50:51], v[64:65], v[50:51] op_sel_hi:[0,1]
	v_pk_mul_f32 v[48:49], v[64:65], v[48:49] op_sel_hi:[0,1]
	v_mul_f32_e32 v60, v60, v60
	v_mul_f32_e32 v57, v57, v57
	v_mul_f32_e32 v58, v58, v58
	v_cvt_pk_bf16_f32 v56, v60, v56
	v_addc_co_u32_e32 v63, vcc, 0, v121, vcc
	v_pk_mul_f32 v[54:55], v[64:65], v[54:55] op_sel_hi:[0,1]
	v_pk_mul_f32 v[52:53], v[64:65], v[52:53] op_sel_hi:[0,1]
	v_max_f32_e32 v48, 0, v48
	v_max_f32_e32 v49, 0, v49
	v_max_f32_e32 v50, 0, v50
	v_cvt_pk_bf16_f32 v57, v57, v58
	v_cvt_pk_bf16_f32 v58, v65, v61
	global_store_dwordx4 v[62:63], v[56:59], off sc0 sc1 nt
	v_max_f32_e32 v52, 0, v52
	v_mul_f32_e32 v52, v52, v52
	v_mul_f32_e32 v56, v48, v48
	v_max_f32_e32 v48, 0, v53
	v_mul_f32_e32 v53, v49, v49
	v_max_f32_e32 v49, 0, v54
	v_mul_f32_e32 v54, v50, v50
	v_max_f32_e32 v50, 0, v55
	v_mul_f32_e32 v49, v49, v49
	v_mul_f32_e32 v50, v50, v50
	v_mul_f32_e32 v48, v48, v48
	v_cvt_pk_bf16_f32 v49, v49, v50
	v_fmamk_f32 v50, v226, 0x3a800000, v222
	v_cvt_pk_bf16_f32 v48, v52, v48
	v_mul_f32_e32 v52, 0x4b800000, v50
	v_cmp_gt_f32_e32 vcc, s67, v50
	v_max_f32_e32 v51, 0, v51
	v_lshl_add_u64 v[60:61], v[120:121], 0, s[18:19]
	v_cndmask_b32_e32 v50, v50, v52, vcc
	v_rsq_f32_e32 v52, v50
	v_mul_f32_e32 v51, v51, v51
	v_cvt_pk_bf16_f32 v50, v56, v53
	v_cvt_pk_bf16_f32 v51, v54, v51
	global_store_dwordx4 v[60:61], v[48:51], off offset:256 sc0 sc1 nt
	s_nop 1
	v_mul_f32_e32 v48, 0x45800000, v52
	v_cndmask_b32_e32 v48, v52, v48, vcc
	v_pk_mul_f32 v[42:43], v[48:49], v[42:43] op_sel_hi:[0,1]
	v_pk_mul_f32 v[40:41], v[48:49], v[40:41] op_sel_hi:[0,1]
	v_pk_mul_f32 v[46:47], v[48:49], v[46:47] op_sel_hi:[0,1]
	v_pk_mul_f32 v[44:45], v[48:49], v[44:45] op_sel_hi:[0,1]
	v_max_f32_e32 v40, 0, v40
	v_max_f32_e32 v41, 0, v41
	v_max_f32_e32 v42, 0, v42
	v_max_f32_e32 v43, 0, v43
	v_mul_f32_e32 v49, v40, v40
	v_max_f32_e32 v40, 0, v45
	v_mul_f32_e32 v45, v41, v41
	v_max_f32_e32 v41, 0, v46
	v_mul_f32_e32 v46, v42, v42
	v_mul_f32_e32 v43, v43, v43
	v_max_f32_e32 v44, 0, v44
	v_mul_f32_e32 v40, v40, v40
	v_max_f32_e32 v42, 0, v47
	v_cvt_pk_bf16_f32 v43, v46, v43
	v_add_co_u32_e32 v46, vcc, s69, v120
	v_pk_mul_f32 v[34:35], v[48:49], v[34:35] op_sel_hi:[0,1]
	v_pk_mul_f32 v[32:33], v[48:49], v[32:33] op_sel_hi:[0,1]
	v_mul_f32_e32 v44, v44, v44
	v_mul_f32_e32 v41, v41, v41
	v_mul_f32_e32 v42, v42, v42
	v_cvt_pk_bf16_f32 v40, v44, v40
	v_addc_co_u32_e32 v47, vcc, 0, v121, vcc
	v_pk_mul_f32 v[38:39], v[48:49], v[38:39] op_sel_hi:[0,1]
	v_pk_mul_f32 v[36:37], v[48:49], v[36:37] op_sel_hi:[0,1]
	v_max_f32_e32 v32, 0, v32
	v_max_f32_e32 v33, 0, v33
	v_max_f32_e32 v34, 0, v34
	v_cvt_pk_bf16_f32 v41, v41, v42
	v_cvt_pk_bf16_f32 v42, v49, v45
	global_store_dwordx4 v[46:47], v[40:43], off sc0 sc1 nt
	v_max_f32_e32 v36, 0, v36
	v_mul_f32_e32 v36, v36, v36
	v_mul_f32_e32 v40, v32, v32
	v_max_f32_e32 v32, 0, v37
	v_mul_f32_e32 v37, v33, v33
	v_max_f32_e32 v33, 0, v38
	v_mul_f32_e32 v38, v34, v34
	v_max_f32_e32 v34, 0, v39
	v_mul_f32_e32 v33, v33, v33
	v_mul_f32_e32 v34, v34, v34
	v_mul_f32_e32 v32, v32, v32
	v_cvt_pk_bf16_f32 v33, v33, v34
	v_fmamk_f32 v34, v225, 0x3a800000, v222
	v_cvt_pk_bf16_f32 v32, v36, v32
	v_mul_f32_e32 v36, 0x4b800000, v34
	v_cmp_gt_f32_e32 vcc, s67, v34
	v_max_f32_e32 v35, 0, v35
	v_lshl_add_u64 v[44:45], v[120:121], 0, s[20:21]
	v_cndmask_b32_e32 v34, v34, v36, vcc
	v_rsq_f32_e32 v36, v34
	v_mul_f32_e32 v35, v35, v35
	v_cvt_pk_bf16_f32 v34, v40, v37
	v_cvt_pk_bf16_f32 v35, v38, v35
	global_store_dwordx4 v[44:45], v[32:35], off offset:256 sc0 sc1 nt
	s_nop 1
	v_mul_f32_e32 v32, 0x45800000, v36
	v_cndmask_b32_e32 v32, v36, v32, vcc
	v_pk_mul_f32 v[26:27], v[32:33], v[26:27] op_sel_hi:[0,1]
	v_pk_mul_f32 v[24:25], v[32:33], v[24:25] op_sel_hi:[0,1]
	v_pk_mul_f32 v[30:31], v[32:33], v[30:31] op_sel_hi:[0,1]
	v_pk_mul_f32 v[28:29], v[32:33], v[28:29] op_sel_hi:[0,1]
	v_max_f32_e32 v24, 0, v24
	v_max_f32_e32 v25, 0, v25
	v_max_f32_e32 v26, 0, v26
	v_max_f32_e32 v27, 0, v27
	v_mul_f32_e32 v33, v24, v24
	v_max_f32_e32 v24, 0, v29
	v_mul_f32_e32 v29, v25, v25
	v_max_f32_e32 v25, 0, v30
	v_mul_f32_e32 v30, v26, v26
	v_mul_f32_e32 v27, v27, v27
	v_max_f32_e32 v28, 0, v28
	v_mul_f32_e32 v24, v24, v24
	v_max_f32_e32 v26, 0, v31
	v_cvt_pk_bf16_f32 v27, v30, v27
	v_add_co_u32_e32 v30, vcc, s76, v120
	v_pk_mul_f32 v[18:19], v[32:33], v[18:19] op_sel_hi:[0,1]
	v_pk_mul_f32 v[16:17], v[32:33], v[16:17] op_sel_hi:[0,1]
	v_mul_f32_e32 v28, v28, v28
	v_mul_f32_e32 v25, v25, v25
	v_mul_f32_e32 v26, v26, v26
	v_cvt_pk_bf16_f32 v24, v28, v24
	v_addc_co_u32_e32 v31, vcc, 0, v121, vcc
	v_pk_mul_f32 v[22:23], v[32:33], v[22:23] op_sel_hi:[0,1]
	v_pk_mul_f32 v[20:21], v[32:33], v[20:21] op_sel_hi:[0,1]
	v_max_f32_e32 v16, 0, v16
	v_max_f32_e32 v17, 0, v17
	v_max_f32_e32 v18, 0, v18
	v_cvt_pk_bf16_f32 v25, v25, v26
	v_cvt_pk_bf16_f32 v26, v33, v29
	global_store_dwordx4 v[30:31], v[24:27], off sc0 sc1 nt
	v_max_f32_e32 v20, 0, v20
	v_mul_f32_e32 v20, v20, v20
	v_mul_f32_e32 v24, v16, v16
	v_max_f32_e32 v16, 0, v21
	v_mul_f32_e32 v21, v17, v17
	v_max_f32_e32 v17, 0, v22
	v_mul_f32_e32 v22, v18, v18
	v_max_f32_e32 v18, 0, v23
	v_mul_f32_e32 v17, v17, v17
	v_mul_f32_e32 v18, v18, v18
	v_mul_f32_e32 v16, v16, v16
	v_cvt_pk_bf16_f32 v17, v17, v18
	v_fmamk_f32 v18, v224, 0x3a800000, v222
	v_cvt_pk_bf16_f32 v16, v20, v16
	v_mul_f32_e32 v20, 0x4b800000, v18
	v_cmp_gt_f32_e32 vcc, s67, v18
	v_max_f32_e32 v19, 0, v19
	v_lshl_add_u64 v[28:29], v[120:121], 0, s[22:23]
	v_cndmask_b32_e32 v18, v18, v20, vcc
	v_rsq_f32_e32 v20, v18
	v_mul_f32_e32 v19, v19, v19
	v_cvt_pk_bf16_f32 v18, v24, v21
	v_cvt_pk_bf16_f32 v19, v22, v19
	global_store_dwordx4 v[28:29], v[16:19], off offset:256 sc0 sc1 nt
	s_nop 1
	v_mul_f32_e32 v16, 0x45800000, v20
	v_cndmask_b32_e32 v16, v20, v16, vcc
	v_pk_mul_f32 v[10:11], v[16:17], v[10:11] op_sel_hi:[0,1]
	v_pk_mul_f32 v[8:9], v[16:17], v[8:9] op_sel_hi:[0,1]
	v_pk_mul_f32 v[14:15], v[16:17], v[14:15] op_sel_hi:[0,1]
	v_pk_mul_f32 v[12:13], v[16:17], v[12:13] op_sel_hi:[0,1]
	v_max_f32_e32 v8, 0, v8
	v_max_f32_e32 v9, 0, v9
	v_max_f32_e32 v10, 0, v10
	v_max_f32_e32 v11, 0, v11
	v_mul_f32_e32 v17, v8, v8
	v_max_f32_e32 v8, 0, v13
	v_mul_f32_e32 v13, v9, v9
	v_max_f32_e32 v9, 0, v14
	v_mul_f32_e32 v14, v10, v10
	v_mul_f32_e32 v11, v11, v11
	v_max_f32_e32 v12, 0, v12
	v_mul_f32_e32 v8, v8, v8
	v_max_f32_e32 v10, 0, v15
	v_cvt_pk_bf16_f32 v11, v14, v11
	v_add_co_u32_e32 v14, vcc, s77, v120
	v_pk_mul_f32 v[2:3], v[16:17], v[2:3] op_sel_hi:[0,1]
	v_pk_mul_f32 v[0:1], v[16:17], v[0:1] op_sel_hi:[0,1]
	v_mul_f32_e32 v12, v12, v12
	v_mul_f32_e32 v9, v9, v9
	v_mul_f32_e32 v10, v10, v10
	v_cvt_pk_bf16_f32 v8, v12, v8
	v_addc_co_u32_e32 v15, vcc, 0, v121, vcc
	v_pk_mul_f32 v[6:7], v[16:17], v[6:7] op_sel_hi:[0,1]
	v_pk_mul_f32 v[4:5], v[16:17], v[4:5] op_sel_hi:[0,1]
	v_max_f32_e32 v0, 0, v0
	v_max_f32_e32 v1, 0, v1
	v_max_f32_e32 v2, 0, v2
	v_cvt_pk_bf16_f32 v9, v9, v10
	v_cvt_pk_bf16_f32 v10, v17, v13
	global_store_dwordx4 v[14:15], v[8:11], off sc0 sc1 nt
	v_max_f32_e32 v3, 0, v3
	v_lshl_add_u64 v[12:13], v[120:121], 0, s[24:25]
	v_mul_f32_e32 v8, v0, v0
	v_max_f32_e32 v0, 0, v5
	v_mul_f32_e32 v5, v1, v1
	v_max_f32_e32 v1, 0, v6
	v_mul_f32_e32 v6, v2, v2
	v_max_f32_e32 v2, 0, v7
	v_max_f32_e32 v4, 0, v4
	v_mul_f32_e32 v0, v0, v0
	v_mul_f32_e32 v1, v1, v1
	v_mul_f32_e32 v2, v2, v2
	v_mul_f32_e32 v3, v3, v3
	s_andn2_b64 vcc, exec, s[36:37]
	s_mov_b64 s[36:37], -1
	v_mul_f32_e32 v4, v4, v4
	v_cvt_pk_bf16_f32 v0, v4, v0
	v_cvt_pk_bf16_f32 v1, v1, v2
	v_cvt_pk_bf16_f32 v2, v8, v5
	v_cvt_pk_bf16_f32 v3, v6, v3
	global_store_dwordx4 v[12:13], v[0:3], off offset:256 sc0 sc1 nt
	s_cbranch_vccnz .LBB0_830
	s_andn2_b64 vcc, exec, s[4:5]
	s_cbranch_vccnz .LBB0_829
	s_barrier
	s_branch .LBB0_829

.LBB0_1298:
	s_waitcnt vmcnt(0)
	v_fmamk_f32 v128, v231, 0x3a800000, v222
	v_mul_f32_e32 v129, 0x4b800000, v128
	v_cmp_gt_f32_e32 vcc, s69, v128
	v_lshlrev_b64 v[132:133], 13, v[208:209]
	s_nop 0
	v_cndmask_b32_e32 v128, v128, v129, vcc
	v_rsq_f32_e32 v130, v128
	v_lshl_or_b32 v128, s80, 8, v221
	v_ashrrev_i32_e32 v129, 31, v128
	v_mul_f32_e32 v131, 0x45800000, v130
	v_cndmask_b32_e32 v130, v130, v131, vcc
	v_pk_mul_f32 v[126:127], v[130:131], v[126:127] op_sel_hi:[0,1]
	v_pk_mul_f32 v[124:125], v[130:131], v[124:125] op_sel_hi:[0,1]
	v_pk_mul_f32 v[122:123], v[130:131], v[122:123] op_sel_hi:[0,1]
	v_pk_mul_f32 v[120:121], v[130:131], v[120:121] op_sel_hi:[0,1]
	v_max_f32_e32 v124, 0, v124
	v_max_f32_e32 v120, 0, v120
	v_max_f32_e32 v125, 0, v125
	v_max_f32_e32 v121, 0, v121
	v_max_f32_e32 v126, 0, v126
	v_max_f32_e32 v122, 0, v122
	v_max_f32_e32 v127, 0, v127
	v_max_f32_e32 v123, 0, v123
	v_mul_f32_e32 v124, v124, v124
	v_mul_f32_e32 v120, v120, v120
	v_mul_f32_e32 v125, v125, v125
	v_mul_f32_e32 v121, v121, v121
	v_mul_f32_e32 v126, v126, v126
	v_mul_f32_e32 v122, v122, v122
	v_mul_f32_e32 v127, v127, v127
	v_mul_f32_e32 v123, v123, v123
	v_cvt_pk_bf16_f32 v124, v124, v125
	v_cvt_pk_bf16_f32 v125, v126, v127
	v_cvt_pk_bf16_f32 v126, v120, v121
	v_cvt_pk_bf16_f32 v127, v122, v123
	v_lshl_add_u64 v[120:121], s[8:9], 0, v[132:133]
	v_lshlrev_b64 v[122:123], 1, v[128:129]
	v_pk_mul_f32 v[112:113], v[130:131], v[112:113] op_sel_hi:[0,1]
	v_lshl_add_u64 v[120:121], v[120:121], 0, v[122:123]
	v_pk_mul_f32 v[116:117], v[130:131], v[116:117] op_sel_hi:[0,1]
	v_pk_mul_f32 v[114:115], v[130:131], v[114:115] op_sel_hi:[0,1]
	v_max_f32_e32 v112, 0, v112
	global_store_dwordx4 v[120:121], v[124:127], off sc0 sc1 nt
	v_pk_mul_f32 v[118:119], v[130:131], v[118:119] op_sel_hi:[0,1]
	v_max_f32_e32 v116, 0, v116
	v_mul_f32_e32 v124, v112, v112
	v_max_f32_e32 v112, 0, v117
	v_max_f32_e32 v113, 0, v113
	v_max_f32_e32 v114, 0, v114
	v_mul_f32_e32 v116, v116, v116
	v_mul_f32_e32 v112, v112, v112
	v_mul_f32_e32 v117, v113, v113
	v_max_f32_e32 v113, 0, v118
	v_mul_f32_e32 v118, v114, v114
	v_max_f32_e32 v114, 0, v119
	v_mul_f32_e32 v113, v113, v113
	v_mul_f32_e32 v114, v114, v114
	v_cvt_pk_bf16_f32 v112, v116, v112
	v_fmamk_f32 v116, v230, 0x3a800000, v222
	v_cvt_pk_bf16_f32 v113, v113, v114
	v_cvt_pk_bf16_f32 v114, v124, v117
	v_mul_f32_e32 v117, 0x4b800000, v116
	v_cmp_gt_f32_e32 vcc, s69, v116
	v_max_f32_e32 v115, 0, v115
	v_mul_f32_e32 v115, v115, v115
	v_cndmask_b32_e32 v116, v116, v117, vcc
	v_rsq_f32_e32 v116, v116
	v_cvt_pk_bf16_f32 v115, v118, v115
	global_store_dwordx4 v[120:121], v[112:115], off offset:256 sc0 sc1 nt
	s_nop 1
	v_mul_f32_e32 v113, 0x45800000, v116
	v_cndmask_b32_e32 v114, v116, v113, vcc
	v_pk_mul_f32 v[106:107], v[114:115], v[106:107] op_sel_hi:[0,1]
	v_pk_mul_f32 v[104:105], v[114:115], v[104:105] op_sel_hi:[0,1]
	v_or_b32_e32 v112, 16, v208
	v_pk_mul_f32 v[110:111], v[114:115], v[110:111] op_sel_hi:[0,1]
	v_pk_mul_f32 v[108:109], v[114:115], v[108:109] op_sel_hi:[0,1]
	v_max_f32_e32 v104, 0, v104
	v_max_f32_e32 v105, 0, v105
	v_max_f32_e32 v106, 0, v106
	v_ashrrev_i32_e32 v113, 31, v112
	v_max_f32_e32 v108, 0, v108
	v_mul_f32_e32 v115, v104, v104
	v_max_f32_e32 v104, 0, v109
	v_mul_f32_e32 v109, v105, v105
	v_max_f32_e32 v105, 0, v110
	v_mul_f32_e32 v110, v106, v106
	v_max_f32_e32 v106, 0, v111
	v_lshlrev_b64 v[112:113], 13, v[112:113]
	v_mul_f32_e32 v108, v108, v108
	v_mul_f32_e32 v104, v104, v104
	v_mul_f32_e32 v105, v105, v105
	v_mul_f32_e32 v106, v106, v106
	v_max_f32_e32 v107, 0, v107
	v_cvt_pk_bf16_f32 v104, v108, v104
	v_cvt_pk_bf16_f32 v105, v105, v106
	v_cvt_pk_bf16_f32 v106, v115, v109
	v_lshl_add_u64 v[108:109], s[8:9], 0, v[112:113]
	v_pk_mul_f32 v[96:97], v[114:115], v[96:97] op_sel_hi:[0,1]
	v_mul_f32_e32 v107, v107, v107
	v_lshl_add_u64 v[108:109], v[108:109], 0, v[122:123]
	v_pk_mul_f32 v[100:101], v[114:115], v[100:101] op_sel_hi:[0,1]
	v_pk_mul_f32 v[98:99], v[114:115], v[98:99] op_sel_hi:[0,1]
	v_max_f32_e32 v96, 0, v96
	v_cvt_pk_bf16_f32 v107, v110, v107
	global_store_dwordx4 v[108:109], v[104:107], off sc0 sc1 nt
	v_pk_mul_f32 v[102:103], v[114:115], v[102:103] op_sel_hi:[0,1]
	v_max_f32_e32 v100, 0, v100
	v_mul_f32_e32 v104, v96, v96
	v_max_f32_e32 v96, 0, v101
	v_max_f32_e32 v97, 0, v97
	v_max_f32_e32 v98, 0, v98
	v_mul_f32_e32 v100, v100, v100
	v_mul_f32_e32 v96, v96, v96
	v_mul_f32_e32 v101, v97, v97
	v_max_f32_e32 v97, 0, v102
	v_mul_f32_e32 v102, v98, v98
	v_max_f32_e32 v98, 0, v103
	v_mul_f32_e32 v97, v97, v97
	v_mul_f32_e32 v98, v98, v98
	v_cvt_pk_bf16_f32 v96, v100, v96
	v_fmamk_f32 v100, v229, 0x3a800000, v222
	v_cvt_pk_bf16_f32 v97, v97, v98
	v_cvt_pk_bf16_f32 v98, v104, v101
	v_mul_f32_e32 v101, 0x4b800000, v100
	v_cmp_gt_f32_e32 vcc, s69, v100
	v_max_f32_e32 v99, 0, v99
	v_mul_f32_e32 v99, v99, v99
	v_cndmask_b32_e32 v100, v100, v101, vcc
	v_rsq_f32_e32 v100, v100
	v_cvt_pk_bf16_f32 v99, v102, v99
	global_store_dwordx4 v[108:109], v[96:99], off offset:256 sc0 sc1 nt
	s_nop 1
	v_mul_f32_e32 v97, 0x45800000, v100
	v_cndmask_b32_e32 v98, v100, v97, vcc
	v_pk_mul_f32 v[90:91], v[98:99], v[90:91] op_sel_hi:[0,1]
	v_pk_mul_f32 v[88:89], v[98:99], v[88:89] op_sel_hi:[0,1]
	v_or_b32_e32 v96, 32, v208
	v_pk_mul_f32 v[94:95], v[98:99], v[94:95] op_sel_hi:[0,1]
	v_pk_mul_f32 v[92:93], v[98:99], v[92:93] op_sel_hi:[0,1]
	v_max_f32_e32 v88, 0, v88
	v_max_f32_e32 v89, 0, v89
	v_max_f32_e32 v90, 0, v90
	v_ashrrev_i32_e32 v97, 31, v96
	v_max_f32_e32 v92, 0, v92
	v_mul_f32_e32 v99, v88, v88
	v_max_f32_e32 v88, 0, v93
	v_mul_f32_e32 v93, v89, v89
	v_max_f32_e32 v89, 0, v94
	v_mul_f32_e32 v94, v90, v90
	v_max_f32_e32 v90, 0, v95
	v_lshlrev_b64 v[96:97], 13, v[96:97]
	v_mul_f32_e32 v92, v92, v92
	v_mul_f32_e32 v88, v88, v88
	v_mul_f32_e32 v89, v89, v89
	v_mul_f32_e32 v90, v90, v90
	v_max_f32_e32 v91, 0, v91
	v_cvt_pk_bf16_f32 v88, v92, v88
	v_cvt_pk_bf16_f32 v89, v89, v90
	v_cvt_pk_bf16_f32 v90, v99, v93
	v_lshl_add_u64 v[92:93], s[8:9], 0, v[96:97]
	v_pk_mul_f32 v[80:81], v[98:99], v[80:81] op_sel_hi:[0,1]
	v_mul_f32_e32 v91, v91, v91
	v_lshl_add_u64 v[92:93], v[92:93], 0, v[122:123]
	v_pk_mul_f32 v[84:85], v[98:99], v[84:85] op_sel_hi:[0,1]
	v_pk_mul_f32 v[82:83], v[98:99], v[82:83] op_sel_hi:[0,1]
	v_max_f32_e32 v80, 0, v80
	v_cvt_pk_bf16_f32 v91, v94, v91
	global_store_dwordx4 v[92:93], v[88:91], off sc0 sc1 nt
	v_pk_mul_f32 v[86:87], v[98:99], v[86:87] op_sel_hi:[0,1]
	v_max_f32_e32 v84, 0, v84
	v_mul_f32_e32 v88, v80, v80
	v_max_f32_e32 v80, 0, v85
	v_max_f32_e32 v81, 0, v81
	v_max_f32_e32 v82, 0, v82
	v_mul_f32_e32 v84, v84, v84
	v_mul_f32_e32 v80, v80, v80
	v_mul_f32_e32 v85, v81, v81
	v_max_f32_e32 v81, 0, v86
	v_mul_f32_e32 v86, v82, v82
	v_max_f32_e32 v82, 0, v87
	v_mul_f32_e32 v81, v81, v81
	v_mul_f32_e32 v82, v82, v82
	v_cvt_pk_bf16_f32 v80, v84, v80
	v_fmamk_f32 v84, v228, 0x3a800000, v222
	v_cvt_pk_bf16_f32 v81, v81, v82
	v_cvt_pk_bf16_f32 v82, v88, v85
	v_mul_f32_e32 v85, 0x4b800000, v84
	v_cmp_gt_f32_e32 vcc, s69, v84
	v_max_f32_e32 v83, 0, v83
	v_mul_f32_e32 v83, v83, v83
	v_cndmask_b32_e32 v84, v84, v85, vcc
	v_rsq_f32_e32 v84, v84
	v_cvt_pk_bf16_f32 v83, v86, v83
	global_store_dwordx4 v[92:93], v[80:83], off offset:256 sc0 sc1 nt
	s_nop 1
	v_mul_f32_e32 v81, 0x45800000, v84
	v_cndmask_b32_e32 v82, v84, v81, vcc
	v_pk_mul_f32 v[74:75], v[82:83], v[74:75] op_sel_hi:[0,1]
	v_pk_mul_f32 v[72:73], v[82:83], v[72:73] op_sel_hi:[0,1]
	v_or_b32_e32 v80, 48, v208
	v_pk_mul_f32 v[78:79], v[82:83], v[78:79] op_sel_hi:[0,1]
	v_pk_mul_f32 v[76:77], v[82:83], v[76:77] op_sel_hi:[0,1]
	v_max_f32_e32 v72, 0, v72
	v_max_f32_e32 v73, 0, v73
	v_max_f32_e32 v74, 0, v74
	v_ashrrev_i32_e32 v81, 31, v80
	v_max_f32_e32 v76, 0, v76
	v_mul_f32_e32 v83, v72, v72
	v_max_f32_e32 v72, 0, v77
	v_mul_f32_e32 v77, v73, v73
	v_max_f32_e32 v73, 0, v78
	v_mul_f32_e32 v78, v74, v74
	v_max_f32_e32 v74, 0, v79
	v_lshlrev_b64 v[80:81], 13, v[80:81]
	v_mul_f32_e32 v76, v76, v76
	v_mul_f32_e32 v72, v72, v72
	v_mul_f32_e32 v73, v73, v73
	v_mul_f32_e32 v74, v74, v74
	v_max_f32_e32 v75, 0, v75
	v_cvt_pk_bf16_f32 v72, v76, v72
	v_cvt_pk_bf16_f32 v73, v73, v74
	v_cvt_pk_bf16_f32 v74, v83, v77
	v_lshl_add_u64 v[76:77], s[8:9], 0, v[80:81]
	v_pk_mul_f32 v[66:67], v[82:83], v[66:67] op_sel_hi:[0,1]
	v_pk_mul_f32 v[64:65], v[82:83], v[64:65] op_sel_hi:[0,1]
	v_mul_f32_e32 v75, v75, v75
	v_lshl_add_u64 v[76:77], v[76:77], 0, v[122:123]
	v_pk_mul_f32 v[70:71], v[82:83], v[70:71] op_sel_hi:[0,1]
	v_pk_mul_f32 v[68:69], v[82:83], v[68:69] op_sel_hi:[0,1]
	v_max_f32_e32 v64, 0, v64
	v_max_f32_e32 v65, 0, v65
	v_max_f32_e32 v66, 0, v66
	v_cvt_pk_bf16_f32 v75, v78, v75
	global_store_dwordx4 v[76:77], v[72:75], off sc0 sc1 nt
	v_max_f32_e32 v68, 0, v68
	v_mul_f32_e32 v68, v68, v68
	v_mul_f32_e32 v72, v64, v64
	v_max_f32_e32 v64, 0, v69
	v_mul_f32_e32 v69, v65, v65
	v_max_f32_e32 v65, 0, v70
	v_mul_f32_e32 v70, v66, v66
	v_max_f32_e32 v66, 0, v71
	v_mul_f32_e32 v65, v65, v65
	v_mul_f32_e32 v66, v66, v66
	v_mul_f32_e32 v64, v64, v64
	v_cvt_pk_bf16_f32 v65, v65, v66
	v_fmamk_f32 v66, v227, 0x3a800000, v222
	v_cvt_pk_bf16_f32 v64, v68, v64
	v_mul_f32_e32 v68, 0x4b800000, v66
	v_cmp_gt_f32_e32 vcc, s69, v66
	v_max_f32_e32 v67, 0, v67
	v_mul_f32_e32 v67, v67, v67
	v_cndmask_b32_e32 v66, v66, v68, vcc
	v_rsq_f32_e32 v68, v66
	v_cvt_pk_bf16_f32 v66, v72, v69
	v_cvt_pk_bf16_f32 v67, v70, v67
	global_store_dwordx4 v[76:77], v[64:67], off offset:256 sc0 sc1 nt
	s_nop 1
	v_mul_f32_e32 v64, 0x45800000, v68
	v_cndmask_b32_e32 v64, v68, v64, vcc
	v_pk_mul_f32 v[58:59], v[64:65], v[58:59] op_sel_hi:[0,1]
	v_pk_mul_f32 v[56:57], v[64:65], v[56:57] op_sel_hi:[0,1]
	v_pk_mul_f32 v[62:63], v[64:65], v[62:63] op_sel_hi:[0,1]
	v_pk_mul_f32 v[60:61], v[64:65], v[60:61] op_sel_hi:[0,1]
	v_max_f32_e32 v56, 0, v56
	v_max_f32_e32 v57, 0, v57
	v_max_f32_e32 v58, 0, v58
	v_max_f32_e32 v59, 0, v59
	v_mul_f32_e32 v65, v56, v56
	v_max_f32_e32 v56, 0, v61
	v_mul_f32_e32 v61, v57, v57
	v_max_f32_e32 v57, 0, v62
	v_mul_f32_e32 v62, v58, v58
	v_mul_f32_e32 v59, v59, v59
	v_max_f32_e32 v60, 0, v60
	v_mul_f32_e32 v56, v56, v56
	v_max_f32_e32 v58, 0, v63
	v_cvt_pk_bf16_f32 v59, v62, v59
	v_add_co_u32_e32 v62, vcc, s76, v120
	v_pk_mul_f32 v[50:51], v[64:65], v[50:51] op_sel_hi:[0,1]
	v_pk_mul_f32 v[48:49], v[64:65], v[48:49] op_sel_hi:[0,1]
	v_mul_f32_e32 v60, v60, v60
	v_mul_f32_e32 v57, v57, v57
	v_mul_f32_e32 v58, v58, v58
	v_cvt_pk_bf16_f32 v56, v60, v56
	v_addc_co_u32_e32 v63, vcc, 0, v121, vcc
	v_pk_mul_f32 v[54:55], v[64:65], v[54:55] op_sel_hi:[0,1]
	v_pk_mul_f32 v[52:53], v[64:65], v[52:53] op_sel_hi:[0,1]
	v_max_f32_e32 v48, 0, v48
	v_max_f32_e32 v49, 0, v49
	v_max_f32_e32 v50, 0, v50
	v_cvt_pk_bf16_f32 v57, v57, v58
	v_cvt_pk_bf16_f32 v58, v65, v61
	global_store_dwordx4 v[62:63], v[56:59], off sc0 sc1 nt
	v_max_f32_e32 v52, 0, v52
	v_mul_f32_e32 v52, v52, v52
	v_mul_f32_e32 v56, v48, v48
	v_max_f32_e32 v48, 0, v53
	v_mul_f32_e32 v53, v49, v49
	v_max_f32_e32 v49, 0, v54
	v_mul_f32_e32 v54, v50, v50
	v_max_f32_e32 v50, 0, v55
	v_mul_f32_e32 v49, v49, v49
	v_mul_f32_e32 v50, v50, v50
	v_mul_f32_e32 v48, v48, v48
	v_cvt_pk_bf16_f32 v49, v49, v50
	v_fmamk_f32 v50, v226, 0x3a800000, v222
	v_cvt_pk_bf16_f32 v48, v52, v48
	v_mul_f32_e32 v52, 0x4b800000, v50
	v_cmp_gt_f32_e32 vcc, s69, v50
	v_max_f32_e32 v51, 0, v51
	v_lshl_add_u64 v[60:61], v[120:121], 0, s[20:21]
	v_cndmask_b32_e32 v50, v50, v52, vcc
	v_rsq_f32_e32 v52, v50
	v_mul_f32_e32 v51, v51, v51
	v_cvt_pk_bf16_f32 v50, v56, v53
	v_cvt_pk_bf16_f32 v51, v54, v51
	global_store_dwordx4 v[60:61], v[48:51], off offset:256 sc0 sc1 nt
	s_nop 1
	v_mul_f32_e32 v48, 0x45800000, v52
	v_cndmask_b32_e32 v48, v52, v48, vcc
	v_pk_mul_f32 v[42:43], v[48:49], v[42:43] op_sel_hi:[0,1]
	v_pk_mul_f32 v[40:41], v[48:49], v[40:41] op_sel_hi:[0,1]
	v_pk_mul_f32 v[46:47], v[48:49], v[46:47] op_sel_hi:[0,1]
	v_pk_mul_f32 v[44:45], v[48:49], v[44:45] op_sel_hi:[0,1]
	v_max_f32_e32 v40, 0, v40
	v_max_f32_e32 v41, 0, v41
	v_max_f32_e32 v42, 0, v42
	v_max_f32_e32 v43, 0, v43
	v_mul_f32_e32 v49, v40, v40
	v_max_f32_e32 v40, 0, v45
	v_mul_f32_e32 v45, v41, v41
	v_max_f32_e32 v41, 0, v46
	v_mul_f32_e32 v46, v42, v42
	v_mul_f32_e32 v43, v43, v43
	v_max_f32_e32 v44, 0, v44
	v_mul_f32_e32 v40, v40, v40
	v_max_f32_e32 v42, 0, v47
	v_cvt_pk_bf16_f32 v43, v46, v43
	v_add_co_u32_e32 v46, vcc, s77, v120
	v_pk_mul_f32 v[34:35], v[48:49], v[34:35] op_sel_hi:[0,1]
	v_pk_mul_f32 v[32:33], v[48:49], v[32:33] op_sel_hi:[0,1]
	v_mul_f32_e32 v44, v44, v44
	v_mul_f32_e32 v41, v41, v41
	v_mul_f32_e32 v42, v42, v42
	v_cvt_pk_bf16_f32 v40, v44, v40
	v_addc_co_u32_e32 v47, vcc, 0, v121, vcc
	v_pk_mul_f32 v[38:39], v[48:49], v[38:39] op_sel_hi:[0,1]
	v_pk_mul_f32 v[36:37], v[48:49], v[36:37] op_sel_hi:[0,1]
	v_max_f32_e32 v32, 0, v32
	v_max_f32_e32 v33, 0, v33
	v_max_f32_e32 v34, 0, v34
	v_cvt_pk_bf16_f32 v41, v41, v42
	v_cvt_pk_bf16_f32 v42, v49, v45
	global_store_dwordx4 v[46:47], v[40:43], off sc0 sc1 nt
	v_max_f32_e32 v36, 0, v36
	v_mul_f32_e32 v36, v36, v36
	v_mul_f32_e32 v40, v32, v32
	v_max_f32_e32 v32, 0, v37
	v_mul_f32_e32 v37, v33, v33
	v_max_f32_e32 v33, 0, v38
	v_mul_f32_e32 v38, v34, v34
	v_max_f32_e32 v34, 0, v39
	v_mul_f32_e32 v33, v33, v33
	v_mul_f32_e32 v34, v34, v34
	v_mul_f32_e32 v32, v32, v32
	v_cvt_pk_bf16_f32 v33, v33, v34
	v_fmamk_f32 v34, v225, 0x3a800000, v222
	v_cvt_pk_bf16_f32 v32, v36, v32
	v_mul_f32_e32 v36, 0x4b800000, v34
	v_cmp_gt_f32_e32 vcc, s69, v34
	v_max_f32_e32 v35, 0, v35
	v_lshl_add_u64 v[44:45], v[120:121], 0, s[22:23]
	v_cndmask_b32_e32 v34, v34, v36, vcc
	v_rsq_f32_e32 v36, v34
	v_mul_f32_e32 v35, v35, v35
	v_cvt_pk_bf16_f32 v34, v40, v37
	v_cvt_pk_bf16_f32 v35, v38, v35
	global_store_dwordx4 v[44:45], v[32:35], off offset:256 sc0 sc1 nt
	s_nop 1
	v_mul_f32_e32 v32, 0x45800000, v36
	v_cndmask_b32_e32 v32, v36, v32, vcc
	v_pk_mul_f32 v[26:27], v[32:33], v[26:27] op_sel_hi:[0,1]
	v_pk_mul_f32 v[24:25], v[32:33], v[24:25] op_sel_hi:[0,1]
	v_pk_mul_f32 v[30:31], v[32:33], v[30:31] op_sel_hi:[0,1]
	v_pk_mul_f32 v[28:29], v[32:33], v[28:29] op_sel_hi:[0,1]
	v_max_f32_e32 v24, 0, v24
	v_max_f32_e32 v25, 0, v25
	v_max_f32_e32 v26, 0, v26
	v_max_f32_e32 v27, 0, v27
	v_mul_f32_e32 v33, v24, v24
	v_max_f32_e32 v24, 0, v29
	v_mul_f32_e32 v29, v25, v25
	v_max_f32_e32 v25, 0, v30
	v_mul_f32_e32 v30, v26, v26
	v_mul_f32_e32 v27, v27, v27
	v_max_f32_e32 v28, 0, v28
	v_mul_f32_e32 v24, v24, v24
	v_max_f32_e32 v26, 0, v31
	v_cvt_pk_bf16_f32 v27, v30, v27
	v_add_co_u32_e32 v30, vcc, s78, v120
	v_pk_mul_f32 v[18:19], v[32:33], v[18:19] op_sel_hi:[0,1]
	v_pk_mul_f32 v[16:17], v[32:33], v[16:17] op_sel_hi:[0,1]
	v_mul_f32_e32 v28, v28, v28
	v_mul_f32_e32 v25, v25, v25
	v_mul_f32_e32 v26, v26, v26
	v_cvt_pk_bf16_f32 v24, v28, v24
	v_addc_co_u32_e32 v31, vcc, 0, v121, vcc
	v_pk_mul_f32 v[22:23], v[32:33], v[22:23] op_sel_hi:[0,1]
	v_pk_mul_f32 v[20:21], v[32:33], v[20:21] op_sel_hi:[0,1]
	v_max_f32_e32 v16, 0, v16
	v_max_f32_e32 v17, 0, v17
	v_max_f32_e32 v18, 0, v18
	v_cvt_pk_bf16_f32 v25, v25, v26
	v_cvt_pk_bf16_f32 v26, v33, v29
	global_store_dwordx4 v[30:31], v[24:27], off sc0 sc1 nt
	v_max_f32_e32 v20, 0, v20
	v_mul_f32_e32 v20, v20, v20
	v_mul_f32_e32 v24, v16, v16
	v_max_f32_e32 v16, 0, v21
	v_mul_f32_e32 v21, v17, v17
	v_max_f32_e32 v17, 0, v22
	v_mul_f32_e32 v22, v18, v18
	v_max_f32_e32 v18, 0, v23
	v_mul_f32_e32 v17, v17, v17
	v_mul_f32_e32 v18, v18, v18
	v_mul_f32_e32 v16, v16, v16
	v_cvt_pk_bf16_f32 v17, v17, v18
	v_fmamk_f32 v18, v224, 0x3a800000, v222
	v_cvt_pk_bf16_f32 v16, v20, v16
	v_mul_f32_e32 v20, 0x4b800000, v18
	v_cmp_gt_f32_e32 vcc, s69, v18
	v_max_f32_e32 v19, 0, v19
	v_lshl_add_u64 v[28:29], v[120:121], 0, s[24:25]
	v_cndmask_b32_e32 v18, v18, v20, vcc
	v_rsq_f32_e32 v20, v18
	v_mul_f32_e32 v19, v19, v19
	v_cvt_pk_bf16_f32 v18, v24, v21
	v_cvt_pk_bf16_f32 v19, v22, v19
	global_store_dwordx4 v[28:29], v[16:19], off offset:256 sc0 sc1 nt
	s_nop 1
	v_mul_f32_e32 v16, 0x45800000, v20
	v_cndmask_b32_e32 v16, v20, v16, vcc
	v_pk_mul_f32 v[10:11], v[16:17], v[10:11] op_sel_hi:[0,1]
	v_pk_mul_f32 v[8:9], v[16:17], v[8:9] op_sel_hi:[0,1]
	v_pk_mul_f32 v[14:15], v[16:17], v[14:15] op_sel_hi:[0,1]
	v_pk_mul_f32 v[12:13], v[16:17], v[12:13] op_sel_hi:[0,1]
	v_max_f32_e32 v8, 0, v8
	v_max_f32_e32 v9, 0, v9
	v_max_f32_e32 v10, 0, v10
	v_max_f32_e32 v11, 0, v11
	v_mul_f32_e32 v17, v8, v8
	v_max_f32_e32 v8, 0, v13
	v_mul_f32_e32 v13, v9, v9
	v_max_f32_e32 v9, 0, v14
	v_mul_f32_e32 v14, v10, v10
	v_mul_f32_e32 v11, v11, v11
	v_max_f32_e32 v12, 0, v12
	v_mul_f32_e32 v8, v8, v8
	v_max_f32_e32 v10, 0, v15
	v_cvt_pk_bf16_f32 v11, v14, v11
	v_add_co_u32_e32 v14, vcc, s79, v120
	v_pk_mul_f32 v[2:3], v[16:17], v[2:3] op_sel_hi:[0,1]
	v_pk_mul_f32 v[0:1], v[16:17], v[0:1] op_sel_hi:[0,1]
	v_mul_f32_e32 v12, v12, v12
	v_mul_f32_e32 v9, v9, v9
	v_mul_f32_e32 v10, v10, v10
	v_cvt_pk_bf16_f32 v8, v12, v8
	v_addc_co_u32_e32 v15, vcc, 0, v121, vcc
	v_pk_mul_f32 v[6:7], v[16:17], v[6:7] op_sel_hi:[0,1]
	v_pk_mul_f32 v[4:5], v[16:17], v[4:5] op_sel_hi:[0,1]
	v_max_f32_e32 v0, 0, v0
	v_max_f32_e32 v1, 0, v1
	v_max_f32_e32 v2, 0, v2
	v_cvt_pk_bf16_f32 v9, v9, v10
	v_cvt_pk_bf16_f32 v10, v17, v13
	global_store_dwordx4 v[14:15], v[8:11], off sc0 sc1 nt
	v_max_f32_e32 v3, 0, v3
	v_lshl_add_u64 v[12:13], v[120:121], 0, s[26:27]
	v_mul_f32_e32 v8, v0, v0
	v_max_f32_e32 v0, 0, v5
	v_mul_f32_e32 v5, v1, v1
	v_max_f32_e32 v1, 0, v6
	v_mul_f32_e32 v6, v2, v2
	v_max_f32_e32 v2, 0, v7
	v_max_f32_e32 v4, 0, v4
	v_mul_f32_e32 v0, v0, v0
	v_mul_f32_e32 v1, v1, v1
	v_mul_f32_e32 v2, v2, v2
	v_mul_f32_e32 v3, v3, v3
	s_andn2_b64 vcc, exec, s[38:39]
	s_mov_b64 s[38:39], -1
	v_mul_f32_e32 v4, v4, v4
	v_cvt_pk_bf16_f32 v0, v4, v0
	v_cvt_pk_bf16_f32 v1, v1, v2
	v_cvt_pk_bf16_f32 v2, v8, v5
	v_cvt_pk_bf16_f32 v3, v6, v3
	global_store_dwordx4 v[12:13], v[0:3], off offset:256 sc0 sc1 nt
	s_cbranch_vccnz .LBB0_1276
	s_andn2_b64 vcc, exec, s[4:5]
	s_cbranch_vccnz .LBB0_1275
	s_barrier
	s_branch .LBB0_1275

.LBB0_1520:
	v_lshl_or_b32 v124, s61, 8, v220
	v_ashrrev_i32_e32 v125, 31, v124
	v_lshlrev_b64 v[126:127], 10, v[206:207]
	v_lshl_add_u64 v[184:185], v[126:127], 0, v[124:125]
	v_lshlrev_b64 v[126:127], 1, v[184:185]
	v_lshl_add_u64 v[128:129], s[14:15], 0, v[126:127]
	global_load_dwordx4 v[208:211], v[128:129], off
	v_lshl_add_u64 v[128:129], s[12:13], 0, v[126:127]
	global_load_dwordx4 v[212:215], v[128:129], off
	v_or_b32_e32 v128, 16, v206
	v_or_b32_e32 v130, 32, v206
	v_or_b32_e32 v136, 48, v206
	v_ashrrev_i32_e32 v129, 31, v128
	s_waitcnt vmcnt(0)
	v_fmamk_f32 v138, v230, 0x3a800000, v221
	v_ashrrev_i32_e32 v131, 31, v130
	v_ashrrev_i32_e32 v137, 31, v136
	v_lshlrev_b64 v[128:129], 10, v[128:129]
	v_mul_f32_e32 v139, 0x4b800000, v138
	v_lshlrev_b64 v[130:131], 10, v[130:131]
	v_lshlrev_b64 v[136:137], 10, v[136:137]
	v_cmp_gt_f32_e32 vcc, s60, v138
	v_lshl_add_u64 v[190:191], v[128:129], 0, v[124:125]
	v_or_b32_e32 v126, 0x100, v126
	v_cndmask_b32_e32 v138, v138, v139, vcc
	v_lshl_add_u64 v[188:189], v[130:131], 0, v[124:125]
	v_lshl_add_u64 v[186:187], v[136:137], 0, v[124:125]
	v_lshlrev_b64 v[124:125], 1, v[190:191]
	v_lshl_add_u64 v[136:137], s[12:13], 0, v[126:127]
	v_rsq_f32_e32 v216, v138
	v_lshl_add_u64 v[126:127], s[14:15], 0, v[126:127]
	v_lshl_add_u64 v[138:139], s[12:13], 0, v[124:125]
	v_lshl_add_u64 v[140:141], s[14:15], 0, v[124:125]
	global_load_dwordx4 v[176:179], v[136:137], off
	global_load_dwordx4 v[180:183], v[126:127], off
	global_load_dwordx4 v[168:171], v[138:139], off
	global_load_dwordx4 v[172:175], v[140:141], off
	v_lshlrev_b64 v[128:129], 1, v[188:189]
	v_lshlrev_b64 v[130:131], 1, v[186:187]
	v_or_b32_e32 v124, 0x100, v124
	v_lshl_add_u64 v[142:143], s[12:13], 0, v[128:129]
	v_lshl_add_u64 v[144:145], s[14:15], 0, v[128:129]
	v_or_b32_e32 v128, 0x100, v128
	v_lshl_add_u64 v[146:147], s[12:13], 0, v[130:131]
	v_lshl_add_u64 v[148:149], s[14:15], 0, v[130:131]
	v_or_b32_e32 v130, 0x100, v130
	v_lshl_add_u64 v[126:127], s[12:13], 0, v[124:125]
	v_lshl_add_u64 v[124:125], s[14:15], 0, v[124:125]
	global_load_dwordx4 v[152:155], v[142:143], off
	global_load_dwordx4 v[156:159], v[144:145], off
	v_lshl_add_u64 v[144:145], s[12:13], 0, v[128:129]
	v_lshl_add_u64 v[128:129], s[14:15], 0, v[128:129]
	v_lshl_add_u64 v[206:207], s[12:13], 0, v[130:131]
	v_lshl_add_u64 v[130:131], s[14:15], 0, v[130:131]
	global_load_dwordx4 v[136:139], v[146:147], off
	global_load_dwordx4 v[140:143], v[148:149], off
	global_load_dwordx4 v[160:163], v[126:127], off
	global_load_dwordx4 v[164:167], v[124:125], off
	s_nop 0
	global_load_dwordx4 v[144:147], v[144:145], off
	s_nop 0
	global_load_dwordx4 v[148:151], v[128:129], off
	global_load_dwordx4 v[124:127], v[206:207], off
	s_nop 0
	global_load_dwordx4 v[128:131], v[130:131], off
	v_mul_f32_e32 v206, 0x45800000, v216
	v_cndmask_b32_e32 v231, v216, v206, vcc
	v_mul_f32_e32 v132, v231, v132
	v_mul_f32_e32 v133, v231, v133
	v_mul_f32_e32 v120, v231, v120
	v_mul_f32_e32 v121, v231, v121
	v_mul_f32_e32 v132, 0xbfb8aa3b, v132
	v_mul_f32_e32 v133, 0xbfb8aa3b, v133
	v_mul_f32_e32 v120, 0xbfb8aa3b, v120
	v_mul_f32_e32 v121, 0xbfb8aa3b, v121
	v_exp_f32_e32 v132, v132
	v_exp_f32_e32 v133, v133
	v_exp_f32_e32 v120, v120
	v_exp_f32_e32 v121, v121
	v_mul_f32_e32 v122, v231, v122
	v_add_f32_e32 v132, 1.0, v132
	v_add_f32_e32 v133, 1.0, v133
	v_mul_f32_e32 v122, 0xbfb8aa3b, v122
	v_mul_f32_e32 v135, v231, v135
	v_add_f32_e32 v206, 1.0, v120
	v_add_f32_e32 v232, 1.0, v121
	v_rcp_f32_e32 v120, v132
	v_rcp_f32_e32 v121, v133
	v_exp_f32_e32 v122, v122
	v_mul_f32_e32 v135, 0xbfb8aa3b, v135
	v_rcp_f32_e32 v132, v206
	v_rcp_f32_e32 v133, v232
	v_mul_f32_e32 v134, v231, v134
	v_exp_f32_e32 v135, v135
	v_mul_f32_e32 v134, 0xbfb8aa3b, v134
	v_exp_f32_e32 v134, v134
	v_add_f32_e32 v122, 1.0, v122
	v_mul_f32_e32 v112, v231, v112
	v_mul_f32_e32 v112, 0xbfb8aa3b, v112
	v_add_f32_e32 v134, 1.0, v134
	v_lshlrev_b32_e32 v206, 16, v208
	v_and_b32_e32 v207, 0xffff0000, v208
	v_lshlrev_b32_e32 v216, 16, v212
	v_and_b32_e32 v217, 0xffff0000, v212
	v_pk_fma_f32 v[120:121], v[120:121], v[206:207], v[216:217]
	v_lshlrev_b32_e32 v206, 16, v210
	v_and_b32_e32 v207, 0xffff0000, v210
	v_lshlrev_b32_e32 v216, 16, v214
	v_and_b32_e32 v217, 0xffff0000, v214
	v_pk_fma_f32 v[132:133], v[132:133], v[206:207], v[216:217]
	v_rcp_f32_e32 v206, v122
	v_add_f32_e32 v122, 1.0, v135
	v_rcp_f32_e32 v135, v122
	v_mul_f32_e32 v122, v231, v123
	v_mul_f32_e32 v122, 0xbfb8aa3b, v122
	v_rcp_f32_e32 v134, v134
	v_exp_f32_e32 v207, v122
	v_lshlrev_b32_e32 v208, 16, v209
	v_and_b32_e32 v209, 0xffff0000, v209
	v_lshlrev_b32_e32 v122, 16, v213
	v_and_b32_e32 v123, 0xffff0000, v213
	v_pk_fma_f32 v[122:123], v[134:135], v[208:209], v[122:123]
	v_add_f32_e32 v134, 1.0, v207
	v_mul_f32_e32 v117, v231, v117
	v_rcp_f32_e32 v207, v134
	v_exp_f32_e32 v112, v112
	v_mul_f32_e32 v117, 0xbfb8aa3b, v117
	v_mul_f32_e32 v116, v231, v116
	v_exp_f32_e32 v117, v117
	v_mul_f32_e32 v116, 0xbfb8aa3b, v116
	v_lshlrev_b32_e32 v134, 16, v211
	v_and_b32_e32 v135, 0xffff0000, v211
	v_lshlrev_b32_e32 v208, 16, v215
	v_and_b32_e32 v209, 0xffff0000, v215
	v_exp_f32_e32 v116, v116
	v_pk_fma_f32 v[134:135], v[206:207], v[134:135], v[208:209]
	v_lshl_add_u64 v[206:207], v[184:185], 2, s[70:71]
	v_add_f32_e32 v112, 1.0, v112
	global_store_dwordx4 v[206:207], v[120:123], off nt
	global_store_dwordx4 v[206:207], v[132:135], off offset:16 nt
	v_add_f32_e32 v116, 1.0, v116
	v_rcp_f32_e32 v120, v112
	v_add_f32_e32 v112, 1.0, v117
	v_rcp_f32_e32 v117, v112
	v_mul_f32_e32 v112, v231, v113
	v_mul_f32_e32 v112, 0xbfb8aa3b, v112
	v_rcp_f32_e32 v116, v116
	v_exp_f32_e32 v121, v112
	v_mul_f32_e32 v114, v231, v114
	s_waitcnt vmcnt(14)
	v_lshlrev_b32_e32 v122, 16, v180
	v_and_b32_e32 v123, 0xffff0000, v180
	v_lshlrev_b32_e32 v112, 16, v176
	v_and_b32_e32 v113, 0xffff0000, v176
	v_mul_f32_e32 v118, v231, v118
	v_mul_f32_e32 v114, 0xbfb8aa3b, v114
	v_mul_f32_e32 v119, v231, v119
	v_pk_fma_f32 v[112:113], v[116:117], v[122:123], v[112:113]
	v_add_f32_e32 v116, 1.0, v121
	v_mul_f32_e32 v118, 0xbfb8aa3b, v118
	v_exp_f32_e32 v114, v114
	v_mul_f32_e32 v119, 0xbfb8aa3b, v119
	v_rcp_f32_e32 v121, v116
	v_exp_f32_e32 v118, v118
	v_exp_f32_e32 v119, v119
	v_lshlrev_b32_e32 v116, 16, v182
	v_and_b32_e32 v117, 0xffff0000, v182
	v_lshlrev_b32_e32 v122, 16, v178
	v_and_b32_e32 v123, 0xffff0000, v178
	v_add_f32_e32 v114, 1.0, v114
	v_pk_fma_f32 v[116:117], v[120:121], v[116:117], v[122:123]
	v_add_f32_e32 v118, 1.0, v118
	v_rcp_f32_e32 v120, v114
	v_add_f32_e32 v114, 1.0, v119
	v_rcp_f32_e32 v118, v118
	v_rcp_f32_e32 v119, v114
	v_mul_f32_e32 v114, v231, v115
	v_mul_f32_e32 v114, 0xbfb8aa3b, v114
	v_lshlrev_b32_e32 v122, 16, v181
	v_and_b32_e32 v123, 0xffff0000, v181
	v_exp_f32_e32 v121, v114
	v_lshlrev_b32_e32 v114, 16, v177
	v_and_b32_e32 v115, 0xffff0000, v177
	v_pk_fma_f32 v[114:115], v[118:119], v[122:123], v[114:115]
	v_fmamk_f32 v119, v229, 0x3a800000, v221
	v_mul_f32_e32 v122, 0x4b800000, v119
	v_cmp_gt_f32_e32 vcc, s60, v119
	v_add_f32_e32 v118, 1.0, v121
	v_rcp_f32_e32 v121, v118
	v_cndmask_b32_e32 v119, v119, v122, vcc
	v_rsq_f32_e32 v132, v119
	v_lshlrev_b32_e32 v118, 16, v183
	v_and_b32_e32 v119, 0xffff0000, v183
	v_lshlrev_b32_e32 v122, 16, v179
	v_mul_f32_e32 v133, 0x45800000, v132
	v_cndmask_b32_e32 v132, v132, v133, vcc
	v_mul_f32_e32 v104, v132, v104
	v_mul_f32_e32 v104, 0xbfb8aa3b, v104
	v_mul_f32_e32 v109, v132, v109
	v_exp_f32_e32 v104, v104
	v_mul_f32_e32 v109, 0xbfb8aa3b, v109
	v_mul_f32_e32 v108, v132, v108
	v_exp_f32_e32 v109, v109
	v_mul_f32_e32 v108, 0xbfb8aa3b, v108
	v_exp_f32_e32 v108, v108
	v_and_b32_e32 v123, 0xffff0000, v179
	v_add_f32_e32 v104, 1.0, v104
	v_pk_fma_f32 v[118:119], v[120:121], v[118:119], v[122:123]
	global_store_dwordx4 v[206:207], v[112:115], off offset:512 nt
	global_store_dwordx4 v[206:207], v[116:119], off offset:528 nt
	v_add_f32_e32 v108, 1.0, v108
	v_rcp_f32_e32 v112, v104
	v_add_f32_e32 v104, 1.0, v109
	v_rcp_f32_e32 v109, v104
	v_mul_f32_e32 v104, v132, v105
	v_mul_f32_e32 v104, 0xbfb8aa3b, v104
	v_rcp_f32_e32 v108, v108
	v_exp_f32_e32 v113, v104
	v_mul_f32_e32 v106, v132, v106
	s_waitcnt vmcnt(14)
	v_lshlrev_b32_e32 v114, 16, v172
	v_and_b32_e32 v115, 0xffff0000, v172
	v_lshlrev_b32_e32 v104, 16, v168
	v_and_b32_e32 v105, 0xffff0000, v168
	v_mul_f32_e32 v106, 0xbfb8aa3b, v106
	v_mul_f32_e32 v111, v132, v111
	v_pk_fma_f32 v[104:105], v[108:109], v[114:115], v[104:105]
	v_add_f32_e32 v108, 1.0, v113
	v_exp_f32_e32 v106, v106
	v_mul_f32_e32 v111, 0xbfb8aa3b, v111
	v_rcp_f32_e32 v113, v108
	v_mul_f32_e32 v110, v132, v110
	v_exp_f32_e32 v111, v111
	v_mul_f32_e32 v110, 0xbfb8aa3b, v110
	v_exp_f32_e32 v110, v110
	v_lshlrev_b32_e32 v108, 16, v174
	v_and_b32_e32 v109, 0xffff0000, v174
	v_lshlrev_b32_e32 v114, 16, v170
	v_and_b32_e32 v115, 0xffff0000, v170
	v_add_f32_e32 v106, 1.0, v106
	v_pk_fma_f32 v[108:109], v[112:113], v[108:109], v[114:115]
	v_rcp_f32_e32 v112, v106
	v_add_f32_e32 v106, 1.0, v111
	v_rcp_f32_e32 v111, v106
	v_mul_f32_e32 v106, v132, v107
	v_add_f32_e32 v110, 1.0, v110
	v_mul_f32_e32 v106, 0xbfb8aa3b, v106
	v_rcp_f32_e32 v110, v110
	v_exp_f32_e32 v113, v106
	v_lshlrev_b32_e32 v114, 16, v173
	v_and_b32_e32 v115, 0xffff0000, v173
	v_lshlrev_b32_e32 v106, 16, v169
	v_and_b32_e32 v107, 0xffff0000, v169
	v_mul_f32_e32 v96, v132, v96
	v_pk_fma_f32 v[106:107], v[110:111], v[114:115], v[106:107]
	v_add_f32_e32 v110, 1.0, v113
	v_mul_f32_e32 v96, 0xbfb8aa3b, v96
	v_mul_f32_e32 v101, v132, v101
	v_rcp_f32_e32 v113, v110
	v_exp_f32_e32 v96, v96
	v_mul_f32_e32 v101, 0xbfb8aa3b, v101
	v_mul_f32_e32 v100, v132, v100
	v_exp_f32_e32 v101, v101
	v_mul_f32_e32 v100, 0xbfb8aa3b, v100
	v_lshlrev_b32_e32 v110, 16, v175
	v_and_b32_e32 v111, 0xffff0000, v175
	v_lshlrev_b32_e32 v114, 16, v171
	v_and_b32_e32 v115, 0xffff0000, v171
	v_exp_f32_e32 v100, v100
	v_pk_fma_f32 v[110:111], v[112:113], v[110:111], v[114:115]
	v_lshl_add_u64 v[112:113], v[190:191], 2, s[70:71]
	v_add_f32_e32 v96, 1.0, v96
	global_store_dwordx4 v[112:113], v[104:107], off nt
	global_store_dwordx4 v[112:113], v[108:111], off offset:16 nt
	v_add_f32_e32 v100, 1.0, v100
	v_rcp_f32_e32 v104, v96
	v_add_f32_e32 v96, 1.0, v101
	v_rcp_f32_e32 v101, v96
	v_mul_f32_e32 v96, v132, v97
	v_mul_f32_e32 v96, 0xbfb8aa3b, v96
	v_rcp_f32_e32 v100, v100
	v_exp_f32_e32 v105, v96
	v_mul_f32_e32 v98, v132, v98
	s_waitcnt vmcnt(10)
	v_lshlrev_b32_e32 v106, 16, v164
	v_and_b32_e32 v107, 0xffff0000, v164
	v_lshlrev_b32_e32 v96, 16, v160
	v_and_b32_e32 v97, 0xffff0000, v160
	v_mul_f32_e32 v102, v132, v102
	v_mul_f32_e32 v98, 0xbfb8aa3b, v98
	v_mul_f32_e32 v103, v132, v103
	v_pk_fma_f32 v[96:97], v[100:101], v[106:107], v[96:97]
	v_add_f32_e32 v100, 1.0, v105
	v_mul_f32_e32 v102, 0xbfb8aa3b, v102
	v_exp_f32_e32 v98, v98
	v_mul_f32_e32 v103, 0xbfb8aa3b, v103
	v_rcp_f32_e32 v105, v100
	v_exp_f32_e32 v102, v102
	v_exp_f32_e32 v103, v103
	v_lshlrev_b32_e32 v100, 16, v166
	v_and_b32_e32 v101, 0xffff0000, v166
	v_lshlrev_b32_e32 v106, 16, v162
	v_and_b32_e32 v107, 0xffff0000, v162
	v_add_f32_e32 v98, 1.0, v98
	v_pk_fma_f32 v[100:101], v[104:105], v[100:101], v[106:107]
	v_add_f32_e32 v102, 1.0, v102
	v_rcp_f32_e32 v104, v98
	v_add_f32_e32 v98, 1.0, v103
	v_rcp_f32_e32 v102, v102
	v_rcp_f32_e32 v103, v98
	v_mul_f32_e32 v98, v132, v99
	v_mul_f32_e32 v98, 0xbfb8aa3b, v98
	v_lshlrev_b32_e32 v106, 16, v165
	v_and_b32_e32 v107, 0xffff0000, v165
	v_exp_f32_e32 v105, v98
	v_lshlrev_b32_e32 v98, 16, v161
	v_and_b32_e32 v99, 0xffff0000, v161
	v_pk_fma_f32 v[98:99], v[102:103], v[106:107], v[98:99]
	v_fmamk_f32 v103, v228, 0x3a800000, v221
	v_mul_f32_e32 v106, 0x4b800000, v103
	v_cmp_gt_f32_e32 vcc, s60, v103
	v_add_f32_e32 v102, 1.0, v105
	v_rcp_f32_e32 v105, v102
	v_cndmask_b32_e32 v103, v103, v106, vcc
	v_rsq_f32_e32 v108, v103
	v_lshlrev_b32_e32 v102, 16, v167
	v_and_b32_e32 v103, 0xffff0000, v167
	v_lshlrev_b32_e32 v106, 16, v163
	v_mul_f32_e32 v109, 0x45800000, v108
	v_cndmask_b32_e32 v108, v108, v109, vcc
	v_mul_f32_e32 v88, v108, v88
	v_mul_f32_e32 v88, 0xbfb8aa3b, v88
	v_mul_f32_e32 v93, v108, v93
	v_exp_f32_e32 v88, v88
	v_mul_f32_e32 v93, 0xbfb8aa3b, v93
	v_mul_f32_e32 v92, v108, v92
	v_exp_f32_e32 v93, v93
	v_mul_f32_e32 v92, 0xbfb8aa3b, v92
	v_exp_f32_e32 v92, v92
	v_and_b32_e32 v107, 0xffff0000, v163
	v_add_f32_e32 v88, 1.0, v88
	v_pk_fma_f32 v[102:103], v[104:105], v[102:103], v[106:107]
	global_store_dwordx4 v[112:113], v[96:99], off offset:512 nt
	global_store_dwordx4 v[112:113], v[100:103], off offset:528 nt
	v_add_f32_e32 v92, 1.0, v92
	v_rcp_f32_e32 v96, v88
	v_add_f32_e32 v88, 1.0, v93
	v_rcp_f32_e32 v93, v88
	v_mul_f32_e32 v88, v108, v89
	v_mul_f32_e32 v88, 0xbfb8aa3b, v88
	v_rcp_f32_e32 v92, v92
	v_exp_f32_e32 v97, v88
	v_mul_f32_e32 v90, v108, v90
	v_lshlrev_b32_e32 v98, 16, v156
	v_and_b32_e32 v99, 0xffff0000, v156
	v_lshlrev_b32_e32 v88, 16, v152
	v_and_b32_e32 v89, 0xffff0000, v152
	v_mul_f32_e32 v90, 0xbfb8aa3b, v90
	v_mul_f32_e32 v95, v108, v95
	v_pk_fma_f32 v[88:89], v[92:93], v[98:99], v[88:89]
	v_add_f32_e32 v92, 1.0, v97
	v_exp_f32_e32 v90, v90
	v_mul_f32_e32 v95, 0xbfb8aa3b, v95
	v_rcp_f32_e32 v97, v92
	v_mul_f32_e32 v94, v108, v94
	v_exp_f32_e32 v95, v95
	v_mul_f32_e32 v94, 0xbfb8aa3b, v94
	v_exp_f32_e32 v94, v94
	v_lshlrev_b32_e32 v92, 16, v158
	v_and_b32_e32 v93, 0xffff0000, v158
	v_lshlrev_b32_e32 v98, 16, v154
	v_and_b32_e32 v99, 0xffff0000, v154
	v_add_f32_e32 v90, 1.0, v90
	v_pk_fma_f32 v[92:93], v[96:97], v[92:93], v[98:99]
	v_rcp_f32_e32 v96, v90
	v_add_f32_e32 v90, 1.0, v95
	v_rcp_f32_e32 v95, v90
	v_mul_f32_e32 v90, v108, v91
	v_add_f32_e32 v94, 1.0, v94
	v_mul_f32_e32 v90, 0xbfb8aa3b, v90
	v_rcp_f32_e32 v94, v94
	v_exp_f32_e32 v97, v90
	v_lshlrev_b32_e32 v98, 16, v157
	v_and_b32_e32 v99, 0xffff0000, v157
	v_lshlrev_b32_e32 v90, 16, v153
	v_and_b32_e32 v91, 0xffff0000, v153
	v_mul_f32_e32 v80, v108, v80
	v_pk_fma_f32 v[90:91], v[94:95], v[98:99], v[90:91]
	v_add_f32_e32 v94, 1.0, v97
	v_mul_f32_e32 v80, 0xbfb8aa3b, v80
	v_mul_f32_e32 v85, v108, v85
	v_rcp_f32_e32 v97, v94
	v_exp_f32_e32 v80, v80
	v_mul_f32_e32 v85, 0xbfb8aa3b, v85
	v_mul_f32_e32 v84, v108, v84
	v_exp_f32_e32 v85, v85
	v_mul_f32_e32 v84, 0xbfb8aa3b, v84
	v_lshlrev_b32_e32 v94, 16, v159
	v_and_b32_e32 v95, 0xffff0000, v159
	v_lshlrev_b32_e32 v98, 16, v155
	v_and_b32_e32 v99, 0xffff0000, v155
	v_exp_f32_e32 v84, v84
	v_pk_fma_f32 v[94:95], v[96:97], v[94:95], v[98:99]
	v_lshl_add_u64 v[96:97], v[188:189], 2, s[70:71]
	v_add_f32_e32 v80, 1.0, v80
	global_store_dwordx4 v[96:97], v[88:91], off nt
	global_store_dwordx4 v[96:97], v[92:95], off offset:16 nt
	v_add_f32_e32 v84, 1.0, v84
	v_rcp_f32_e32 v88, v80
	v_add_f32_e32 v80, 1.0, v85
	v_rcp_f32_e32 v85, v80
	v_mul_f32_e32 v80, v108, v81
	v_mul_f32_e32 v80, 0xbfb8aa3b, v80
	v_rcp_f32_e32 v84, v84
	v_exp_f32_e32 v89, v80
	v_mul_f32_e32 v82, v108, v82
	s_waitcnt vmcnt(12)
	v_lshlrev_b32_e32 v90, 16, v148
	v_and_b32_e32 v91, 0xffff0000, v148
	v_lshlrev_b32_e32 v80, 16, v144
	v_and_b32_e32 v81, 0xffff0000, v144
	v_mul_f32_e32 v86, v108, v86
	v_mul_f32_e32 v82, 0xbfb8aa3b, v82
	v_mul_f32_e32 v87, v108, v87
	v_pk_fma_f32 v[80:81], v[84:85], v[90:91], v[80:81]
	v_add_f32_e32 v84, 1.0, v89
	v_mul_f32_e32 v86, 0xbfb8aa3b, v86
	v_exp_f32_e32 v82, v82
	v_mul_f32_e32 v87, 0xbfb8aa3b, v87
	v_rcp_f32_e32 v89, v84
	v_exp_f32_e32 v86, v86
	v_exp_f32_e32 v87, v87
	v_lshlrev_b32_e32 v84, 16, v150
	v_and_b32_e32 v85, 0xffff0000, v150
	v_lshlrev_b32_e32 v90, 16, v146
	v_and_b32_e32 v91, 0xffff0000, v146
	v_add_f32_e32 v82, 1.0, v82
	v_pk_fma_f32 v[84:85], v[88:89], v[84:85], v[90:91]
	v_add_f32_e32 v86, 1.0, v86
	v_rcp_f32_e32 v88, v82
	v_add_f32_e32 v82, 1.0, v87
	v_rcp_f32_e32 v86, v86
	v_rcp_f32_e32 v87, v82
	v_mul_f32_e32 v82, v108, v83
	v_mul_f32_e32 v82, 0xbfb8aa3b, v82
	v_lshlrev_b32_e32 v90, 16, v149
	v_and_b32_e32 v91, 0xffff0000, v149
	v_exp_f32_e32 v89, v82
	v_lshlrev_b32_e32 v82, 16, v145
	v_and_b32_e32 v83, 0xffff0000, v145
	v_pk_fma_f32 v[82:83], v[86:87], v[90:91], v[82:83]
	v_fmamk_f32 v87, v227, 0x3a800000, v221
	v_mul_f32_e32 v90, 0x4b800000, v87
	v_cmp_gt_f32_e32 vcc, s60, v87
	v_add_f32_e32 v86, 1.0, v89
	v_rcp_f32_e32 v89, v86
	v_cndmask_b32_e32 v87, v87, v90, vcc
	v_rsq_f32_e32 v92, v87
	v_lshlrev_b32_e32 v86, 16, v151
	v_and_b32_e32 v87, 0xffff0000, v151
	v_lshlrev_b32_e32 v90, 16, v147
	v_mul_f32_e32 v93, 0x45800000, v92
	v_cndmask_b32_e32 v92, v92, v93, vcc
	v_mul_f32_e32 v72, v92, v72
	v_mul_f32_e32 v72, 0xbfb8aa3b, v72
	v_mul_f32_e32 v77, v92, v77
	v_exp_f32_e32 v72, v72
	v_mul_f32_e32 v77, 0xbfb8aa3b, v77
	v_mul_f32_e32 v76, v92, v76
	v_exp_f32_e32 v77, v77
	v_mul_f32_e32 v76, 0xbfb8aa3b, v76
	v_exp_f32_e32 v76, v76
	v_and_b32_e32 v91, 0xffff0000, v147
	v_add_f32_e32 v72, 1.0, v72
	v_pk_fma_f32 v[86:87], v[88:89], v[86:87], v[90:91]
	global_store_dwordx4 v[96:97], v[80:83], off offset:512 nt
	global_store_dwordx4 v[96:97], v[84:87], off offset:528 nt
	v_add_f32_e32 v76, 1.0, v76
	v_rcp_f32_e32 v80, v72
	v_add_f32_e32 v72, 1.0, v77
	v_rcp_f32_e32 v77, v72
	v_mul_f32_e32 v72, v92, v73
	v_mul_f32_e32 v72, 0xbfb8aa3b, v72
	v_rcp_f32_e32 v76, v76
	v_exp_f32_e32 v81, v72
	v_mul_f32_e32 v74, v92, v74
	v_lshlrev_b32_e32 v82, 16, v140
	v_and_b32_e32 v83, 0xffff0000, v140
	v_lshlrev_b32_e32 v72, 16, v136
	v_and_b32_e32 v73, 0xffff0000, v136
	v_mul_f32_e32 v74, 0xbfb8aa3b, v74
	v_mul_f32_e32 v79, v92, v79
	v_pk_fma_f32 v[72:73], v[76:77], v[82:83], v[72:73]
	v_add_f32_e32 v76, 1.0, v81
	v_exp_f32_e32 v74, v74
	v_mul_f32_e32 v79, 0xbfb8aa3b, v79
	v_rcp_f32_e32 v81, v76
	v_mul_f32_e32 v78, v92, v78
	v_exp_f32_e32 v79, v79
	v_mul_f32_e32 v78, 0xbfb8aa3b, v78
	v_exp_f32_e32 v78, v78
	v_lshlrev_b32_e32 v76, 16, v142
	v_and_b32_e32 v77, 0xffff0000, v142
	v_lshlrev_b32_e32 v82, 16, v138
	v_and_b32_e32 v83, 0xffff0000, v138
	v_add_f32_e32 v74, 1.0, v74
	v_pk_fma_f32 v[76:77], v[80:81], v[76:77], v[82:83]
	v_rcp_f32_e32 v80, v74
	v_add_f32_e32 v74, 1.0, v79
	v_rcp_f32_e32 v79, v74
	v_mul_f32_e32 v74, v92, v75
	v_add_f32_e32 v78, 1.0, v78
	v_mul_f32_e32 v74, 0xbfb8aa3b, v74
	v_rcp_f32_e32 v78, v78
	v_exp_f32_e32 v81, v74
	v_lshlrev_b32_e32 v82, 16, v141
	v_and_b32_e32 v83, 0xffff0000, v141
	v_lshlrev_b32_e32 v74, 16, v137
	v_and_b32_e32 v75, 0xffff0000, v137
	v_mul_f32_e32 v64, v92, v64
	v_pk_fma_f32 v[74:75], v[78:79], v[82:83], v[74:75]
	v_add_f32_e32 v78, 1.0, v81
	v_mul_f32_e32 v64, 0xbfb8aa3b, v64
	v_mul_f32_e32 v69, v92, v69
	v_rcp_f32_e32 v81, v78
	v_exp_f32_e32 v64, v64
	v_mul_f32_e32 v69, 0xbfb8aa3b, v69
	v_mul_f32_e32 v68, v92, v68
	v_exp_f32_e32 v69, v69
	v_mul_f32_e32 v68, 0xbfb8aa3b, v68
	v_lshlrev_b32_e32 v78, 16, v143
	v_and_b32_e32 v79, 0xffff0000, v143
	v_lshlrev_b32_e32 v82, 16, v139
	v_and_b32_e32 v83, 0xffff0000, v139
	v_exp_f32_e32 v68, v68
	v_pk_fma_f32 v[78:79], v[80:81], v[78:79], v[82:83]
	v_lshl_add_u64 v[80:81], v[186:187], 2, s[70:71]
	v_add_f32_e32 v64, 1.0, v64
	global_store_dwordx4 v[80:81], v[72:75], off nt
	global_store_dwordx4 v[80:81], v[76:79], off offset:16 nt
	v_add_f32_e32 v68, 1.0, v68
	v_rcp_f32_e32 v72, v64
	v_add_f32_e32 v64, 1.0, v69
	v_rcp_f32_e32 v69, v64
	v_mul_f32_e32 v64, v92, v65
	v_mul_f32_e32 v64, 0xbfb8aa3b, v64
	v_rcp_f32_e32 v68, v68
	v_exp_f32_e32 v73, v64
	v_mul_f32_e32 v66, v92, v66
	s_waitcnt vmcnt(14)
	v_lshlrev_b32_e32 v74, 16, v128
	v_and_b32_e32 v75, 0xffff0000, v128
	v_lshlrev_b32_e32 v64, 16, v124
	v_and_b32_e32 v65, 0xffff0000, v124
	v_mul_f32_e32 v66, 0xbfb8aa3b, v66
	v_mul_f32_e32 v71, v92, v71
	v_pk_fma_f32 v[64:65], v[68:69], v[74:75], v[64:65]
	v_add_f32_e32 v68, 1.0, v73
	v_exp_f32_e32 v66, v66
	v_mul_f32_e32 v71, 0xbfb8aa3b, v71
	v_rcp_f32_e32 v73, v68
	v_mul_f32_e32 v70, v92, v70
	v_exp_f32_e32 v71, v71
	v_mul_f32_e32 v70, 0xbfb8aa3b, v70
	v_exp_f32_e32 v70, v70
	v_lshlrev_b32_e32 v68, 16, v130
	v_and_b32_e32 v69, 0xffff0000, v130
	v_lshlrev_b32_e32 v74, 16, v126
	v_and_b32_e32 v75, 0xffff0000, v126
	v_add_f32_e32 v66, 1.0, v66
	v_pk_fma_f32 v[68:69], v[72:73], v[68:69], v[74:75]
	v_rcp_f32_e32 v72, v66
	v_add_f32_e32 v66, 1.0, v71
	v_rcp_f32_e32 v71, v66
	v_mul_f32_e32 v66, v92, v67
	v_add_f32_e32 v70, 1.0, v70
	v_mul_f32_e32 v66, 0xbfb8aa3b, v66
	v_rcp_f32_e32 v70, v70
	v_exp_f32_e32 v73, v66
	v_lshlrev_b32_e32 v74, 16, v129
	v_and_b32_e32 v75, 0xffff0000, v129
	v_lshlrev_b32_e32 v66, 16, v125
	v_and_b32_e32 v67, 0xffff0000, v125
	v_pk_fma_f32 v[66:67], v[70:71], v[74:75], v[66:67]
	v_add_f32_e32 v70, 1.0, v73
	v_rcp_f32_e32 v73, v70
	v_lshlrev_b32_e32 v70, 16, v131
	v_and_b32_e32 v71, 0xffff0000, v131
	v_lshlrev_b32_e32 v74, 16, v127
	v_and_b32_e32 v75, 0xffff0000, v127
	v_lshl_add_u64 v[134:135], v[184:185], 0, s[10:11]
	v_pk_fma_f32 v[70:71], v[72:73], v[70:71], v[74:75]
	global_store_dwordx4 v[80:81], v[64:67], off offset:512 nt
	global_store_dwordx4 v[80:81], v[68:71], off offset:528 nt
	v_lshl_add_u64 v[124:125], v[184:185], 0, s[16:17]
	v_lshlrev_b64 v[64:65], 1, v[134:135]
	v_lshl_add_u64 v[66:67], s[14:15], 0, v[64:65]
	global_load_dwordx4 v[126:129], v[66:67], off
	v_lshl_add_u64 v[66:67], s[12:13], 0, v[64:65]
	global_load_dwordx4 v[130:133], v[66:67], off
	v_or_b32_e32 v64, 0x100, v64
	v_lshl_add_u64 v[66:67], s[12:13], 0, v[64:65]
	v_lshl_add_u64 v[64:65], s[14:15], 0, v[64:65]
	global_load_dwordx4 v[112:115], v[66:67], off
	global_load_dwordx4 v[116:119], v[64:65], off
	v_lshlrev_b64 v[64:65], 1, v[124:125]
	v_lshl_add_u64 v[66:67], s[12:13], 0, v[64:65]
	v_lshl_add_u64 v[68:69], s[14:15], 0, v[64:65]
	global_load_dwordx4 v[104:107], v[66:67], off
	global_load_dwordx4 v[108:111], v[68:69], off
	v_or_b32_e32 v64, 0x100, v64
	v_fmamk_f32 v70, v226, 0x3a800000, v221
	v_lshl_add_u64 v[66:67], s[12:13], 0, v[64:65]
	v_lshl_add_u64 v[64:65], s[14:15], 0, v[64:65]
	v_lshl_add_u64 v[122:123], v[184:185], 0, s[18:19]
	v_mul_f32_e32 v71, 0x4b800000, v70
	v_cmp_gt_f32_e32 vcc, s60, v70
	global_load_dwordx4 v[96:99], v[66:67], off
	global_load_dwordx4 v[100:103], v[64:65], off
	v_lshlrev_b64 v[64:65], 1, v[122:123]
	v_cndmask_b32_e32 v70, v70, v71, vcc
	v_lshl_add_u64 v[66:67], s[12:13], 0, v[64:65]
	v_lshl_add_u64 v[68:69], s[14:15], 0, v[64:65]
	v_or_b32_e32 v64, 0x100, v64
	v_rsq_f32_e32 v70, v70
	global_load_dwordx4 v[88:91], v[66:67], off
	global_load_dwordx4 v[92:95], v[68:69], off
	v_lshl_add_u64 v[66:67], s[12:13], 0, v[64:65]
	v_lshl_add_u64 v[64:65], s[14:15], 0, v[64:65]
	v_lshl_add_u64 v[120:121], v[184:185], 0, s[20:21]
	global_load_dwordx4 v[80:83], v[66:67], off
	global_load_dwordx4 v[84:87], v[64:65], off
	v_lshlrev_b64 v[64:65], 1, v[120:121]
	v_lshl_add_u64 v[66:67], s[12:13], 0, v[64:65]
	v_lshl_add_u64 v[68:69], s[14:15], 0, v[64:65]
	global_load_dwordx4 v[72:75], v[66:67], off
	global_load_dwordx4 v[76:79], v[68:69], off
	v_mul_f32_e32 v68, 0x45800000, v70
	v_cndmask_b32_e32 v140, v70, v68, vcc
	v_mul_f32_e32 v56, v140, v56
	v_mul_f32_e32 v56, 0xbfb8aa3b, v56
	v_mul_f32_e32 v61, v140, v61
	v_exp_f32_e32 v56, v56
	v_mul_f32_e32 v61, 0xbfb8aa3b, v61
	v_mul_f32_e32 v60, v140, v60
	v_exp_f32_e32 v61, v61
	v_mul_f32_e32 v60, 0xbfb8aa3b, v60
	v_exp_f32_e32 v60, v60
	v_add_f32_e32 v56, 1.0, v56
	v_rcp_f32_e32 v136, v56
	v_add_f32_e32 v56, 1.0, v61
	v_rcp_f32_e32 v61, v56
	v_mul_f32_e32 v56, v140, v57
	v_add_f32_e32 v60, 1.0, v60
	v_mul_f32_e32 v56, 0xbfb8aa3b, v56
	v_mul_f32_e32 v58, v140, v58
	v_rcp_f32_e32 v60, v60
	v_mul_f32_e32 v58, 0xbfb8aa3b, v58
	v_mul_f32_e32 v63, v140, v63
	v_exp_f32_e32 v58, v58
	v_mul_f32_e32 v63, 0xbfb8aa3b, v63
	v_mul_f32_e32 v62, v140, v62
	v_exp_f32_e32 v63, v63
	v_mul_f32_e32 v62, 0xbfb8aa3b, v62
	v_exp_f32_e32 v62, v62
	v_add_f32_e32 v58, 1.0, v58
	v_mul_f32_e32 v48, v140, v48
	v_mul_f32_e32 v48, 0xbfb8aa3b, v48
	v_add_f32_e32 v62, 1.0, v62
	v_rcp_f32_e32 v62, v62
	v_mul_f32_e32 v53, v140, v53
	v_exp_f32_e32 v48, v48
	v_mul_f32_e32 v53, 0xbfb8aa3b, v53
	v_mul_f32_e32 v52, v140, v52
	v_exp_f32_e32 v53, v53
	v_mul_f32_e32 v52, 0xbfb8aa3b, v52
	v_or_b32_e32 v64, 0x100, v64
	v_exp_f32_e32 v52, v52
	v_lshl_add_u64 v[66:67], s[12:13], 0, v[64:65]
	v_lshl_add_u64 v[68:69], s[14:15], 0, v[64:65]
	v_add_f32_e32 v48, 1.0, v48
	global_load_dwordx4 v[64:67], v[66:67], off
	s_nop 0
	global_load_dwordx4 v[68:71], v[68:69], off
	v_add_f32_e32 v52, 1.0, v52
	s_waitcnt vmcnt(15)
	v_lshlrev_b32_e32 v138, 16, v126
	v_and_b32_e32 v139, 0xffff0000, v126
	v_exp_f32_e32 v126, v56
	s_waitcnt vmcnt(14)
	v_lshlrev_b32_e32 v56, 16, v130
	v_and_b32_e32 v57, 0xffff0000, v130
	v_pk_fma_f32 v[56:57], v[60:61], v[138:139], v[56:57]
	v_add_f32_e32 v60, 1.0, v126
	v_rcp_f32_e32 v137, v60
	v_rcp_f32_e32 v126, v58
	v_add_f32_e32 v58, 1.0, v63
	v_rcp_f32_e32 v63, v58
	v_mul_f32_e32 v58, v140, v59
	v_lshlrev_b32_e32 v60, 16, v128
	v_and_b32_e32 v61, 0xffff0000, v128
	v_lshlrev_b32_e32 v138, 16, v132
	v_and_b32_e32 v139, 0xffff0000, v132
	v_mul_f32_e32 v58, 0xbfb8aa3b, v58
	v_pk_fma_f32 v[60:61], v[136:137], v[60:61], v[138:139]
	v_lshlrev_b32_e32 v136, 16, v127
	v_and_b32_e32 v137, 0xffff0000, v127
	v_exp_f32_e32 v127, v58
	v_lshlrev_b32_e32 v58, 16, v131
	v_and_b32_e32 v59, 0xffff0000, v131
	v_pk_fma_f32 v[58:59], v[62:63], v[136:137], v[58:59]
	v_add_f32_e32 v62, 1.0, v127
	v_rcp_f32_e32 v127, v62
	v_lshlrev_b32_e32 v62, 16, v129
	v_and_b32_e32 v63, 0xffff0000, v129
	v_lshlrev_b32_e32 v128, 16, v133
	v_and_b32_e32 v129, 0xffff0000, v133
	v_pk_fma_f32 v[62:63], v[126:127], v[62:63], v[128:129]
	v_lshl_add_u64 v[126:127], v[134:135], 2, s[70:71]
	global_store_dwordx4 v[126:127], v[56:59], off nt
	global_store_dwordx4 v[126:127], v[60:63], off offset:16 nt
	v_rcp_f32_e32 v52, v52
	v_rcp_f32_e32 v56, v48
	v_add_f32_e32 v48, 1.0, v53
	v_rcp_f32_e32 v53, v48
	v_mul_f32_e32 v48, v140, v49
	v_mul_f32_e32 v48, 0xbfb8aa3b, v48
	v_exp_f32_e32 v57, v48
	v_mul_f32_e32 v50, v140, v50
	s_waitcnt vmcnt(14)
	v_lshlrev_b32_e32 v58, 16, v116
	v_and_b32_e32 v59, 0xffff0000, v116
	v_lshlrev_b32_e32 v48, 16, v112
	v_and_b32_e32 v49, 0xffff0000, v112
	v_mul_f32_e32 v54, v140, v54
	v_mul_f32_e32 v50, 0xbfb8aa3b, v50
	v_mul_f32_e32 v55, v140, v55
	v_pk_fma_f32 v[48:49], v[52:53], v[58:59], v[48:49]
	v_add_f32_e32 v52, 1.0, v57
	v_mul_f32_e32 v54, 0xbfb8aa3b, v54
	v_exp_f32_e32 v50, v50
	v_mul_f32_e32 v55, 0xbfb8aa3b, v55
	v_rcp_f32_e32 v57, v52
	v_exp_f32_e32 v54, v54
	v_exp_f32_e32 v55, v55
	v_lshlrev_b32_e32 v52, 16, v118
	v_and_b32_e32 v53, 0xffff0000, v118
	v_lshlrev_b32_e32 v58, 16, v114
	v_and_b32_e32 v59, 0xffff0000, v114
	v_add_f32_e32 v50, 1.0, v50
	v_pk_fma_f32 v[52:53], v[56:57], v[52:53], v[58:59]
	v_add_f32_e32 v54, 1.0, v54
	v_rcp_f32_e32 v56, v50
	v_add_f32_e32 v50, 1.0, v55
	v_rcp_f32_e32 v54, v54
	v_rcp_f32_e32 v55, v50
	v_mul_f32_e32 v50, v140, v51
	v_mul_f32_e32 v50, 0xbfb8aa3b, v50
	v_lshlrev_b32_e32 v58, 16, v117
	v_and_b32_e32 v59, 0xffff0000, v117
	v_exp_f32_e32 v57, v50
	v_lshlrev_b32_e32 v50, 16, v113
	v_and_b32_e32 v51, 0xffff0000, v113
	v_pk_fma_f32 v[50:51], v[54:55], v[58:59], v[50:51]
	v_fmamk_f32 v55, v225, 0x3a800000, v221
	v_mul_f32_e32 v58, 0x4b800000, v55
	v_cmp_gt_f32_e32 vcc, s60, v55
	v_add_f32_e32 v54, 1.0, v57
	v_rcp_f32_e32 v57, v54
	v_cndmask_b32_e32 v55, v55, v58, vcc
	v_rsq_f32_e32 v60, v55
	v_lshlrev_b32_e32 v54, 16, v119
	v_and_b32_e32 v55, 0xffff0000, v119
	v_lshlrev_b32_e32 v58, 16, v115
	v_mul_f32_e32 v61, 0x45800000, v60
	v_cndmask_b32_e32 v60, v60, v61, vcc
	v_mul_f32_e32 v40, v60, v40
	v_mul_f32_e32 v40, 0xbfb8aa3b, v40
	v_mul_f32_e32 v45, v60, v45
	v_exp_f32_e32 v40, v40
	v_mul_f32_e32 v45, 0xbfb8aa3b, v45
	v_mul_f32_e32 v44, v60, v44
	v_exp_f32_e32 v45, v45
	v_mul_f32_e32 v44, 0xbfb8aa3b, v44
	v_exp_f32_e32 v44, v44
	v_and_b32_e32 v59, 0xffff0000, v115
	v_add_f32_e32 v40, 1.0, v40
	v_pk_fma_f32 v[54:55], v[56:57], v[54:55], v[58:59]
	global_store_dwordx4 v[126:127], v[48:51], off offset:512 nt
	global_store_dwordx4 v[126:127], v[52:55], off offset:528 nt
	v_add_f32_e32 v44, 1.0, v44
	v_rcp_f32_e32 v48, v40
	v_add_f32_e32 v40, 1.0, v45
	v_rcp_f32_e32 v45, v40
	v_mul_f32_e32 v40, v60, v41
	v_mul_f32_e32 v40, 0xbfb8aa3b, v40
	v_rcp_f32_e32 v44, v44
	v_exp_f32_e32 v49, v40
	v_mul_f32_e32 v42, v60, v42
	s_waitcnt vmcnt(14)
	v_lshlrev_b32_e32 v50, 16, v108
	v_and_b32_e32 v51, 0xffff0000, v108
	v_lshlrev_b32_e32 v40, 16, v104
	v_and_b32_e32 v41, 0xffff0000, v104
	v_mul_f32_e32 v42, 0xbfb8aa3b, v42
	v_mul_f32_e32 v47, v60, v47
	v_pk_fma_f32 v[40:41], v[44:45], v[50:51], v[40:41]
	v_add_f32_e32 v44, 1.0, v49
	v_exp_f32_e32 v42, v42
	v_mul_f32_e32 v47, 0xbfb8aa3b, v47
	v_rcp_f32_e32 v49, v44
	v_mul_f32_e32 v46, v60, v46
	v_exp_f32_e32 v47, v47
	v_mul_f32_e32 v46, 0xbfb8aa3b, v46
	v_exp_f32_e32 v46, v46
	v_lshlrev_b32_e32 v44, 16, v110
	v_and_b32_e32 v45, 0xffff0000, v110
	v_lshlrev_b32_e32 v50, 16, v106
	v_and_b32_e32 v51, 0xffff0000, v106
	v_add_f32_e32 v42, 1.0, v42
	v_pk_fma_f32 v[44:45], v[48:49], v[44:45], v[50:51]
	v_rcp_f32_e32 v48, v42
	v_add_f32_e32 v42, 1.0, v47
	v_rcp_f32_e32 v47, v42
	v_mul_f32_e32 v42, v60, v43
	v_add_f32_e32 v46, 1.0, v46
	v_mul_f32_e32 v42, 0xbfb8aa3b, v42
	v_rcp_f32_e32 v46, v46
	v_exp_f32_e32 v49, v42
	v_lshlrev_b32_e32 v50, 16, v109
	v_and_b32_e32 v51, 0xffff0000, v109
	v_lshlrev_b32_e32 v42, 16, v105
	v_and_b32_e32 v43, 0xffff0000, v105
	v_mul_f32_e32 v32, v60, v32
	v_pk_fma_f32 v[42:43], v[46:47], v[50:51], v[42:43]
	v_add_f32_e32 v46, 1.0, v49
	v_mul_f32_e32 v32, 0xbfb8aa3b, v32
	v_mul_f32_e32 v37, v60, v37
	v_rcp_f32_e32 v49, v46
	v_exp_f32_e32 v32, v32
	v_mul_f32_e32 v37, 0xbfb8aa3b, v37
	v_mul_f32_e32 v36, v60, v36
	v_exp_f32_e32 v37, v37
	v_mul_f32_e32 v36, 0xbfb8aa3b, v36
	v_lshlrev_b32_e32 v46, 16, v111
	v_and_b32_e32 v47, 0xffff0000, v111
	v_lshlrev_b32_e32 v50, 16, v107
	v_and_b32_e32 v51, 0xffff0000, v107
	v_exp_f32_e32 v36, v36
	v_pk_fma_f32 v[46:47], v[48:49], v[46:47], v[50:51]
	v_lshl_add_u64 v[48:49], v[124:125], 2, s[70:71]
	v_add_f32_e32 v32, 1.0, v32
	global_store_dwordx4 v[48:49], v[40:43], off nt
	global_store_dwordx4 v[48:49], v[44:47], off offset:16 nt
	v_add_f32_e32 v36, 1.0, v36
	v_rcp_f32_e32 v40, v32
	v_add_f32_e32 v32, 1.0, v37
	v_rcp_f32_e32 v37, v32
	v_mul_f32_e32 v32, v60, v33
	v_mul_f32_e32 v32, 0xbfb8aa3b, v32
	v_rcp_f32_e32 v36, v36
	v_exp_f32_e32 v41, v32
	v_mul_f32_e32 v34, v60, v34
	s_waitcnt vmcnt(14)
	v_lshlrev_b32_e32 v42, 16, v100
	v_and_b32_e32 v43, 0xffff0000, v100
	v_lshlrev_b32_e32 v32, 16, v96
	v_and_b32_e32 v33, 0xffff0000, v96
	v_mul_f32_e32 v38, v60, v38
	v_mul_f32_e32 v34, 0xbfb8aa3b, v34
	v_mul_f32_e32 v39, v60, v39
	v_pk_fma_f32 v[32:33], v[36:37], v[42:43], v[32:33]
	v_add_f32_e32 v36, 1.0, v41
	v_mul_f32_e32 v38, 0xbfb8aa3b, v38
	v_exp_f32_e32 v34, v34
	v_mul_f32_e32 v39, 0xbfb8aa3b, v39
	v_rcp_f32_e32 v41, v36
	v_exp_f32_e32 v38, v38
	v_exp_f32_e32 v39, v39
	v_lshlrev_b32_e32 v36, 16, v102
	v_and_b32_e32 v37, 0xffff0000, v102
	v_lshlrev_b32_e32 v42, 16, v98
	v_and_b32_e32 v43, 0xffff0000, v98
	v_add_f32_e32 v34, 1.0, v34
	v_pk_fma_f32 v[36:37], v[40:41], v[36:37], v[42:43]
	v_add_f32_e32 v38, 1.0, v38
	v_rcp_f32_e32 v40, v34
	v_add_f32_e32 v34, 1.0, v39
	v_rcp_f32_e32 v38, v38
	v_rcp_f32_e32 v39, v34
	v_mul_f32_e32 v34, v60, v35
	v_mul_f32_e32 v34, 0xbfb8aa3b, v34
	v_lshlrev_b32_e32 v42, 16, v101
	v_and_b32_e32 v43, 0xffff0000, v101
	v_exp_f32_e32 v41, v34
	v_lshlrev_b32_e32 v34, 16, v97
	v_and_b32_e32 v35, 0xffff0000, v97
	v_pk_fma_f32 v[34:35], v[38:39], v[42:43], v[34:35]
	v_fmamk_f32 v39, v224, 0x3a800000, v221
	v_mul_f32_e32 v42, 0x4b800000, v39
	v_cmp_gt_f32_e32 vcc, s60, v39
	v_add_f32_e32 v38, 1.0, v41
	v_rcp_f32_e32 v41, v38
	v_cndmask_b32_e32 v39, v39, v42, vcc
	v_rsq_f32_e32 v44, v39
	v_lshlrev_b32_e32 v38, 16, v103
	v_and_b32_e32 v39, 0xffff0000, v103
	v_lshlrev_b32_e32 v42, 16, v99
	v_mul_f32_e32 v45, 0x45800000, v44
	v_cndmask_b32_e32 v44, v44, v45, vcc
	v_mul_f32_e32 v24, v44, v24
	v_mul_f32_e32 v24, 0xbfb8aa3b, v24
	v_mul_f32_e32 v29, v44, v29
	v_exp_f32_e32 v24, v24
	v_mul_f32_e32 v29, 0xbfb8aa3b, v29
	v_mul_f32_e32 v28, v44, v28
	v_exp_f32_e32 v29, v29
	v_mul_f32_e32 v28, 0xbfb8aa3b, v28
	v_exp_f32_e32 v28, v28
	v_and_b32_e32 v43, 0xffff0000, v99
	v_add_f32_e32 v24, 1.0, v24
	v_pk_fma_f32 v[38:39], v[40:41], v[38:39], v[42:43]
	global_store_dwordx4 v[48:49], v[32:35], off offset:512 nt
	global_store_dwordx4 v[48:49], v[36:39], off offset:528 nt
	v_add_f32_e32 v28, 1.0, v28
	v_rcp_f32_e32 v32, v24
	v_add_f32_e32 v24, 1.0, v29
	v_rcp_f32_e32 v29, v24
	v_mul_f32_e32 v24, v44, v25
	v_mul_f32_e32 v24, 0xbfb8aa3b, v24
	v_rcp_f32_e32 v28, v28
	v_exp_f32_e32 v33, v24
	v_mul_f32_e32 v26, v44, v26
	s_waitcnt vmcnt(14)
	v_lshlrev_b32_e32 v34, 16, v92
	v_and_b32_e32 v35, 0xffff0000, v92
	v_lshlrev_b32_e32 v24, 16, v88
	v_and_b32_e32 v25, 0xffff0000, v88
	v_mul_f32_e32 v26, 0xbfb8aa3b, v26
	v_mul_f32_e32 v31, v44, v31
	v_pk_fma_f32 v[24:25], v[28:29], v[34:35], v[24:25]
	v_add_f32_e32 v28, 1.0, v33
	v_exp_f32_e32 v26, v26
	v_mul_f32_e32 v31, 0xbfb8aa3b, v31
	v_rcp_f32_e32 v33, v28
	v_mul_f32_e32 v30, v44, v30
	v_exp_f32_e32 v31, v31
	v_mul_f32_e32 v30, 0xbfb8aa3b, v30
	v_exp_f32_e32 v30, v30
	v_lshlrev_b32_e32 v28, 16, v94
	v_and_b32_e32 v29, 0xffff0000, v94
	v_lshlrev_b32_e32 v34, 16, v90
	v_and_b32_e32 v35, 0xffff0000, v90
	v_add_f32_e32 v26, 1.0, v26
	v_pk_fma_f32 v[28:29], v[32:33], v[28:29], v[34:35]
	v_rcp_f32_e32 v32, v26
	v_add_f32_e32 v26, 1.0, v31
	v_rcp_f32_e32 v31, v26
	v_mul_f32_e32 v26, v44, v27
	v_add_f32_e32 v30, 1.0, v30
	v_mul_f32_e32 v26, 0xbfb8aa3b, v26
	v_rcp_f32_e32 v30, v30
	v_exp_f32_e32 v33, v26
	v_lshlrev_b32_e32 v34, 16, v93
	v_and_b32_e32 v35, 0xffff0000, v93
	v_lshlrev_b32_e32 v26, 16, v89
	v_and_b32_e32 v27, 0xffff0000, v89
	v_mul_f32_e32 v16, v44, v16
	v_pk_fma_f32 v[26:27], v[30:31], v[34:35], v[26:27]
	v_add_f32_e32 v30, 1.0, v33
	v_mul_f32_e32 v16, 0xbfb8aa3b, v16
	v_mul_f32_e32 v21, v44, v21
	v_rcp_f32_e32 v33, v30
	v_exp_f32_e32 v16, v16
	v_mul_f32_e32 v21, 0xbfb8aa3b, v21
	v_mul_f32_e32 v20, v44, v20
	v_exp_f32_e32 v21, v21
	v_mul_f32_e32 v20, 0xbfb8aa3b, v20
	v_lshlrev_b32_e32 v30, 16, v95
	v_and_b32_e32 v31, 0xffff0000, v95
	v_lshlrev_b32_e32 v34, 16, v91
	v_and_b32_e32 v35, 0xffff0000, v91
	v_exp_f32_e32 v20, v20
	v_pk_fma_f32 v[30:31], v[32:33], v[30:31], v[34:35]
	v_lshl_add_u64 v[32:33], v[122:123], 2, s[70:71]
	v_add_f32_e32 v16, 1.0, v16
	global_store_dwordx4 v[32:33], v[24:27], off nt
	global_store_dwordx4 v[32:33], v[28:31], off offset:16 nt
	v_add_f32_e32 v20, 1.0, v20
	v_rcp_f32_e32 v24, v16
	v_add_f32_e32 v16, 1.0, v21
	v_rcp_f32_e32 v21, v16
	v_mul_f32_e32 v16, v44, v17
	v_mul_f32_e32 v16, 0xbfb8aa3b, v16
	v_rcp_f32_e32 v20, v20
	v_exp_f32_e32 v25, v16
	v_mul_f32_e32 v18, v44, v18
	s_waitcnt vmcnt(14)
	v_lshlrev_b32_e32 v26, 16, v84
	v_and_b32_e32 v27, 0xffff0000, v84
	v_lshlrev_b32_e32 v16, 16, v80
	v_and_b32_e32 v17, 0xffff0000, v80
	v_mul_f32_e32 v22, v44, v22
	v_mul_f32_e32 v18, 0xbfb8aa3b, v18
	v_mul_f32_e32 v23, v44, v23
	v_pk_fma_f32 v[16:17], v[20:21], v[26:27], v[16:17]
	v_add_f32_e32 v20, 1.0, v25
	v_mul_f32_e32 v22, 0xbfb8aa3b, v22
	v_exp_f32_e32 v18, v18
	v_mul_f32_e32 v23, 0xbfb8aa3b, v23
	v_rcp_f32_e32 v25, v20
	v_exp_f32_e32 v22, v22
	v_exp_f32_e32 v23, v23
	v_lshlrev_b32_e32 v20, 16, v86
	v_and_b32_e32 v21, 0xffff0000, v86
	v_lshlrev_b32_e32 v26, 16, v82
	v_and_b32_e32 v27, 0xffff0000, v82
	v_add_f32_e32 v18, 1.0, v18
	v_pk_fma_f32 v[20:21], v[24:25], v[20:21], v[26:27]
	v_add_f32_e32 v22, 1.0, v22
	v_rcp_f32_e32 v24, v18
	v_add_f32_e32 v18, 1.0, v23
	v_rcp_f32_e32 v22, v22
	v_rcp_f32_e32 v23, v18
	v_mul_f32_e32 v18, v44, v19
	v_mul_f32_e32 v18, 0xbfb8aa3b, v18
	v_lshlrev_b32_e32 v26, 16, v85
	v_and_b32_e32 v27, 0xffff0000, v85
	v_exp_f32_e32 v25, v18
	v_lshlrev_b32_e32 v18, 16, v81
	v_and_b32_e32 v19, 0xffff0000, v81
	v_pk_fma_f32 v[18:19], v[22:23], v[26:27], v[18:19]
	v_fmamk_f32 v23, v223, 0x3a800000, v221
	v_mul_f32_e32 v26, 0x4b800000, v23
	v_cmp_gt_f32_e32 vcc, s60, v23
	v_add_f32_e32 v22, 1.0, v25
	v_rcp_f32_e32 v25, v22
	v_cndmask_b32_e32 v23, v23, v26, vcc
	v_rsq_f32_e32 v28, v23
	v_lshlrev_b32_e32 v22, 16, v87
	v_and_b32_e32 v23, 0xffff0000, v87
	v_lshlrev_b32_e32 v26, 16, v83
	v_mul_f32_e32 v29, 0x45800000, v28
	v_cndmask_b32_e32 v28, v28, v29, vcc
	v_mul_f32_e32 v8, v28, v8
	v_mul_f32_e32 v8, 0xbfb8aa3b, v8
	v_mul_f32_e32 v13, v28, v13
	v_exp_f32_e32 v8, v8
	v_mul_f32_e32 v13, 0xbfb8aa3b, v13
	v_mul_f32_e32 v12, v28, v12
	v_exp_f32_e32 v13, v13
	v_mul_f32_e32 v12, 0xbfb8aa3b, v12
	v_exp_f32_e32 v12, v12
	v_and_b32_e32 v27, 0xffff0000, v83
	v_add_f32_e32 v8, 1.0, v8
	v_pk_fma_f32 v[22:23], v[24:25], v[22:23], v[26:27]
	global_store_dwordx4 v[32:33], v[16:19], off offset:512 nt
	global_store_dwordx4 v[32:33], v[20:23], off offset:528 nt
	v_add_f32_e32 v12, 1.0, v12
	v_rcp_f32_e32 v16, v8
	v_add_f32_e32 v8, 1.0, v13
	v_rcp_f32_e32 v13, v8
	v_mul_f32_e32 v8, v28, v9
	v_mul_f32_e32 v8, 0xbfb8aa3b, v8
	v_rcp_f32_e32 v12, v12
	v_exp_f32_e32 v17, v8
	v_mul_f32_e32 v10, v28, v10
	s_waitcnt vmcnt(14)
	v_lshlrev_b32_e32 v18, 16, v76
	v_and_b32_e32 v19, 0xffff0000, v76
	v_lshlrev_b32_e32 v8, 16, v72
	v_and_b32_e32 v9, 0xffff0000, v72
	v_mul_f32_e32 v10, 0xbfb8aa3b, v10
	v_mul_f32_e32 v15, v28, v15
	v_pk_fma_f32 v[8:9], v[12:13], v[18:19], v[8:9]
	v_add_f32_e32 v12, 1.0, v17
	v_exp_f32_e32 v10, v10
	v_mul_f32_e32 v15, 0xbfb8aa3b, v15
	v_rcp_f32_e32 v17, v12
	v_mul_f32_e32 v14, v28, v14
	v_exp_f32_e32 v15, v15
	v_mul_f32_e32 v14, 0xbfb8aa3b, v14
	v_exp_f32_e32 v14, v14
	v_lshlrev_b32_e32 v12, 16, v78
	v_and_b32_e32 v13, 0xffff0000, v78
	v_lshlrev_b32_e32 v18, 16, v74
	v_and_b32_e32 v19, 0xffff0000, v74
	v_add_f32_e32 v10, 1.0, v10
	v_pk_fma_f32 v[12:13], v[16:17], v[12:13], v[18:19]
	v_rcp_f32_e32 v16, v10
	v_add_f32_e32 v10, 1.0, v15
	v_rcp_f32_e32 v15, v10
	v_mul_f32_e32 v10, v28, v11
	v_add_f32_e32 v14, 1.0, v14
	v_mul_f32_e32 v10, 0xbfb8aa3b, v10
	v_rcp_f32_e32 v14, v14
	v_exp_f32_e32 v17, v10
	v_lshlrev_b32_e32 v18, 16, v77
	v_and_b32_e32 v19, 0xffff0000, v77
	v_lshlrev_b32_e32 v10, 16, v73
	v_and_b32_e32 v11, 0xffff0000, v73
	v_mul_f32_e32 v0, v28, v0
	v_pk_fma_f32 v[10:11], v[14:15], v[18:19], v[10:11]
	v_add_f32_e32 v14, 1.0, v17
	v_mul_f32_e32 v0, 0xbfb8aa3b, v0
	v_mul_f32_e32 v5, v28, v5
	v_rcp_f32_e32 v17, v14
	v_exp_f32_e32 v0, v0
	v_mul_f32_e32 v5, 0xbfb8aa3b, v5
	v_mul_f32_e32 v4, v28, v4
	v_exp_f32_e32 v5, v5
	v_mul_f32_e32 v4, 0xbfb8aa3b, v4
	v_lshlrev_b32_e32 v14, 16, v79
	v_and_b32_e32 v15, 0xffff0000, v79
	v_lshlrev_b32_e32 v18, 16, v75
	v_and_b32_e32 v19, 0xffff0000, v75
	v_exp_f32_e32 v4, v4
	v_pk_fma_f32 v[14:15], v[16:17], v[14:15], v[18:19]
	v_lshl_add_u64 v[16:17], v[120:121], 2, s[70:71]
	v_add_f32_e32 v0, 1.0, v0
	global_store_dwordx4 v[16:17], v[8:11], off nt
	global_store_dwordx4 v[16:17], v[12:15], off offset:16 nt
	v_add_f32_e32 v4, 1.0, v4
	v_rcp_f32_e32 v8, v0
	v_add_f32_e32 v0, 1.0, v5
	v_rcp_f32_e32 v5, v0
	v_mul_f32_e32 v0, v28, v1
	v_mul_f32_e32 v0, 0xbfb8aa3b, v0
	v_rcp_f32_e32 v4, v4
	v_exp_f32_e32 v9, v0
	v_mul_f32_e32 v2, v28, v2
	s_waitcnt vmcnt(14)
	v_lshlrev_b32_e32 v10, 16, v68
	v_and_b32_e32 v11, 0xffff0000, v68
	v_lshlrev_b32_e32 v0, 16, v64
	v_and_b32_e32 v1, 0xffff0000, v64
	v_mul_f32_e32 v2, 0xbfb8aa3b, v2
	v_mul_f32_e32 v7, v28, v7
	v_pk_fma_f32 v[0:1], v[4:5], v[10:11], v[0:1]
	v_add_f32_e32 v4, 1.0, v9
	v_exp_f32_e32 v2, v2
	v_mul_f32_e32 v7, 0xbfb8aa3b, v7
	v_rcp_f32_e32 v9, v4
	v_mul_f32_e32 v6, v28, v6
	v_exp_f32_e32 v7, v7
	v_mul_f32_e32 v6, 0xbfb8aa3b, v6
	v_exp_f32_e32 v6, v6
	v_lshlrev_b32_e32 v4, 16, v70
	v_and_b32_e32 v5, 0xffff0000, v70
	v_lshlrev_b32_e32 v10, 16, v66
	v_and_b32_e32 v11, 0xffff0000, v66
	v_add_f32_e32 v2, 1.0, v2
	v_pk_fma_f32 v[4:5], v[8:9], v[4:5], v[10:11]
	v_rcp_f32_e32 v8, v2
	v_add_f32_e32 v2, 1.0, v7
	v_rcp_f32_e32 v7, v2
	v_mul_f32_e32 v2, v28, v3
	v_add_f32_e32 v6, 1.0, v6
	v_mul_f32_e32 v2, 0xbfb8aa3b, v2
	v_rcp_f32_e32 v6, v6
	v_exp_f32_e32 v9, v2
	v_lshlrev_b32_e32 v10, 16, v69
	v_and_b32_e32 v11, 0xffff0000, v69
	v_lshlrev_b32_e32 v2, 16, v65
	v_and_b32_e32 v3, 0xffff0000, v65
	v_pk_fma_f32 v[2:3], v[6:7], v[10:11], v[2:3]
	v_add_f32_e32 v6, 1.0, v9
	v_rcp_f32_e32 v9, v6
	v_lshlrev_b32_e32 v6, 16, v71
	v_and_b32_e32 v7, 0xffff0000, v71
	v_lshlrev_b32_e32 v10, 16, v67
	v_and_b32_e32 v11, 0xffff0000, v67
	v_pk_fma_f32 v[6:7], v[8:9], v[6:7], v[10:11]
	global_store_dwordx4 v[16:17], v[0:3], off offset:512 nt
	global_store_dwordx4 v[16:17], v[4:7], off offset:528 nt
	s_andn2_b64 vcc, exec, s[28:29]
	s_mov_b64 s[28:29], -1
	s_cbranch_vccnz .LBB0_1498
	s_andn2_b64 vcc, exec, s[0:1]
	s_cbranch_vccnz .LBB0_1497
	s_barrier
	s_branch .LBB0_1497
